# RG items: gate constants (softplus, biases) cached in LDS after the first item instead of reload+log1p per item; gate-row loads of pass-3/prompt tails issued together before the barrier; P4 vmcnt drai
# speedup vs baseline: 1.0336x; 1.0261x over previous
_Z14fwd_megakernel6Params:
	s_mov_b32 s98, 0
	s_load_dwordx4 s[72:75], s[0:1], 0xb8
	s_load_dwordx2 s[64:65], s[0:1], 0xc8
	s_load_dword s70, s[0:1], 0xd0
	s_mov_b32 s66, s2
	s_add_u32 s2, s0, 0xd0
	v_writelane_b32 v250, s0, 0
	s_addc_u32 s3, s1, 0
	v_readfirstlane_b32 s38, v0
	v_writelane_b32 v250, s1, 1
	s_waitcnt lgkmcnt(0)
	s_sub_i32 s0, s65, s64
	v_writelane_b32 v250, s2, 2
	s_cmp_lt_i32 s0, 2
	s_mov_b32 s95, 0
	v_writelane_b32 v250, s3, 3
	s_cbranch_scc1 .LBB0_7
	v_cmp_eq_u32_e32 vcc, 0, v0
	s_and_saveexec_b64 s[0:1], vcc
	s_cbranch_execz .LBB0_3
	s_add_i32 s2, 0, 0x27ff0
	v_mov_b32_e32 v1, 0
	v_mov_b32_e32 v2, s2
	s_add_i32 s2, 0, 0x27ff4
	ds_write_b32 v2, v1
	v_mov_b32_e32 v2, s2
	s_add_i32 s2, 0, 0x27ff8
	ds_write_b32 v2, v1
	v_mov_b32_e32 v2, s2
	s_add_i32 s2, 0, 0x27ffc
	ds_write_b32 v2, v1
	v_mov_b32_e32 v2, s2
	ds_write_b32 v2, v1

.LBB0_474:
	s_and_b32 s2, s42, 7
	s_lshl_b32 s8, s2, 7
	s_waitcnt lgkmcnt(0)
	v_or_b32_e32 v10, s8, v155
	v_lshlrev_b32_e32 v10, 2, v10
	s_waitcnt lgkmcnt(0)
	v_lshl_add_u64 v[12:13], s[12:13], 0, v[10:11]
	global_load_dwordx4 v[26:29], v10, s[12:13] offset:16
	global_load_dwordx4 v[30:33], v10, s[14:15] offset:16
	v_lshl_add_u64 v[42:43], v[12:13], 0, s[20:21]
	v_add_co_u32_e32 v54, vcc, s34, v12
	global_load_dwordx4 v[34:37], v10, s[12:13]
	global_load_dwordx4 v[38:41], v10, s[14:15]
	s_nop 0
	global_load_dwordx4 v[42:45], v[42:43], off offset:16
	v_addc_co_u32_e32 v55, vcc, 0, v13, vcc
	v_lshl_add_u64 v[50:51], v[12:13], 0, s[22:23]
	global_load_dwordx4 v[46:49], v[54:55], off offset:-4096
	v_lshl_add_u64 v[58:59], v[12:13], 0, s[24:25]
	global_load_dwordx4 v[50:53], v[50:51], off offset:16
	v_add_co_u32_e32 v12, vcc, s35, v12
	global_load_dwordx4 v[54:57], v[54:55], off
	s_nop 0
	global_load_dwordx4 v[58:61], v[58:59], off offset:16
	v_addc_co_u32_e32 v13, vcc, 0, v13, vcc
	global_load_dwordx4 v[62:65], v[12:13], off
	s_lshl_b32 s2, s2, 15
	v_lshl_add_u64 v[86:87], v[158:159], 0, s[2:3]
	global_load_dwordx4 v[70:73], v[86:87], off
	global_load_dwordx4 v[74:77], v[86:87], off offset:64
	s_mov_b32 s7, s3
	s_or_b32 s6, s2, 0x80000
	v_lshl_add_u64 v[120:121], v[158:159], 0, s[6:7]
	global_load_dwordx4 v[78:81], v[120:121], off
	global_load_dwordx4 v[82:85], v[86:87], off offset:128
	global_load_dwordx4 v[94:97], v[86:87], off offset:192
	s_nop 0
	global_load_dwordx4 v[86:89], v[120:121], off offset:64
	global_load_dwordx4 v[98:101], v[120:121], off offset:128
	global_load_dwordx4 v[134:137], v[120:121], off offset:192
	s_waitcnt vmcnt(18)
	v_lshlrev_b32_e32 v12, 16, v5
	v_and_b32_e32 v13, 0xffff0000, v5
	v_lshlrev_b32_e32 v90, 16, v9
	v_and_b32_e32 v91, 0xffff0000, v9
	v_lshlrev_b32_e32 v102, 16, v4
	v_and_b32_e32 v103, 0xffff0000, v4
	v_lshlrev_b32_e32 v108, 16, v8
	v_and_b32_e32 v109, 0xffff0000, v8
	v_lshlrev_b32_e32 v112, 16, v3
	v_and_b32_e32 v113, 0xffff0000, v3
	v_lshlrev_b32_e32 v66, 16, v17
	v_and_b32_e32 v67, 0xffff0000, v17
	v_lshlrev_b32_e32 v104, 16, v16
	v_and_b32_e32 v105, 0xffff0000, v16
	v_lshlrev_b32_e32 v114, 16, v15
	v_and_b32_e32 v115, 0xffff0000, v15
	v_lshlrev_b32_e32 v118, 16, v7
	v_and_b32_e32 v119, 0xffff0000, v7
	v_lshlrev_b32_e32 v68, 16, v21
	v_and_b32_e32 v69, 0xffff0000, v21
	v_lshlrev_b32_e32 v106, 16, v20
	v_and_b32_e32 v107, 0xffff0000, v20
	v_lshlrev_b32_e32 v116, 16, v19
	v_and_b32_e32 v117, 0xffff0000, v19
	v_lshlrev_b32_e32 v110, 16, v24
	v_and_b32_e32 v111, 0xffff0000, v24
	v_lshlrev_b32_e32 v92, 16, v25
	v_and_b32_e32 v93, 0xffff0000, v25
	v_add_u32_e32 v10, s8, v154
	s_add_u32 s8, s74, s2
	s_addc_u32 s9, s75, 0
	s_add_u32 s6, s74, s6
	s_addc_u32 s7, s75, 0
	v_lshlrev_b64 v[166:167], 2, v[10:11]
	v_lshl_add_u64 v[168:169], s[18:19], 0, v[166:167]
	v_lshl_add_u64 v[164:165], s[0:1], 0, v[166:167]
	v_lshl_add_u64 v[166:167], s[16:17], 0, v[166:167]
	s_waitcnt vmcnt(16)
	v_pk_fma_f32 v[120:121], v[28:29], v[12:13], v[32:33]
	v_pk_fma_f32 v[28:29], v[28:29], v[90:91], v[32:33]
	v_pk_fma_f32 v[32:33], v[26:27], v[102:103], v[30:31]
	v_pk_fma_f32 v[26:27], v[26:27], v[108:109], v[30:31]
	s_waitcnt vmcnt(14)
	v_pk_fma_f32 v[30:31], v[36:37], v[112:113], v[40:41]
	s_waitcnt vmcnt(13)
	v_pk_fma_f32 v[12:13], v[44:45], v[12:13], v[28:29]
	v_pk_fma_f32 v[36:37], v[36:37], v[118:119], v[40:41]
	v_pk_fma_f32 v[40:41], v[44:45], v[66:67], v[120:121]
	v_pk_fma_f32 v[28:29], v[42:43], v[104:105], v[32:33]
	s_waitcnt vmcnt(12)
	v_pk_fma_f32 v[30:31], v[48:49], v[114:115], v[30:31]
	s_waitcnt vmcnt(11)
	v_pk_fma_f32 v[12:13], v[52:53], v[66:67], v[12:13]
	v_pk_fma_f32 v[26:27], v[42:43], v[102:103], v[26:27]
	v_pk_fma_f32 v[32:33], v[48:49], v[112:113], v[36:37]
	v_pk_fma_f32 v[36:37], v[52:53], v[68:69], v[40:41]
	v_pk_fma_f32 v[40:41], v[50:51], v[106:107], v[28:29]
	s_waitcnt vmcnt(10)
	v_pk_fma_f32 v[42:43], v[56:57], v[116:117], v[30:31]
	s_waitcnt vmcnt(9)
	v_pk_fma_f32 v[28:29], v[60:61], v[68:69], v[12:13]
	v_lshlrev_b32_e32 v12, 16, v23
	v_and_b32_e32 v13, 0xffff0000, v23
	v_pk_fma_f32 v[26:27], v[50:51], v[104:105], v[26:27]
	v_pk_fma_f32 v[30:31], v[58:59], v[110:111], v[40:41]
	s_waitcnt vmcnt(8)
	v_pk_fma_f32 v[40:41], v[64:65], v[12:13], v[42:43]
	v_lshlrev_b32_e32 v12, 16, v2
	v_and_b32_e32 v13, 0xffff0000, v2
	v_lshlrev_b32_e32 v50, 16, v6
	v_and_b32_e32 v51, 0xffff0000, v6
	v_pk_fma_f32 v[44:45], v[56:57], v[114:115], v[32:33]
	v_pk_fma_f32 v[42:43], v[34:35], v[12:13], v[38:39]
	v_pk_fma_f32 v[34:35], v[34:35], v[50:51], v[38:39]
	v_pk_fma_f32 v[32:33], v[60:61], v[92:93], v[36:37]
	v_pk_fma_f32 v[36:37], v[64:65], v[116:117], v[44:45]
	v_lshlrev_b32_e32 v44, 16, v14
	v_and_b32_e32 v45, 0xffff0000, v14
	v_pk_fma_f32 v[12:13], v[46:47], v[12:13], v[34:35]
	v_pk_fma_f32 v[42:43], v[46:47], v[44:45], v[42:43]
	v_lshlrev_b32_e32 v48, 16, v18
	v_and_b32_e32 v49, 0xffff0000, v18
	v_pk_fma_f32 v[12:13], v[54:55], v[44:45], v[12:13]
	v_pk_fma_f32 v[26:27], v[58:59], v[106:107], v[26:27]
	v_pk_fma_f32 v[42:43], v[54:55], v[48:49], v[42:43]
	v_pk_fma_f32 v[34:35], v[62:63], v[48:49], v[12:13]
	v_lshlrev_b32_e32 v12, 16, v22
	v_and_b32_e32 v13, 0xffff0000, v22
	v_pk_fma_f32 v[38:39], v[62:63], v[12:13], v[42:43]
	v_cvt_pk_bf16_f32 v42, v34, v35
	v_cvt_pk_bf16_f32 v43, v36, v37
	v_cvt_pk_bf16_f32 v44, v26, v27
	v_cvt_pk_bf16_f32 v45, v28, v29
	ds_write_b128 v172, v[42:45]
	ds_write_b128 v173, v[34:37] offset:17408
	ds_write_b128 v173, v[26:29] offset:17424
	v_cvt_pk_bf16_f32 v26, v38, v39
	v_cvt_pk_bf16_f32 v27, v40, v41
	v_cvt_pk_bf16_f32 v28, v30, v31
	v_cvt_pk_bf16_f32 v29, v32, v33
	ds_write_b128 v174, v[26:29]
	ds_write_b128 v175, v[38:41] offset:17408
	ds_write_b128 v175, v[30:33] offset:17424
	s_waitcnt lgkmcnt(0)
	s_barrier
	ds_read_b128 v[26:29], v176
	ds_read_b128 v[30:33], v176 offset:64
	ds_read_b128 v[50:53], v176 offset:4352
	ds_read_b128 v[34:37], v176 offset:4416
	ds_read_b128 v[58:61], v176 offset:8704
	ds_read_b128 v[46:49], v176 offset:8768
	ds_read_b128 v[66:69], v176 offset:13056
	ds_read_b128 v[54:57], v176 offset:13120
	s_waitcnt vmcnt(7) lgkmcnt(7)
	v_mfma_f32_16x16x32_bf16 v[38:41], v[26:29], v[70:73], 0
	v_lshl_add_u64 v[12:13], s[8:9], 0, v[156:157]
	v_lshl_add_u64 v[12:13], v[12:13], 0, v[160:161]
	s_waitcnt vmcnt(5)
	v_mfma_f32_16x16x32_bf16 v[42:45], v[26:29], v[78:81], 0
	s_waitcnt lgkmcnt(5)
	v_mfma_f32_16x16x32_bf16 v[62:65], v[50:53], v[70:73], 0
	v_mfma_f32_16x16x32_bf16 v[90:93], v[50:53], v[78:81], 0
	s_waitcnt lgkmcnt(3)
	v_mfma_f32_16x16x32_bf16 v[102:105], v[58:61], v[70:73], 0
	v_mfma_f32_16x16x32_bf16 v[106:109], v[58:61], v[78:81], 0
	s_waitcnt lgkmcnt(1)
	v_mfma_f32_16x16x32_bf16 v[70:73], v[66:69], v[70:73], 0
	v_mfma_f32_16x16x32_bf16 v[78:81], v[66:69], v[78:81], 0
	v_mfma_f32_16x16x32_bf16 v[38:41], v[30:33], v[74:77], v[38:41]
	s_waitcnt vmcnt(2)
	v_mfma_f32_16x16x32_bf16 v[42:45], v[30:33], v[86:89], v[42:45]
	v_mfma_f32_16x16x32_bf16 v[110:113], v[34:37], v[74:77], v[62:65]
	v_mfma_f32_16x16x32_bf16 v[90:93], v[34:37], v[86:89], v[90:93]
	v_mfma_f32_16x16x32_bf16 v[102:105], v[46:49], v[74:77], v[102:105]
	s_waitcnt lgkmcnt(0)
	v_mfma_f32_16x16x32_bf16 v[114:117], v[54:57], v[74:77], v[70:73]
	s_nop 2
	ds_read_b128 v[70:73], v176 offset:128
	ds_read_b128 v[74:77], v176 offset:192
	v_mfma_f32_16x16x32_bf16 v[118:121], v[54:57], v[86:89], v[78:81]
	s_nop 2
	ds_read_b128 v[78:81], v176 offset:4480
	ds_read_b128 v[62:65], v176 offset:4544
	v_mfma_f32_16x16x32_bf16 v[106:109], v[46:49], v[86:89], v[106:109]
	s_waitcnt lgkmcnt(3)
	v_mfma_f32_16x16x32_bf16 v[122:125], v[70:73], v[82:85], v[38:41]
	s_waitcnt vmcnt(1)
	v_mfma_f32_16x16x32_bf16 v[130:133], v[70:73], v[98:101], v[42:45]
	ds_read_b128 v[86:89], v176 offset:8832
	s_nop 1
	ds_read_b128 v[42:45], v176 offset:8896
	s_waitcnt lgkmcnt(3)
	v_mfma_f32_16x16x32_bf16 v[138:141], v[78:81], v[98:101], v[90:93]
	s_nop 2
	ds_read_b128 v[90:93], v176 offset:13184
	ds_read_b128 v[38:41], v176 offset:13248
	v_mfma_f32_16x16x32_bf16 v[110:113], v[78:81], v[82:85], v[110:113]
	s_waitcnt lgkmcnt(3)
	v_mfma_f32_16x16x32_bf16 v[102:105], v[86:89], v[82:85], v[102:105]
	s_waitcnt lgkmcnt(1)
	v_mfma_f32_16x16x32_bf16 v[82:85], v[90:93], v[82:85], v[114:117]
	v_mfma_f32_16x16x32_bf16 v[126:129], v[74:77], v[94:97], v[122:125]
	s_waitcnt vmcnt(0)
	v_mfma_f32_16x16x32_bf16 v[122:125], v[74:77], v[134:137], v[130:133]
	s_waitcnt lgkmcnt(0)
	v_mfma_f32_16x16x32_bf16 v[130:133], v[38:41], v[94:97], v[82:85]
	s_nop 2
	v_lshl_add_u64 v[82:83], v[12:13], 0, s[26:27]
	v_add_co_u32_e32 v12, vcc, s36, v12
	v_mfma_f32_16x16x32_bf16 v[106:109], v[86:89], v[98:101], v[106:109]
	s_nop 0
	v_addc_co_u32_e32 v13, vcc, 0, v13, vcc
	v_mfma_f32_16x16x32_bf16 v[184:187], v[90:93], v[98:101], v[118:121]
	v_mfma_f32_16x16x32_bf16 v[150:153], v[62:65], v[94:97], v[110:113]
	v_mfma_f32_16x16x32_bf16 v[142:145], v[42:45], v[94:97], v[102:105]
	s_nop 2
	global_load_dwordx4 v[102:105], v[82:83], off offset:64
	global_load_dwordx4 v[98:101], v[82:83], off offset:128
	global_load_dwordx4 v[110:113], v[12:13], off
	s_nop 0
	global_load_dwordx4 v[82:85], v[82:83], off offset:192
	v_lshl_add_u64 v[12:13], s[6:7], 0, v[156:157]
	v_lshl_add_u64 v[12:13], v[12:13], 0, v[160:161]
	v_lshl_add_u64 v[94:95], v[12:13], 0, s[26:27]
	v_add_co_u32_e32 v12, vcc, s36, v12
	v_mfma_f32_16x16x32_bf16 v[146:149], v[62:65], v[134:137], v[138:141]
	s_nop 0
	v_addc_co_u32_e32 v13, vcc, 0, v13, vcc
	v_mfma_f32_16x16x32_bf16 v[138:141], v[42:45], v[134:137], v[106:109]
	global_load_dwordx4 v[114:117], v[94:95], off offset:64
	s_nop 1
	global_load_dwordx4 v[106:109], v[94:95], off offset:128
	global_load_dwordx4 v[118:121], v[12:13], off
	s_nop 0
	global_load_dwordx4 v[94:97], v[94:95], off offset:192
	s_nop 0
	s_cmp_lg_u32 s98, 0
	s_cbranch_scc1 .Lrgc_a_fast
	global_load_dword v183, v[168:169], off
	global_load_dword v13, v[164:165], off
	global_load_dword v12, v[166:167], off
	v_mfma_f32_16x16x32_bf16 v[134:137], v[38:41], v[134:137], v[184:187]
	s_waitcnt vmcnt(2)
	v_xor_b32_e32 v163, 0x80000000, v183
	v_cmp_ngt_f32_e32 vcc, s37, v183
	s_and_saveexec_b64 s[6:7], vcc
	s_cbranch_execz .LBB0_476
	v_mul_f32_e32 v163, 0xbfb8aa3b, v183
	v_exp_f32_e32 v183, v163
	s_nop 0
	v_add_f32_e32 v163, 1.0, v183
	v_frexp_mant_f32_e32 v187, v163
	v_cvt_f64_f32_e32 v[184:185], v163
	v_add_f32_e32 v186, -1.0, v163
	v_frexp_exp_i32_f64_e32 v184, v[184:185]
	v_cmp_gt_f32_e32 vcc, s38, v187
	v_sub_f32_e32 v188, v186, v163
	v_sub_f32_e32 v186, v183, v186
	v_subbrev_co_u32_e32 v192, vcc, 0, v184, vcc
	v_add_f32_e32 v188, 1.0, v188
	v_sub_u32_e32 v184, 0, v192
	v_add_f32_e32 v186, v186, v188
	v_ldexp_f32 v163, v163, v184
	v_ldexp_f32 v184, v186, v184
	v_add_f32_e32 v186, -1.0, v163
	v_add_f32_e32 v185, 1.0, v186
	v_sub_f32_e32 v185, v163, v185
	v_add_f32_e32 v187, v184, v185
	v_add_f32_e32 v185, 1.0, v163
	v_add_f32_e32 v188, -1.0, v185
	v_sub_f32_e32 v163, v163, v188
	v_add_f32_e32 v163, v184, v163
	v_add_f32_e32 v193, v185, v163
	v_rcp_f32_e32 v194, v193
	v_sub_f32_e32 v184, v193, v185
	v_add_f32_e32 v185, v186, v187
	v_sub_f32_e32 v163, v163, v184
	v_mul_f32_e32 v196, v185, v194
	v_sub_f32_e32 v184, v185, v186
	v_mul_f32_e32 v186, v193, v196
	v_fma_f32 v188, v196, v193, -v186
	v_fmac_f32_e32 v188, v196, v163
	v_sub_f32_e32 v195, v187, v184
	v_add_f32_e32 v184, v186, v188
	v_sub_f32_e32 v187, v185, v184
	v_pk_add_f32 v[190:191], v[184:185], v[186:187] neg_lo:[0,1] neg_hi:[0,1]
	v_mov_b32_e32 v189, v184
	v_pk_add_f32 v[184:185], v[190:191], v[188:189] neg_lo:[0,1] neg_hi:[0,1]
	v_cmp_neq_f32_e32 vcc, s40, v183
	v_add_f32_e32 v185, v195, v185
	v_add_f32_e32 v184, v184, v185
	v_add_f32_e32 v185, v187, v184
	v_mul_f32_e32 v195, v194, v185
	v_mul_f32_e32 v186, v193, v195
	v_fma_f32 v188, v195, v193, -v186
	v_fmac_f32_e32 v188, v195, v163
	v_sub_f32_e32 v163, v187, v185
	v_add_f32_e32 v163, v184, v163
	v_add_f32_e32 v184, v186, v188
	v_sub_f32_e32 v187, v185, v184
	v_pk_add_f32 v[190:191], v[184:185], v[186:187] neg_lo:[0,1] neg_hi:[0,1]
	v_mov_b32_e32 v189, v184
	v_pk_add_f32 v[184:185], v[190:191], v[188:189] neg_lo:[0,1] neg_hi:[0,1]
	s_nop 0
	v_add_f32_e32 v163, v163, v185
	v_add_f32_e32 v163, v184, v163
	v_add_f32_e32 v185, v196, v195
	v_add_f32_e32 v163, v187, v163
	v_sub_f32_e32 v184, v185, v196
	v_mul_f32_e32 v163, v194, v163
	v_sub_f32_e32 v184, v195, v184
	v_add_f32_e32 v186, v184, v163
	v_add_f32_e32 v188, v185, v186
	v_cvt_f32_i32_e32 v184, v192
	v_mul_f32_e32 v189, v188, v188
	v_sub_f32_e32 v185, v188, v185
	v_fmamk_f32 v163, v189, 0x3e9b6dac, v177
	v_sub_f32_e32 v185, v186, v185
	v_fmaak_f32 v163, v189, v163, 0x3f2aaada
	v_ldexp_f32 v190, v185, 1
	v_mul_f32_e32 v185, v188, v189
	v_ldexp_f32 v187, v188, 1
	v_pk_mul_f32 v[188:189], v[184:185], v[162:163]
	s_nop 0
	v_fma_f32 v186, v184, s39, -v188
	v_fmac_f32_e32 v186, 0xb102e308, v184
	v_pk_add_f32 v[184:185], v[188:189], v[186:187]
	s_nop 0
	v_sub_f32_e32 v163, v185, v187
	v_sub_f32_e32 v163, v189, v163
	v_add_f32_e32 v191, v190, v163
	v_mov_b32_e32 v190, v188
	v_pk_add_f32 v[188:189], v[184:185], v[188:189] neg_lo:[0,1] neg_hi:[0,1]
	v_pk_add_f32 v[192:193], v[184:185], v[190:191]
	v_mov_b32_e32 v187, v184
	v_mov_b32_e32 v189, v193
	v_pk_add_f32 v[194:195], v[186:187], v[188:189] neg_lo:[0,1] neg_hi:[0,1]
	v_pk_add_f32 v[186:187], v[186:187], v[188:189]
	v_mov_b32_e32 v190, v191
	v_pk_add_f32 v[188:189], v[186:187], v[184:185] op_sel:[1,0] op_sel_hi:[0,1] neg_lo:[0,1] neg_hi:[0,1]
	v_pk_add_f32 v[196:197], v[192:193], v[188:189] op_sel_hi:[1,0] neg_lo:[0,1] neg_hi:[0,1]
	v_mov_b32_e32 v192, v193
	v_mov_b32_e32 v193, v187
	v_pk_mov_b32 v[188:189], v[184:185], v[188:189] op_sel:[1,0]
	v_mov_b32_e32 v191, v184
	v_pk_add_f32 v[188:189], v[192:193], v[188:189] neg_lo:[0,1] neg_hi:[0,1]
	v_mov_b32_e32 v196, v194
	v_pk_add_f32 v[184:185], v[190:191], v[188:189] neg_lo:[0,1] neg_hi:[0,1]
	v_mov_b32_e32 v195, v187
	v_pk_add_f32 v[188:189], v[196:197], v[184:185]
	s_nop 0
	v_pk_add_f32 v[190:191], v[188:189], v[188:189] op_sel:[0,1] op_sel_hi:[1,0]
	s_nop 0
	v_pk_add_f32 v[186:187], v[186:187], v[190:191] op_sel:[1,0] op_sel_hi:[0,1]
	v_mov_b32_e32 v189, v186
	v_pk_add_f32 v[192:193], v[188:189], v[194:195] neg_lo:[0,1] neg_hi:[0,1]
	v_mov_b32_e32 v185, v190
	v_sub_f32_e32 v163, v188, v192
	v_pk_add_f32 v[184:185], v[184:185], v[192:193] neg_lo:[0,1] neg_hi:[0,1]
	v_sub_f32_e32 v163, v194, v163
	v_add_f32_e32 v163, v184, v163
	v_add_f32_e32 v163, v163, v185
	v_add_f32_e32 v163, v186, v163
	v_cndmask_b32_e32 v163, v179, v163, vcc
	v_cmp_ngt_f32_e32 vcc, -1.0, v183
	s_nop 1
	v_cndmask_b32_e32 v163, v180, v163, vcc
	v_cmp_neq_f32_e32 vcc, -1.0, v183
	s_nop 1
	v_cndmask_b32_e32 v163, v181, v163, vcc
	v_cmp_lt_f32_e64 vcc, |v183|, s41
	s_nop 1
	v_cndmask_b32_e32 v163, v163, v183, vcc
.LBB0_476:
	s_or_b64 exec, exec, s[6:7]
	v_lshlrev_b32_e32 v251, 2, v0
	v_add_u32_e32 v251, 0x24a00, v251
	ds_write_b32 v251, v163 offset:0
	s_waitcnt vmcnt(0)
	ds_write_b32 v251, v13 offset:2048
	ds_write_b32 v251, v12 offset:4096
	s_branch .Lrgc_a_join
.Lrgc_a_fast:
	v_mfma_f32_16x16x32_bf16 v[134:137], v[38:41], v[134:137], v[184:187]
	v_lshlrev_b32_e32 v251, 2, v0
	v_add_u32_e32 v251, 0x24a00, v251
	ds_read_b32 v163, v251 offset:0
	ds_read_b32 v13, v251 offset:2048
	ds_read_b32 v12, v251 offset:4096
	s_nop 7
	s_waitcnt lgkmcnt(0)
.Lrgc_a_join:
	s_nop 0
	v_mul_f32_e32 v13, 0xbfb8aa3b, v13
	v_fmamk_f32 v142, v142, 0xbfb8aa3b, v13
	v_exp_f32_e32 v142, v142
	v_mul_f32_e32 v163, 0xc1800000, v163
	v_mul_f32_e32 v163, 0x3fb8aa3b, v163
	v_mul_f32_e32 v163, 0.5, v163
	v_add_f32_e32 v142, 1.0, v142
	v_rcp_f32_e32 v142, v142
	s_nop 0
	v_mul_f32_e32 v12, 0xbfb8aa3b, v12
	v_fmamk_f32 v138, v138, 0xbfb8aa3b, v12
	v_exp_f32_e32 v138, v138
	v_mul_f32_e32 v142, v142, v163
	v_exp_f32_e32 v190, v142
	v_fmamk_f32 v143, v143, 0xbfb8aa3b, v13
	v_exp_f32_e32 v191, v143
	v_add_f32_e32 v138, 1.0, v138
	v_fma_f32 v142, v190, v190, -1.0
	v_max_f32_e64 v142, -v142, 0
	v_sqrt_f32_e32 v192, v142
	ds_read2st64_b32 v[142:143], v178 offset0:132 offset1:134
	v_rcp_f32_e32 v138, v138
	v_add_f32_e32 v191, 1.0, v191
	v_fmamk_f32 v139, v139, 0xbfb8aa3b, v12
	v_exp_f32_e32 v139, v139
	v_rcp_f32_e32 v191, v191
	s_waitcnt lgkmcnt(0)
	v_mul_f32_e32 v138, v138, v142
	v_mul_f32_e32 v192, v138, v192
	v_add_f32_e32 v138, 1.0, v139
	v_mul_f32_e32 v139, v191, v163
	v_exp_f32_e32 v191, v139
	v_fmamk_f32 v139, v144, 0xbfb8aa3b, v13
	v_exp_f32_e32 v139, v139
	v_fmamk_f32 v140, v140, 0xbfb8aa3b, v12
	v_rcp_f32_e32 v138, v138
	v_exp_f32_e32 v140, v140
	v_add_f32_e32 v139, 1.0, v139
	v_rcp_f32_e32 v139, v139
	v_mul_f32_e32 v193, v138, v143
	v_add_f32_e32 v138, 1.0, v140
	v_rcp_f32_e32 v140, v138
	v_mul_f32_e32 v139, v139, v163
	v_exp_f32_e32 v194, v139
	v_fmamk_f32 v138, v145, 0xbfb8aa3b, v13
	v_exp_f32_e32 v145, v138
	v_fmamk_f32 v130, v130, 0xbfb8aa3b, v13
	v_exp_f32_e32 v130, v130
	v_fma_f32 v138, v194, v194, -1.0
	v_max_f32_e64 v195, -v138, 0
	ds_read2st64_b32 v[138:139], v178 offset0:136 offset1:138
	v_add_f32_e32 v145, 1.0, v145
	v_fmamk_f32 v141, v141, 0xbfb8aa3b, v12
	v_exp_f32_e32 v141, v141
	v_rcp_f32_e32 v145, v145
	v_fmamk_f32 v131, v131, 0xbfb8aa3b, v13
	v_add_f32_e32 v130, 1.0, v130
	v_exp_f32_e32 v131, v131
	v_rcp_f32_e32 v130, v130
	s_waitcnt lgkmcnt(0)
	v_mul_f32_e32 v196, v140, v138
	v_add_f32_e32 v140, 1.0, v141
	v_mul_f32_e32 v141, v145, v163
	v_exp_f32_e32 v197, v141
	v_add_f32_e32 v131, 1.0, v131
	v_fmamk_f32 v134, v134, 0xbfb8aa3b, v12
	v_mul_f32_e32 v130, v130, v163
	v_rcp_f32_e32 v131, v131
	v_rcp_f32_e32 v140, v140
	v_exp_f32_e32 v134, v134
	v_exp_f32_e32 v199, v130
	v_fmamk_f32 v150, v150, 0xbfb8aa3b, v13
	v_exp_f32_e32 v150, v150
	v_fma_f32 v141, v197, v197, -1.0
	v_max_f32_e64 v141, -v141, 0
	v_mul_f32_e32 v131, v131, v163
	v_sqrt_f32_e32 v198, v141
	v_mul_f32_e32 v200, v140, v139
	v_add_f32_e32 v130, 1.0, v134
	v_fma_f32 v134, v199, v199, -1.0
	ds_read2st64_b32 v[140:141], v178 offset0:164 offset1:166
	v_exp_f32_e32 v202, v131
	v_rcp_f32_e32 v130, v130
	v_max_f32_e64 v134, -v134, 0
	v_fmamk_f32 v135, v135, 0xbfb8aa3b, v12
	v_add_f32_e32 v150, 1.0, v150
	v_sqrt_f32_e32 v134, v134
	v_exp_f32_e32 v135, v135
	v_rcp_f32_e32 v150, v150
	v_fmamk_f32 v131, v132, 0xbfb8aa3b, v13
	v_fma_f32 v132, v202, v202, -1.0
	s_waitcnt lgkmcnt(0)
	v_mul_f32_e32 v130, v130, v140
	v_max_f32_e64 v132, -v132, 0
	v_mul_f32_e32 v201, v134, v130
	v_add_f32_e32 v130, 1.0, v135
	v_sqrt_f32_e32 v203, v132
	v_fmamk_f32 v132, v136, 0xbfb8aa3b, v12
	v_mul_f32_e32 v150, v150, v163
	v_rcp_f32_e32 v130, v130
	v_exp_f32_e32 v132, v132
	v_exp_f32_e32 v183, v150
	v_fmamk_f32 v146, v146, 0xbfb8aa3b, v12
	v_exp_f32_e32 v146, v146
	v_mul_f32_e32 v205, v130, v141
	v_add_f32_e32 v130, 1.0, v132
	v_fmamk_f32 v150, v151, 0xbfb8aa3b, v13
	v_fma_f32 v151, v183, v183, -1.0
	v_rcp_f32_e32 v132, v130
	v_fmamk_f32 v130, v133, 0xbfb8aa3b, v13
	v_exp_f32_e32 v184, v150
	v_max_f32_e64 v150, -v151, 0
	v_exp_f32_e32 v133, v130
	v_add_f32_e32 v146, 1.0, v146
	v_sqrt_f32_e32 v185, v150
	ds_read2st64_b32 v[150:151], v178 offset0:100 offset1:102
	v_exp_f32_e32 v131, v131
	v_rcp_f32_e32 v146, v146
	v_fmamk_f32 v147, v147, 0xbfb8aa3b, v12
	v_exp_f32_e32 v147, v147
	v_add_f32_e32 v133, 1.0, v133
	v_add_f32_e32 v131, 1.0, v131
	v_rcp_f32_e32 v133, v133
	v_fmamk_f32 v126, v126, 0xbfb8aa3b, v13
	s_waitcnt lgkmcnt(0)
	v_mul_f32_e32 v146, v146, v150
	v_rcp_f32_e32 v131, v131
	v_exp_f32_e32 v126, v126
	v_fmamk_f32 v127, v127, 0xbfb8aa3b, v13
	v_add_f32_e32 v184, 1.0, v184
	v_mul_f32_e32 v185, v146, v185
	v_add_f32_e32 v146, 1.0, v147
	v_fmamk_f32 v148, v148, 0xbfb8aa3b, v12
	v_exp_f32_e32 v127, v127
	v_rcp_f32_e32 v184, v184
	v_rcp_f32_e32 v146, v146
	v_exp_f32_e32 v148, v148
	v_mul_f32_e32 v133, v133, v163
	v_mul_f32_e32 v131, v131, v163
	v_exp_f32_e32 v208, v133
	v_add_f32_e32 v126, 1.0, v126
	v_exp_f32_e32 v204, v131
	v_rcp_f32_e32 v126, v126
	v_add_f32_e32 v127, 1.0, v127
	v_mul_f32_e32 v147, v184, v163
	v_mul_f32_e32 v186, v146, v151
	v_add_f32_e32 v146, 1.0, v148
	v_rcp_f32_e32 v127, v127
	v_fmamk_f32 v128, v128, 0xbfb8aa3b, v13
	v_exp_f32_e32 v184, v147
	v_fmamk_f32 v147, v152, 0xbfb8aa3b, v13
	v_rcp_f32_e32 v187, v146
	v_fmamk_f32 v146, v153, 0xbfb8aa3b, v13
	v_exp_f32_e32 v128, v128
	v_fmac_f32_e32 v13, 0xbfb8aa3b, v129
	v_fma_f32 v133, v208, v208, -1.0
	v_exp_f32_e32 v13, v13
	v_fma_f32 v134, v204, v204, -1.0
	ds_read2st64_b32 v[130:131], v178 offset0:168 offset1:170
	v_max_f32_e64 v133, -v133, 0
	v_mul_f32_e32 v126, v126, v163
	v_max_f32_e64 v134, -v134, 0
	v_sqrt_f32_e32 v209, v133
	v_exp_f32_e32 v133, v126
	v_mul_f32_e32 v126, v127, v163
	v_sqrt_f32_e32 v206, v134
	v_exp_f32_e32 v134, v126
	v_add_f32_e32 v126, 1.0, v128
	v_rcp_f32_e32 v126, v126
	v_add_f32_e32 v13, 1.0, v13
	v_fmamk_f32 v125, v125, 0xbfb8aa3b, v12
	v_rcp_f32_e32 v13, v13
	v_exp_f32_e32 v125, v125
	v_fmamk_f32 v124, v124, 0xbfb8aa3b, v12
	s_waitcnt lgkmcnt(0)
	v_mul_f32_e32 v207, v132, v130
	v_fmamk_f32 v132, v137, 0xbfb8aa3b, v12
	v_exp_f32_e32 v124, v124
	v_exp_f32_e32 v132, v132
	v_mul_f32_e32 v126, v126, v163
	v_exp_f32_e32 v147, v147
	v_exp_f32_e32 v129, v126
	v_mul_f32_e32 v13, v13, v163
	ds_read2st64_b32 v[126:127], v178 offset0:72 offset1:74
	v_add_f32_e32 v125, 1.0, v125
	v_exp_f32_e32 v13, v13
	v_rcp_f32_e32 v125, v125
	v_add_f32_e32 v124, 1.0, v124
	v_fmamk_f32 v149, v149, 0xbfb8aa3b, v12
	v_add_f32_e32 v132, 1.0, v132
	v_rcp_f32_e32 v124, v124
	v_fmamk_f32 v123, v123, 0xbfb8aa3b, v12
	v_fmac_f32_e32 v12, 0xbfb8aa3b, v122
	v_exp_f32_e32 v153, v146
	v_rcp_f32_e32 v132, v132
	v_mul_f32_e32 v128, v133, v134
	v_exp_f32_e32 v12, v12
	v_add_f32_e32 v147, 1.0, v147
	v_mul_f32_e32 v128, v129, v128
	v_rcp_f32_e32 v147, v147
	v_mul_f32_e32 v135, v13, v128
	s_waitcnt lgkmcnt(0)
	v_mul_f32_e32 v128, v125, v127
	v_fma_f32 v125, v13, v13, -1.0
	v_exp_f32_e32 v123, v123
	v_max_f32_e64 v125, -v125, 0
	v_mul_f32_e32 v136, v124, v126
	v_fma_f32 v124, v129, v129, -1.0
	v_add_f32_e32 v153, 1.0, v153
	v_mul_f32_e32 v210, v132, v131
	v_sqrt_f32_e32 v132, v125
	v_max_f32_e64 v137, -v124, 0
	ds_read2st64_b32 v[124:125], v178 offset0:68 offset1:70
	v_add_f32_e32 v12, 1.0, v12
	v_fma_f32 v133, v133, v133, -1.0
	v_rcp_f32_e32 v153, v153
	v_rcp_f32_e32 v12, v12
	v_max_f32_e64 v133, -v133, 0
	v_mul_f32_e32 v147, v147, v163
	v_add_f32_e32 v123, 1.0, v123
	v_sqrt_f32_e32 v122, v137
	v_fma_f32 v137, v134, v134, -1.0
	v_sqrt_f32_e32 v133, v133
	v_exp_f32_e32 v148, v147
	v_rcp_f32_e32 v123, v123
	v_max_f32_e64 v137, -v137, 0
	v_sqrt_f32_e32 v137, v137
	v_mul_f32_e32 v153, v153, v163
	s_waitcnt lgkmcnt(0)
	v_mul_f32_e32 v12, v12, v124
	v_fma_f32 v152, v184, v184, -1.0
	v_exp_f32_e32 v149, v149
	v_exp_f32_e32 v153, v153
	v_mul_f32_e32 v12, v133, v12
	v_max_f32_e64 v152, -v152, 0
	v_fma_f32 v146, v148, v148, -1.0
	v_mul_f32_e32 v123, v123, v125
	v_mul_f32_e32 v12, v134, v12
	v_sqrt_f32_e32 v152, v152
	v_max_f32_e64 v188, -v146, 0
	ds_read2st64_b32 v[146:147], v178 offset0:104 offset1:106
	v_fmac_f32_e32 v12, v137, v123
	v_mul_f32_e32 v12, v129, v12
	v_sqrt_f32_e32 v188, v188
	v_add_f32_e32 v149, 1.0, v149
	v_fma_f32 v189, v153, v153, -1.0
	v_fmac_f32_e32 v12, v122, v136
	v_rcp_f32_e32 v149, v149
	v_max_f32_e64 v189, -v189, 0
	v_mul_f32_e32 v12, v13, v12
	v_mul_f32_e32 v13, v184, v185
	v_sqrt_f32_e32 v189, v189
	v_fma_f32 v144, v191, v191, -1.0
	v_fmac_f32_e32 v13, v186, v152
	s_waitcnt lgkmcnt(0)
	v_mul_f32_e32 v187, v187, v146
	v_max_f32_e64 v144, -v144, 0
	v_mul_f32_e32 v13, v148, v13
	v_sqrt_f32_e32 v144, v144
	v_fmac_f32_e32 v13, v187, v188
	v_mul_f32_e32 v149, v149, v147
	v_fmac_f32_e32 v12, v132, v128
	v_mul_f32_e32 v13, v153, v13
	v_sqrt_f32_e32 v195, v195
	ds_bpermute_b32 v123, v182, v12
	ds_bpermute_b32 v128, v182, v12 offset:64
	ds_bpermute_b32 v129, v182, v12 offset:128
	ds_bpermute_b32 v122, v182, v12 offset:192
	v_mul_f32_e32 v12, v183, v184
	v_fmac_f32_e32 v13, v149, v189
	v_mul_f32_e32 v12, v148, v12
	ds_bpermute_b32 v145, v182, v13
	ds_bpermute_b32 v148, v182, v13 offset:64
	ds_bpermute_b32 v149, v182, v13 offset:128
	ds_bpermute_b32 v136, v182, v13 offset:192
	v_mul_f32_e32 v13, v191, v192
	v_fmac_f32_e32 v13, v193, v144
	v_mul_f32_e32 v13, v194, v13
	v_fmac_f32_e32 v13, v196, v195
	v_mul_f32_e32 v13, v197, v13
	v_mul_f32_e32 v12, v153, v12
	v_fmac_f32_e32 v13, v200, v198
	ds_bpermute_b32 v152, v182, v12
	ds_bpermute_b32 v153, v182, v12 offset:64
	ds_bpermute_b32 v163, v182, v12 offset:128
	ds_bpermute_b32 v183, v182, v12 offset:192
	v_mul_f32_e32 v12, v190, v191
	ds_bpermute_b32 v191, v182, v13
	ds_bpermute_b32 v192, v182, v13 offset:64
	ds_bpermute_b32 v193, v182, v13 offset:128
	ds_bpermute_b32 v137, v182, v13 offset:192
	v_mul_f32_e32 v13, v202, v201
	v_mul_f32_e32 v12, v194, v12
	v_fmac_f32_e32 v13, v203, v205
	v_mul_f32_e32 v12, v197, v12
	v_mul_f32_e32 v13, v204, v13
	ds_bpermute_b32 v194, v182, v12
	ds_bpermute_b32 v195, v182, v12 offset:64
	ds_bpermute_b32 v196, v182, v12 offset:128
	ds_bpermute_b32 v197, v182, v12 offset:192
	v_mul_f32_e32 v12, v199, v202
	v_fmac_f32_e32 v13, v206, v207
	v_mul_f32_e32 v12, v204, v12
	v_mul_f32_e32 v13, v208, v13
	v_mul_f32_e32 v12, v208, v12
	v_fmac_f32_e32 v13, v209, v210
	ds_bpermute_b32 v132, v182, v135
	ds_bpermute_b32 v133, v182, v135 offset:64
	ds_bpermute_b32 v134, v182, v135 offset:128
	ds_bpermute_b32 v135, v182, v135 offset:192
	ds_bpermute_b32 v187, v182, v12
	ds_bpermute_b32 v184, v182, v13
	ds_bpermute_b32 v188, v182, v12 offset:64
	ds_bpermute_b32 v185, v182, v13 offset:64
	ds_bpermute_b32 v189, v182, v12 offset:128
	ds_bpermute_b32 v186, v182, v13 offset:128
	ds_bpermute_b32 v190, v182, v12 offset:192
	ds_bpermute_b32 v144, v182, v13 offset:192
	s_ashr_i32 s2, s42, 2
	s_and_b32 s2, s2, -2
	s_add_i32 s28, s2, 0x100
	v_lshl_add_u64 v[12:13], v[10:11], 2, s[10:11]
	s_waitcnt vmcnt(0)
	s_and_saveexec_b64 s[6:7], s[4:5]
	s_cbranch_execz .LBB0_478
	s_waitcnt lgkmcnt(14)
	v_fmac_f32_e32 v191, 0, v194
	v_fmac_f32_e32 v145, 0, v152
	v_fmac_f32_e32 v192, v191, v195
	v_mul_f32_e32 v191, v152, v153
	v_fmac_f32_e32 v148, v145, v153
	s_waitcnt lgkmcnt(10)
	v_mul_f32_e32 v145, v132, v133
	v_fmac_f32_e32 v123, 0, v132
	v_mul_f32_e32 v10, v194, v195
	v_mul_f32_e32 v191, v191, v163
	s_waitcnt lgkmcnt(9)
	v_mul_f32_e32 v145, v145, v134
	v_fmac_f32_e32 v128, v123, v133
	v_mul_f32_e32 v10, v10, v196
	v_mul_f32_e32 v191, v191, v183
	s_waitcnt lgkmcnt(8)
	v_mul_f32_e32 v145, v145, v135
	v_fmac_f32_e32 v129, v128, v134
	s_waitcnt lgkmcnt(5)
	v_mul_f32_e32 v128, v187, v188
	v_mul_f32_e32 v10, v10, v197
	v_fmac_f32_e32 v149, v148, v163
	v_fmac_f32_e32 v122, v129, v135
	v_mul_f32_e32 v123, v145, v191
	s_waitcnt lgkmcnt(3)
	v_mul_f32_e32 v128, v128, v189
	v_fmac_f32_e32 v184, 0, v187
	s_ashr_i32 s29, s28, 31
	v_fmac_f32_e32 v193, v192, v196
	v_fmac_f32_e32 v136, v149, v183
	v_mul_f32_e32 v123, v123, v10
	s_waitcnt lgkmcnt(1)
	v_mul_f32_e32 v128, v128, v190
	v_fmac_f32_e32 v122, 0, v145
	v_fmac_f32_e32 v185, v184, v188
	s_lshl_b64 s[8:9], s[28:29], 13
	v_fmac_f32_e32 v137, v193, v197
	v_mul_f32_e32 v129, v123, v128
	v_fmac_f32_e32 v136, v122, v191
	v_fmac_f32_e32 v186, v185, v189
	v_lshl_add_u64 v[122:123], v[12:13], 0, s[8:9]
	v_fmac_f32_e32 v137, v136, v10
	s_waitcnt lgkmcnt(0)
	v_fmac_f32_e32 v144, v186, v190
	global_store_dword v[122:123], v129, off
	v_add_co_u32_e32 v122, vcc, 0x1000, v122
	v_fmac_f32_e32 v144, v137, v128
	s_nop 0
	v_addc_co_u32_e32 v123, vcc, 0, v123, vcc
	global_store_dword v[122:123], v144, off
.LBB0_478:
	s_or_b64 exec, exec, s[6:7]
	s_waitcnt lgkmcnt(8)
	v_mfma_f32_16x16x32_bf16 v[132:135], v[26:29], v[110:113], 0
	v_mfma_f32_16x16x32_bf16 v[26:29], v[26:29], v[118:121], 0
	s_waitcnt lgkmcnt(2)
	v_mfma_f32_16x16x32_bf16 v[184:187], v[50:53], v[110:113], 0
	v_mfma_f32_16x16x32_bf16 v[50:53], v[50:53], v[118:121], 0
	s_waitcnt lgkmcnt(1)
	v_mfma_f32_16x16x32_bf16 v[188:191], v[58:61], v[110:113], 0
	v_mfma_f32_16x16x32_bf16 v[58:61], v[58:61], v[118:121], 0
	v_mfma_f32_16x16x32_bf16 v[110:113], v[66:69], v[110:113], 0
	v_mfma_f32_16x16x32_bf16 v[66:69], v[66:69], v[118:121], 0
	v_mfma_f32_16x16x32_bf16 v[118:121], v[30:33], v[102:105], v[132:135]
	v_mfma_f32_16x16x32_bf16 v[26:29], v[30:33], v[114:117], v[26:29]
	v_mfma_f32_16x16x32_bf16 v[30:33], v[34:37], v[102:105], v[184:187]
	v_mfma_f32_16x16x32_bf16 v[34:37], v[34:37], v[114:117], v[50:53]
	v_mfma_f32_16x16x32_bf16 v[50:53], v[46:49], v[102:105], v[188:191]
	v_mfma_f32_16x16x32_bf16 v[46:49], v[46:49], v[114:117], v[58:61]
	v_mfma_f32_16x16x32_bf16 v[58:61], v[54:57], v[102:105], v[110:113]
	v_mfma_f32_16x16x32_bf16 v[54:57], v[54:57], v[114:117], v[66:69]
	v_mfma_f32_16x16x32_bf16 v[66:69], v[70:73], v[98:101], v[118:121]
	v_mfma_f32_16x16x32_bf16 v[34:37], v[78:81], v[106:109], v[34:37]
	v_mfma_f32_16x16x32_bf16 v[26:29], v[70:73], v[106:109], v[26:29]
	v_mfma_f32_16x16x32_bf16 v[70:73], v[78:81], v[98:101], v[30:33]
	v_mfma_f32_16x16x32_bf16 v[30:33], v[74:77], v[82:85], v[66:69]
	s_nop 3
	v_add_co_u32_e32 v66, vcc, s33, v164
	s_mov_b64 s[6:7], vcc
	v_add_co_u32_e32 v68, vcc, 0x1000, v166
	v_mfma_f32_16x16x32_bf16 v[78:81], v[90:93], v[98:101], v[58:61]
	s_mov_b64 s[8:9], vcc
	v_mfma_f32_16x16x32_bf16 v[58:61], v[62:65], v[94:97], v[34:37]
	s_nop 2
	v_add_co_u32_e32 v34, vcc, 0x1000, v168
	v_mfma_f32_16x16x32_bf16 v[50:53], v[86:89], v[98:101], v[50:53]
	s_nop 0
	v_addc_co_u32_e32 v35, vcc, 0, v169, vcc
	v_addc_co_u32_e64 v67, vcc, 0, v165, s[6:7]
	v_mfma_f32_16x16x32_bf16 v[46:49], v[86:89], v[106:109], v[46:49]
	v_addc_co_u32_e64 v69, vcc, 0, v167, s[8:9]
	s_cmp_lg_u32 s98, 0
	s_cbranch_scc1 .Lrgc_b_fast
	global_load_dword v10, v[68:69], off
	v_mfma_f32_16x16x32_bf16 v[86:89], v[90:93], v[106:109], v[54:57]
	v_mfma_f32_16x16x32_bf16 v[54:57], v[62:65], v[82:85], v[70:73]
	global_load_dword v64, v[34:35], off
	global_load_dword v62, v[66:67], off
	s_waitcnt vmcnt(1)
	v_xor_b32_e32 v63, 0x80000000, v64
	v_mfma_f32_16x16x32_bf16 v[26:29], v[74:77], v[94:97], v[26:29]
	v_cmp_ngt_f32_e32 vcc, s37, v64
	v_mfma_f32_16x16x32_bf16 v[50:53], v[42:45], v[82:85], v[50:53]
	v_mfma_f32_16x16x32_bf16 v[46:49], v[42:45], v[94:97], v[46:49]
	v_mfma_f32_16x16x32_bf16 v[42:45], v[38:41], v[82:85], v[78:81]
	v_mfma_f32_16x16x32_bf16 v[34:37], v[38:41], v[94:97], v[86:89]
	s_and_saveexec_b64 s[6:7], vcc
	s_cbranch_execz .LBB0_480
	v_mul_f32_e32 v38, 0xbfb8aa3b, v64
	v_exp_f32_e32 v63, v38
	s_nop 0
	v_add_f32_e32 v40, 1.0, v63
	v_frexp_mant_f32_e32 v64, v40
	v_cvt_f64_f32_e32 v[38:39], v40
	v_frexp_exp_i32_f64_e32 v38, v[38:39]
	v_cmp_gt_f32_e32 vcc, s38, v64
	v_add_f32_e32 v41, -1.0, v40
	v_sub_f32_e32 v65, v41, v40
	v_subbrev_co_u32_e32 v68, vcc, 0, v38, vcc
	v_sub_u32_e32 v38, 0, v68
	v_sub_f32_e32 v41, v63, v41
	v_add_f32_e32 v65, 1.0, v65
	v_ldexp_f32 v39, v40, v38
	v_add_f32_e32 v41, v41, v65
	v_add_f32_e32 v40, -1.0, v39
	v_add_f32_e32 v64, 1.0, v39
	v_ldexp_f32 v38, v41, v38
	v_add_f32_e32 v41, 1.0, v40
	v_add_f32_e32 v65, -1.0, v64
	v_sub_f32_e32 v41, v39, v41
	v_sub_f32_e32 v39, v39, v65
	v_add_f32_e32 v41, v38, v41
	v_add_f32_e32 v38, v38, v39
	v_add_f32_e32 v69, v64, v38
	v_rcp_f32_e32 v71, v69
	v_sub_f32_e32 v39, v69, v64
	v_sub_f32_e32 v70, v38, v39
	v_add_f32_e32 v39, v40, v41
	v_mul_f32_e32 v73, v39, v71
	v_sub_f32_e32 v38, v39, v40
	v_mul_f32_e32 v40, v69, v73
	v_fma_f32 v64, v73, v69, -v40
	v_fmac_f32_e32 v64, v73, v70
	v_sub_f32_e32 v72, v41, v38
	v_add_f32_e32 v38, v40, v64
	v_sub_f32_e32 v41, v39, v38
	v_pk_add_f32 v[66:67], v[38:39], v[40:41] neg_lo:[0,1] neg_hi:[0,1]
	v_mov_b32_e32 v65, v38
	v_pk_add_f32 v[38:39], v[66:67], v[64:65] neg_lo:[0,1] neg_hi:[0,1]
	v_cmp_neq_f32_e32 vcc, s40, v63
	v_add_f32_e32 v39, v72, v39
	v_add_f32_e32 v38, v38, v39
	v_add_f32_e32 v39, v41, v38
	v_mul_f32_e32 v72, v71, v39
	v_mul_f32_e32 v40, v69, v72
	v_fma_f32 v64, v72, v69, -v40
	v_fmac_f32_e32 v64, v72, v70
	v_sub_f32_e32 v41, v41, v39
	v_add_f32_e32 v69, v38, v41
	v_add_f32_e32 v38, v40, v64
	v_sub_f32_e32 v41, v39, v38
	v_pk_add_f32 v[66:67], v[38:39], v[40:41] neg_lo:[0,1] neg_hi:[0,1]
	v_mov_b32_e32 v65, v38
	v_pk_add_f32 v[38:39], v[66:67], v[64:65] neg_lo:[0,1] neg_hi:[0,1]
	s_nop 0
	v_add_f32_e32 v39, v69, v39
	v_add_f32_e32 v38, v38, v39
	v_add_f32_e32 v39, v73, v72
	v_add_f32_e32 v38, v41, v38
	v_sub_f32_e32 v40, v39, v73
	v_mul_f32_e32 v38, v71, v38
	v_sub_f32_e32 v40, v72, v40
	v_add_f32_e32 v40, v40, v38
	v_add_f32_e32 v64, v39, v40
	v_mul_f32_e32 v65, v64, v64
	v_fmamk_f32 v38, v65, 0x3e9b6dac, v177
	v_fmaak_f32 v163, v65, v38, 0x3f2aaada
	v_cvt_f32_i32_e32 v38, v68
	v_sub_f32_e32 v39, v64, v39
	v_sub_f32_e32 v39, v40, v39
	v_ldexp_f32 v66, v39, 1
	v_mul_f32_e32 v39, v64, v65
	v_ldexp_f32 v41, v64, 1
	v_pk_mul_f32 v[64:65], v[38:39], v[162:163]
	s_nop 0
	v_fma_f32 v40, v38, s39, -v64
	v_fmac_f32_e32 v40, 0xb102e308, v38
	v_pk_add_f32 v[38:39], v[64:65], v[40:41]
	s_nop 0
	v_sub_f32_e32 v41, v39, v41
	v_sub_f32_e32 v41, v65, v41
	v_add_f32_e32 v67, v66, v41
	v_mov_b32_e32 v66, v64
	v_pk_add_f32 v[64:65], v[38:39], v[64:65] neg_lo:[0,1] neg_hi:[0,1]
	v_pk_add_f32 v[68:69], v[38:39], v[66:67]
	v_mov_b32_e32 v41, v38
	v_mov_b32_e32 v65, v69
	v_pk_add_f32 v[70:71], v[40:41], v[64:65] neg_lo:[0,1] neg_hi:[0,1]
	v_pk_add_f32 v[40:41], v[40:41], v[64:65]
	v_mov_b32_e32 v66, v67
	v_pk_add_f32 v[64:65], v[40:41], v[38:39] op_sel:[1,0] op_sel_hi:[0,1] neg_lo:[0,1] neg_hi:[0,1]
	v_pk_add_f32 v[72:73], v[68:69], v[64:65] op_sel_hi:[1,0] neg_lo:[0,1] neg_hi:[0,1]
	v_mov_b32_e32 v68, v69
	v_mov_b32_e32 v69, v41
	v_pk_mov_b32 v[64:65], v[38:39], v[64:65] op_sel:[1,0]
	v_mov_b32_e32 v67, v38
	v_pk_add_f32 v[64:65], v[68:69], v[64:65] neg_lo:[0,1] neg_hi:[0,1]
	v_mov_b32_e32 v72, v70
	v_pk_add_f32 v[38:39], v[66:67], v[64:65] neg_lo:[0,1] neg_hi:[0,1]
	v_mov_b32_e32 v71, v41
	v_pk_add_f32 v[64:65], v[72:73], v[38:39]
	s_nop 0
	v_pk_add_f32 v[66:67], v[64:65], v[64:65] op_sel:[0,1] op_sel_hi:[1,0]
	s_nop 0
	v_pk_add_f32 v[40:41], v[40:41], v[66:67] op_sel:[1,0] op_sel_hi:[0,1]
	v_mov_b32_e32 v65, v40
	v_pk_add_f32 v[68:69], v[64:65], v[70:71] neg_lo:[0,1] neg_hi:[0,1]
	v_mov_b32_e32 v39, v66
	v_sub_f32_e32 v41, v64, v68
	v_pk_add_f32 v[38:39], v[38:39], v[68:69] neg_lo:[0,1] neg_hi:[0,1]
	v_sub_f32_e32 v41, v70, v41
	v_add_f32_e32 v38, v38, v41
	v_add_f32_e32 v38, v38, v39
	v_add_f32_e32 v38, v40, v38
	v_cndmask_b32_e32 v38, v179, v38, vcc
	v_cmp_ngt_f32_e32 vcc, -1.0, v63
	s_nop 1
	v_cndmask_b32_e32 v38, v180, v38, vcc
	v_cmp_neq_f32_e32 vcc, -1.0, v63
	s_nop 1
	v_cndmask_b32_e32 v38, v181, v38, vcc
	v_cmp_lt_f32_e64 vcc, |v63|, s41
	s_nop 1
	v_cndmask_b32_e32 v63, v38, v63, vcc
.LBB0_480:
	s_or_b64 exec, exec, s[6:7]
	v_lshlrev_b32_e32 v251, 2, v0
	v_add_u32_e32 v251, 0x24a00, v251
	ds_write_b32 v251, v63 offset:6144
	s_waitcnt vmcnt(0)
	ds_write_b32 v251, v62 offset:8192
	ds_write_b32 v251, v10 offset:10240
	s_mov_b32 s98, 1
	s_branch .Lrgc_b_join
.Lrgc_b_fast:
	v_mfma_f32_16x16x32_bf16 v[86:89], v[90:93], v[106:109], v[54:57]
	v_mfma_f32_16x16x32_bf16 v[54:57], v[62:65], v[82:85], v[70:73]
	v_lshlrev_b32_e32 v251, 2, v0
	v_add_u32_e32 v251, 0x24a00, v251
	ds_read_b32 v63, v251 offset:6144
	ds_read_b32 v62, v251 offset:8192
	ds_read_b32 v10, v251 offset:10240
	v_mfma_f32_16x16x32_bf16 v[26:29], v[74:77], v[94:97], v[26:29]
	v_mfma_f32_16x16x32_bf16 v[50:53], v[42:45], v[82:85], v[50:53]
	v_mfma_f32_16x16x32_bf16 v[46:49], v[42:45], v[94:97], v[46:49]
	v_mfma_f32_16x16x32_bf16 v[42:45], v[38:41], v[82:85], v[78:81]
	v_mfma_f32_16x16x32_bf16 v[34:37], v[38:41], v[94:97], v[86:89]
	s_nop 7
	s_waitcnt lgkmcnt(0)
.Lrgc_b_join:
	s_nop 0
	v_mul_f32_e32 v38, 0xbfb8aa3b, v62
	v_mul_f32_e32 v10, 0xbfb8aa3b, v10
	s_nop 1
	v_fmamk_f32 v34, v34, 0xbfb8aa3b, v10
	v_fmamk_f32 v43, v43, 0xbfb8aa3b, v38
	v_exp_f32_e32 v34, v34
	v_exp_f32_e32 v43, v43
	v_fmamk_f32 v35, v35, 0xbfb8aa3b, v10
	v_exp_f32_e32 v35, v35
	v_add_f32_e32 v34, 1.0, v34
	v_add_f32_e32 v43, 1.0, v43
	v_rcp_f32_e32 v34, v34
	v_rcp_f32_e32 v43, v43
	v_mul_f32_e32 v40, 0xc1800000, v63
	v_mul_f32_e32 v40, 0x3fb8aa3b, v40
	v_mul_f32_e32 v40, 0.5, v40
	v_mul_f32_e32 v70, v140, v34
	v_add_f32_e32 v34, 1.0, v35
	v_mul_f32_e32 v35, v43, v40
	v_exp_f32_e32 v43, v35
	v_fmamk_f32 v35, v44, 0xbfb8aa3b, v38
	v_exp_f32_e32 v35, v35
	v_fmamk_f32 v36, v36, 0xbfb8aa3b, v10
	v_rcp_f32_e32 v34, v34
	v_exp_f32_e32 v36, v36
	v_add_f32_e32 v35, 1.0, v35
	v_rcp_f32_e32 v35, v35
	v_fmamk_f32 v33, v33, 0xbfb8aa3b, v38
	v_fmamk_f32 v32, v32, 0xbfb8aa3b, v38
	v_fmamk_f32 v31, v31, 0xbfb8aa3b, v38
	v_mul_f32_e32 v35, v35, v40
	v_exp_f32_e32 v72, v35
	v_fmamk_f32 v35, v45, 0xbfb8aa3b, v38
	v_exp_f32_e32 v35, v35
	v_exp_f32_e32 v33, v33
	v_exp_f32_e32 v32, v32
	v_exp_f32_e32 v31, v31
	v_add_f32_e32 v35, 1.0, v35
	v_rcp_f32_e32 v35, v35
	v_mul_f32_e32 v71, v141, v34
	v_add_f32_e32 v34, 1.0, v36
	v_fmamk_f32 v37, v37, 0xbfb8aa3b, v10
	v_mul_f32_e32 v35, v35, v40
	v_rcp_f32_e32 v34, v34
	v_exp_f32_e32 v37, v37
	v_exp_f32_e32 v74, v35
	v_add_f32_e32 v33, 1.0, v33
	v_add_f32_e32 v32, 1.0, v32
	v_add_f32_e32 v31, 1.0, v31
	v_fmamk_f32 v39, v54, 0xbfb8aa3b, v38
	v_fmamk_f32 v54, v55, 0xbfb8aa3b, v38
	v_fmamk_f32 v56, v56, 0xbfb8aa3b, v38
	v_fmamk_f32 v57, v57, 0xbfb8aa3b, v38
	v_fmamk_f32 v50, v50, 0xbfb8aa3b, v38
	v_fmamk_f32 v51, v51, 0xbfb8aa3b, v38
	v_fmamk_f32 v52, v52, 0xbfb8aa3b, v38
	v_fmamk_f32 v53, v53, 0xbfb8aa3b, v38
	v_fmamk_f32 v42, v42, 0xbfb8aa3b, v38
	v_rcp_f32_e32 v33, v33
	v_rcp_f32_e32 v32, v32
	v_rcp_f32_e32 v31, v31
	v_fmac_f32_e32 v38, 0xbfb8aa3b, v30
	v_exp_f32_e32 v30, v38
	v_exp_f32_e32 v57, v57
	v_mul_f32_e32 v73, v130, v34
	v_add_f32_e32 v34, 1.0, v37
	v_fma_f32 v35, v74, v74, -1.0
	v_fmamk_f32 v41, v58, 0xbfb8aa3b, v10
	v_fmamk_f32 v58, v59, 0xbfb8aa3b, v10
	v_exp_f32_e32 v56, v56
	v_fmamk_f32 v60, v60, 0xbfb8aa3b, v10
	v_fmamk_f32 v61, v61, 0xbfb8aa3b, v10
	v_fmamk_f32 v46, v46, 0xbfb8aa3b, v10
	v_fmamk_f32 v47, v47, 0xbfb8aa3b, v10
	v_fmamk_f32 v48, v48, 0xbfb8aa3b, v10
	v_fmamk_f32 v49, v49, 0xbfb8aa3b, v10
	v_rcp_f32_e32 v34, v34
	v_max_f32_e64 v35, -v35, 0
	v_mul_f32_e32 v33, v33, v40
	v_mul_f32_e32 v32, v32, v40
	v_mul_f32_e32 v31, v31, v40
	v_fmamk_f32 v26, v26, 0xbfb8aa3b, v10
	v_fmamk_f32 v27, v27, 0xbfb8aa3b, v10
	v_fmamk_f32 v28, v28, 0xbfb8aa3b, v10
	v_fmac_f32_e32 v10, 0xbfb8aa3b, v29
	v_sqrt_f32_e32 v35, v35
	v_exp_f32_e32 v33, v33
	v_exp_f32_e32 v32, v32
	v_add_f32_e32 v30, 1.0, v30
	v_exp_f32_e32 v31, v31
	v_exp_f32_e32 v10, v10
	v_exp_f32_e32 v54, v54
	v_add_f32_e32 v57, 1.0, v57
	v_rcp_f32_e32 v30, v30
	v_rcp_f32_e32 v57, v57
	v_fma_f32 v36, v72, v72, -1.0
	v_exp_f32_e32 v28, v28
	v_exp_f32_e32 v39, v39
	v_add_f32_e32 v56, 1.0, v56
	v_max_f32_e64 v36, -v36, 0
	v_mul_f32_e32 v34, v131, v34
	v_rcp_f32_e32 v56, v56
	v_exp_f32_e32 v53, v53
	v_sqrt_f32_e32 v45, v36
	v_mul_f32_e32 v75, v34, v35
	v_mul_f32_e32 v34, v33, v32
	v_exp_f32_e32 v27, v27
	v_fma_f32 v36, v31, v31, -1.0
	v_add_f32_e32 v10, 1.0, v10
	v_fma_f32 v33, v33, v33, -1.0
	v_add_f32_e32 v54, 1.0, v54
	v_mul_f32_e32 v30, v30, v40
	v_max_f32_e64 v36, -v36, 0
	v_rcp_f32_e32 v10, v10
	v_max_f32_e64 v33, -v33, 0
	v_rcp_f32_e32 v54, v54
	v_mul_f32_e32 v57, v57, v40
	v_exp_f32_e32 v52, v52
	v_exp_f32_e32 v26, v26
	v_exp_f32_e32 v30, v30
	v_add_f32_e32 v28, 1.0, v28
	v_sqrt_f32_e32 v29, v36
	v_fma_f32 v36, v32, v32, -1.0
	v_sqrt_f32_e32 v33, v33
	v_add_f32_e32 v39, 1.0, v39
	v_exp_f32_e32 v61, v61
	v_exp_f32_e32 v57, v57
	v_rcp_f32_e32 v28, v28
	v_max_f32_e64 v36, -v36, 0
	v_rcp_f32_e32 v39, v39
	v_mul_f32_e32 v56, v56, v40
	v_exp_f32_e32 v51, v51
	v_add_f32_e32 v53, 1.0, v53
	v_add_f32_e32 v27, 1.0, v27
	v_sqrt_f32_e32 v36, v36
	v_exp_f32_e32 v60, v60
	v_exp_f32_e32 v56, v56
	v_rcp_f32_e32 v53, v53
	v_rcp_f32_e32 v27, v27
	v_mul_f32_e32 v10, v127, v10
	v_mul_f32_e32 v54, v54, v40
	v_exp_f32_e32 v50, v50
	v_add_f32_e32 v52, 1.0, v52
	v_add_f32_e32 v26, 1.0, v26
	v_fma_f32 v35, v30, v30, -1.0
	v_mul_f32_e32 v10, v10, v33
	v_exp_f32_e32 v58, v58
	v_exp_f32_e32 v54, v54
	v_add_f32_e32 v61, 1.0, v61
	v_fma_f32 v66, v57, v57, -1.0
	v_rcp_f32_e32 v52, v52
	v_rcp_f32_e32 v26, v26
	v_max_f32_e64 v35, -v35, 0
	v_mul_f32_e32 v28, v126, v28
	v_mul_f32_e32 v10, v32, v10
	v_mul_f32_e32 v39, v39, v40
	v_rcp_f32_e32 v61, v61
	v_max_f32_e64 v66, -v66, 0
	v_add_f32_e32 v51, 1.0, v51
	v_sqrt_f32_e32 v35, v35
	v_fmac_f32_e32 v10, v28, v36
	v_exp_f32_e32 v41, v41
	v_exp_f32_e32 v39, v39
	v_add_f32_e32 v60, 1.0, v60
	v_fma_f32 v63, v56, v56, -1.0
	v_sqrt_f32_e32 v66, v66
	v_rcp_f32_e32 v51, v51
	v_mul_f32_e32 v53, v53, v40
	v_exp_f32_e32 v42, v42
	v_mul_f32_e32 v27, v125, v27
	v_mul_f32_e32 v10, v31, v10
	v_rcp_f32_e32 v60, v60
	v_max_f32_e64 v63, -v63, 0
	v_add_f32_e32 v50, 1.0, v50
	v_exp_f32_e32 v49, v49
	v_exp_f32_e32 v53, v53
	v_fmac_f32_e32 v10, v27, v29
	v_add_f32_e32 v58, 1.0, v58
	v_fma_f32 v59, v54, v54, -1.0
	v_sqrt_f32_e32 v63, v63
	v_rcp_f32_e32 v50, v50
	v_mul_f32_e32 v52, v52, v40
	v_mul_f32_e32 v26, v124, v26
	v_mul_f32_e32 v32, v30, v10
	v_rcp_f32_e32 v58, v58
	v_max_f32_e64 v59, -v59, 0
	v_mul_f32_e32 v61, v147, v61
	v_exp_f32_e32 v48, v48
	v_exp_f32_e32 v52, v52
	v_mul_f32_e32 v34, v31, v34
	v_fmac_f32_e32 v32, v26, v35
	v_mul_f32_e32 v26, v57, v56
	v_or_b32_e32 v64, 64, v182
	v_or_b32_e32 v65, 0x80, v182
	v_or_b32_e32 v62, 0xc0, v182
	v_add_f32_e32 v41, 1.0, v41
	v_fma_f32 v55, v39, v39, -1.0
	v_sqrt_f32_e32 v59, v59
	v_mul_f32_e32 v61, v61, v66
	v_mul_f32_e32 v51, v51, v40
	v_add_f32_e32 v42, 1.0, v42
	v_mul_f32_e32 v34, v30, v34
	v_mul_f32_e32 v26, v54, v26
	v_rcp_f32_e32 v41, v41
	v_max_f32_e64 v55, -v55, 0
	v_mul_f32_e32 v60, v146, v60
	v_exp_f32_e32 v47, v47
	v_exp_f32_e32 v51, v51
	v_add_f32_e32 v49, 1.0, v49
	v_fma_f32 v69, v53, v53, -1.0
	v_rcp_f32_e32 v42, v42
	ds_bpermute_b32 v27, v182, v34
	ds_bpermute_b32 v29, v64, v34
	ds_bpermute_b32 v31, v65, v34
	ds_bpermute_b32 v33, v62, v34
	v_mul_f32_e32 v34, v39, v26
	v_mul_f32_e32 v26, v56, v61
	v_sqrt_f32_e32 v55, v55
	v_mul_f32_e32 v50, v50, v40
	v_rcp_f32_e32 v49, v49
	v_max_f32_e64 v69, -v69, 0
	v_fmac_f32_e32 v26, v60, v63
	v_mul_f32_e32 v58, v151, v58
	v_exp_f32_e32 v46, v46
	v_exp_f32_e32 v50, v50
	v_add_f32_e32 v48, 1.0, v48
	v_fma_f32 v68, v52, v52, -1.0
	v_sqrt_f32_e32 v69, v69
	v_mul_f32_e32 v26, v54, v26
	v_rcp_f32_e32 v48, v48
	v_max_f32_e64 v68, -v68, 0
	v_fmac_f32_e32 v26, v58, v59
	v_mul_f32_e32 v41, v150, v41
	v_add_f32_e32 v47, 1.0, v47
	v_fma_f32 v67, v51, v51, -1.0
	v_sqrt_f32_e32 v68, v68
	v_mul_f32_e32 v42, v42, v40
	v_mul_f32_e32 v40, v39, v26
	v_rcp_f32_e32 v47, v47
	v_max_f32_e64 v67, -v67, 0
	v_mul_f32_e32 v49, v139, v49
	v_fmac_f32_e32 v40, v41, v55
	ds_bpermute_b32 v35, v182, v34
	ds_bpermute_b32 v37, v64, v34
	ds_bpermute_b32 v39, v65, v34
	ds_bpermute_b32 v41, v62, v34
	v_mul_f32_e32 v34, v53, v52
	v_add_f32_e32 v46, 1.0, v46
	v_fma_f32 v66, v50, v50, -1.0
	v_sqrt_f32_e32 v67, v67
	v_mul_f32_e32 v49, v49, v69
	v_mul_f32_e32 v34, v51, v34
	v_rcp_f32_e32 v46, v46
	v_max_f32_e64 v66, -v66, 0
	v_mul_f32_e32 v48, v138, v48
	v_mul_f32_e32 v55, v50, v34
	v_mul_f32_e32 v34, v52, v49
	v_sqrt_f32_e32 v66, v66
	v_fmac_f32_e32 v34, v48, v68
	v_mul_f32_e32 v47, v143, v47
	v_exp_f32_e32 v42, v42
	v_mul_f32_e32 v34, v51, v34
	v_fmac_f32_e32 v34, v47, v67
	v_mul_f32_e32 v46, v142, v46
	v_fma_f32 v44, v43, v43, -1.0
	v_mul_f32_e32 v47, v50, v34
	v_max_f32_e64 v44, -v44, 0
	v_fmac_f32_e32 v47, v46, v66
	v_mul_f32_e32 v46, v74, v72
	v_fma_f32 v69, v42, v42, -1.0
	v_sqrt_f32_e32 v44, v44
	v_mul_f32_e32 v46, v43, v46
	v_max_f32_e64 v69, -v69, 0
	v_mul_f32_e32 v48, v42, v46
	v_mul_f32_e32 v46, v72, v75
	v_sqrt_f32_e32 v69, v69
	v_fmac_f32_e32 v46, v73, v45
	v_mul_f32_e32 v43, v43, v46
	v_fmac_f32_e32 v43, v71, v44
	v_mul_f32_e32 v57, v42, v43
	v_fmac_f32_e32 v57, v70, v69
	ds_bpermute_b32 v10, v182, v32
	ds_bpermute_b32 v28, v64, v32
	ds_bpermute_b32 v30, v65, v32
	ds_bpermute_b32 v32, v62, v32
	ds_bpermute_b32 v26, v182, v40
	ds_bpermute_b32 v36, v64, v40
	ds_bpermute_b32 v38, v65, v40
	ds_bpermute_b32 v40, v62, v40
	ds_bpermute_b32 v50, v182, v55
	ds_bpermute_b32 v34, v182, v47
	ds_bpermute_b32 v52, v64, v55
	ds_bpermute_b32 v51, v64, v47
	ds_bpermute_b32 v54, v65, v55
	ds_bpermute_b32 v53, v65, v47
	ds_bpermute_b32 v56, v62, v55
	ds_bpermute_b32 v55, v62, v47
	ds_bpermute_b32 v43, v182, v48
	ds_bpermute_b32 v42, v182, v57
	ds_bpermute_b32 v45, v64, v48
	ds_bpermute_b32 v44, v64, v57
	ds_bpermute_b32 v47, v65, v48
	ds_bpermute_b32 v46, v65, v57
	ds_bpermute_b32 v49, v62, v48
	ds_bpermute_b32 v48, v62, v57
	s_and_saveexec_b64 s[6:7], s[4:5]
	s_cbranch_execz .LBB0_482
	s_waitcnt lgkmcnt(8)
	v_fmac_f32_e32 v55, 0, v56
	v_mul_f32_e32 v57, v54, v56
	v_fmac_f32_e32 v53, v55, v54
	v_mul_f32_e32 v57, v57, v52
	v_fmac_f32_e32 v51, v53, v52
	v_fmac_f32_e32 v40, 0, v41
	v_mul_f32_e32 v57, v57, v50
	v_fmac_f32_e32 v34, v51, v50
	v_mul_f32_e32 v50, v39, v41
	v_fmac_f32_e32 v38, v40, v39
	v_mul_f32_e32 v50, v50, v37
	v_fmac_f32_e32 v36, v38, v37
	v_fmac_f32_e32 v32, 0, v33
	v_mul_f32_e32 v50, v50, v35
	v_fmac_f32_e32 v26, v36, v35
	v_mul_f32_e32 v35, v31, v33
	v_fmac_f32_e32 v30, v32, v31
	v_mul_f32_e32 v35, v35, v29
	v_fmac_f32_e32 v28, v30, v29
	v_mul_f32_e32 v35, v35, v27
	v_fmac_f32_e32 v10, v28, v27
	s_waitcnt lgkmcnt(1)
	v_mul_f32_e32 v27, v47, v49
	s_waitcnt lgkmcnt(0)
	v_fmac_f32_e32 v48, 0, v49
	v_mul_f32_e32 v27, v27, v45
	v_fmac_f32_e32 v46, v48, v47
	v_mul_f32_e32 v27, v27, v43
	v_fmac_f32_e32 v44, v46, v45
	s_or_b32 s8, s28, 1
	v_mul_f32_e32 v28, v57, v27
	v_fmac_f32_e32 v42, v44, v43
	s_ashr_i32 s9, s8, 31
	v_mul_f32_e32 v28, v50, v28
	v_fmac_f32_e32 v42, 0, v27
	s_lshl_b64 s[8:9], s[8:9], 13
	v_mul_f32_e32 v28, v35, v28
	v_fmac_f32_e32 v34, v57, v42
	v_lshl_add_u64 v[12:13], v[12:13], 0, s[8:9]
	v_fmac_f32_e32 v26, v50, v34
	global_store_dword v[12:13], v28, off
	v_add_co_u32_e32 v12, vcc, 0x1000, v12
	v_fmac_f32_e32 v10, v35, v26
	s_nop 0
	v_addc_co_u32_e32 v13, vcc, 0, v13, vcc
	global_store_dword v[12:13], v10, off

.LBB0_796:
	s_or_b64 exec, exec, s[12:13]
	s_waitcnt lgkmcnt(0)
	v_cndmask_b32_e64 v4, v11, 1.0, s[10:11]
	v_mul_f32_e32 v8, v4, v13
	v_cndmask_b32_e64 v4, v4, v8, s[6:7]
	v_mul_f32_e32 v8, v4, v9
	v_cndmask_b32_e64 v4, v4, v8, s[4:5]
	v_cndmask_b32_e64 v8, v62, 0, s[10:11]
	v_fmac_f32_e32 v63, v8, v13
	v_cndmask_b32_e64 v8, v8, v63, s[6:7]
	v_fmac_f32_e32 v10, v8, v9
	v_cndmask_b32_e64 v8, v8, v10, s[4:5]
	v_fmac_f32_e32 v8, v4, v64
	v_cndmask_b32_e64 v4, v204, 1.0, s[4:5]
	v_mul_f32_e32 v9, v4, v200
	v_cndmask_b32_e64 v4, v4, v9, s[8:9]
	v_mul_f32_e32 v9, v4, v198
	v_cndmask_b32_e64 v4, v4, v9, s[10:11]
	v_cndmask_b32_e64 v9, v202, 0, s[4:5]
	v_fmac_f32_e32 v201, v9, v200
	v_cndmask_b32_e64 v9, v9, v201, s[8:9]
	v_fmac_f32_e32 v199, v9, v198
	v_cndmask_b32_e64 v9, v9, v199, s[10:11]
	v_fmac_f32_e32 v9, v4, v230
	v_fmac_f32_e32 v196, v197, v9
	v_fmac_f32_e32 v5, v20, v8
	v_add_f32_e32 v4, 0, v196
	v_fmac_f32_e32 v194, v195, v9
	v_add_f32_e32 v4, v4, v5
	v_fmac_f32_e32 v2, v21, v8
	v_add_f32_e32 v5, 0, v194
	v_fmac_f32_e32 v192, v193, v9
	v_add_f32_e32 v2, v5, v2
	v_fmac_f32_e32 v6, v22, v8
	v_add_f32_e32 v5, 0, v192
	v_fmac_f32_e32 v191, v190, v9
	v_add_f32_e32 v5, v5, v6
	v_fmac_f32_e32 v7, v23, v8
	v_add_f32_e32 v6, 0, v191
	v_add_f32_e32 v6, v6, v7
	v_cndmask_b32_e64 v7, v60, 1.0, s[10:11]
	v_mul_f32_e32 v8, v7, v55
	v_cndmask_b32_e64 v7, v7, v8, s[6:7]
	v_mul_f32_e32 v8, v7, v56
	v_cndmask_b32_e64 v7, v7, v8, s[4:5]
	v_cndmask_b32_e64 v8, v59, 0, s[10:11]
	v_fmac_f32_e32 v58, v8, v55
	v_cndmask_b32_e64 v8, v8, v58, s[6:7]
	v_fmac_f32_e32 v57, v8, v56
	v_cndmask_b32_e64 v8, v8, v57, s[4:5]
	v_fmac_f32_e32 v8, v7, v61
	v_cndmask_b32_e64 v7, v229, 1.0, s[4:5]
	v_mul_f32_e32 v9, v7, v226
	v_cndmask_b32_e64 v7, v7, v9, s[8:9]
	v_mul_f32_e32 v9, v7, v224
	v_cndmask_b32_e64 v7, v7, v9, s[10:11]
	v_cndmask_b32_e64 v9, v228, 0, s[4:5]
	v_fmac_f32_e32 v227, v9, v226
	v_cndmask_b32_e64 v9, v9, v227, s[8:9]
	v_fmac_f32_e32 v225, v9, v224
	v_cndmask_b32_e64 v9, v9, v225, s[10:11]
	v_fmac_f32_e32 v9, v7, v189
	v_fmac_f32_e32 v222, v223, v9
	v_fmac_f32_e32 v220, v221, v9
	v_fmac_f32_e32 v212, v213, v9
	v_fmac_f32_e32 v185, v184, v9
	v_cndmask_b32_e64 v9, v53, 1.0, s[10:11]
	v_mul_f32_e32 v12, v9, v48
	v_cndmask_b32_e64 v9, v9, v12, s[6:7]
	v_mul_f32_e32 v12, v9, v49
	v_cndmask_b32_e64 v9, v9, v12, s[4:5]
	v_cndmask_b32_e64 v12, v52, 0, s[10:11]
	v_fmac_f32_e32 v51, v12, v48
	v_cndmask_b32_e64 v12, v12, v51, s[6:7]
	v_fmac_f32_e32 v50, v12, v49
	v_cndmask_b32_e64 v12, v12, v50, s[4:5]
	v_fmac_f32_e32 v12, v9, v54
	v_cndmask_b32_e64 v9, v219, 1.0, s[4:5]
	v_mul_f32_e32 v13, v9, v216
	v_cndmask_b32_e64 v9, v9, v13, s[8:9]
	v_mul_f32_e32 v13, v9, v214
	v_cndmask_b32_e64 v9, v9, v13, s[10:11]
	v_cndmask_b32_e64 v13, v218, 0, s[4:5]
	v_fmac_f32_e32 v217, v13, v216
	v_cndmask_b32_e64 v13, v13, v217, s[8:9]
	v_fmac_f32_e32 v215, v13, v214
	v_cndmask_b32_e64 v13, v13, v215, s[10:11]
	v_fmac_f32_e32 v13, v9, v207
	v_fmac_f32_e32 v210, v211, v13
	v_fmac_f32_e32 v208, v209, v13
	v_fmac_f32_e32 v205, v206, v13
	v_fmac_f32_e32 v187, v186, v13
	v_cndmask_b32_e64 v13, v41, 1.0, s[10:11]
	v_fmac_f32_e32 v17, v16, v12
	v_mul_f32_e32 v16, v13, v37
	v_cndmask_b32_e64 v13, v13, v16, s[6:7]
	v_mul_f32_e32 v16, v13, v30
	v_cndmask_b32_e64 v13, v13, v16, s[4:5]
	v_cndmask_b32_e64 v16, v40, 0, s[10:11]
	v_fmac_f32_e32 v39, v16, v37
	v_cndmask_b32_e64 v16, v16, v39, s[6:7]
	v_fmac_f32_e32 v38, v16, v30
	v_cndmask_b32_e64 v16, v16, v38, s[4:5]
	v_fmac_f32_e32 v16, v3, v13
	v_cndmask_b32_e64 v3, v109, 1.0, s[4:5]
	v_mul_f32_e32 v13, v3, v105
	v_cndmask_b32_e64 v3, v3, v13, s[8:9]
	v_mul_f32_e32 v13, v3, v107
	v_cndmask_b32_e64 v3, v3, v13, s[10:11]
	v_cndmask_b32_e64 v13, v129, 0, s[4:5]
	v_fmac_f32_e32 v128, v13, v105
	v_cndmask_b32_e64 v13, v13, v128, s[8:9]
	v_fmac_f32_e32 v104, v13, v107
	v_cndmask_b32_e64 v13, v13, v104, s[10:11]
	v_fmac_f32_e32 v13, v3, v203
	v_add_f32_e32 v9, 0, v210
	v_fmac_f32_e32 v102, v103, v13
	v_fmac_f32_e32 v15, v14, v8
	v_add_f32_e32 v7, 0, v222
	v_add_f32_e32 v9, v9, v17
	v_fmac_f32_e32 v34, v36, v12
	v_add_f32_e32 v14, 0, v208
	v_fmac_f32_e32 v124, v125, v13
	v_fmac_f32_e32 v27, v29, v16
	v_add_f32_e32 v17, 0, v102
	v_fmac_f32_e32 v100, v101, v13
	v_fmac_f32_e32 v99, v188, v13
	v_add_f32_e32 v7, v7, v15
	v_fmac_f32_e32 v45, v47, v8
	v_add_f32_e32 v10, 0, v220
	v_fmac_f32_e32 v43, v46, v8
	v_add_f32_e32 v11, 0, v212
	v_fmac_f32_e32 v42, v44, v8
	v_add_f32_e32 v8, 0, v185
	v_add_f32_e32 v14, v14, v34
	v_fmac_f32_e32 v32, v35, v12
	v_add_f32_e32 v15, 0, v205
	v_fmac_f32_e32 v31, v33, v12
	v_add_f32_e32 v12, 0, v187
	v_fmac_f32_e32 v19, v18, v16
	v_add_f32_e32 v3, 0, v124
	v_add_f32_e32 v17, v17, v27
	v_fmac_f32_e32 v25, v28, v16
	v_add_f32_e32 v18, 0, v100
	v_fmac_f32_e32 v24, v26, v16
	v_add_f32_e32 v13, 0, v99
	v_add_f32_e32 v10, v10, v45
	v_add_f32_e32 v11, v11, v43
	v_add_f32_e32 v8, v8, v42
	v_add_f32_e32 v15, v15, v32
	v_add_f32_e32 v12, v12, v31
	v_add_f32_e32 v3, v3, v19
	v_add_f32_e32 v18, v18, v25
	v_add_f32_e32 v13, v13, v24
	ds_write2st64_b32 v143, v6, v5 offset0:196 offset1:198
	ds_write2st64_b32 v143, v2, v4 offset0:200 offset1:202
	ds_write2st64_b32 v143, v8, v11 offset0:228 offset1:230
	ds_write2st64_b32 v143, v10, v7 offset0:232 offset1:234
	ds_write_b32 v170, v12 offset:50176
	ds_write_b32 v171, v15 offset:50176
	ds_write_b32 v172, v14 offset:50176
	ds_write_b32 v173, v9 offset:50176
	ds_write_b32 v174, v13 offset:50176
	ds_write_b32 v175, v18 offset:50176
	ds_write_b32 v176, v17 offset:50176
	ds_write_b32 v177, v3 offset:50176
	v_or_b32_e32 v14, s52, v158
	v_mov_b64_e32 v[16:17], s[74:75]
	v_mad_i64_i32 v[2:3], s[12:13], v14, s33, v[16:17]
	s_lshl_b32 s2, s53, 1
	v_lshl_add_u64 v[2:3], v[2:3], 0, s[2:3]
	v_lshlrev_b32_e32 v136, 1, v132
	v_lshl_add_u64 v[2:3], v[2:3], 0, v[136:137]
	v_add_co_u32_e32 v2, vcc, s42, v2
	s_nop 1
	v_addc_co_u32_e32 v3, vcc, 0, v3, vcc
	global_load_dwordx4 v[2:5], v[2:3], off offset:2048
	v_add_u32_e32 v251, s52, v163
	v_mad_i64_i32 v[252:253], s[12:13], v251, s33, v[16:17]
	v_lshl_add_u64 v[252:253], v[252:253], 0, s[2:3]
	v_lshl_add_u64 v[252:253], v[252:253], 0, v[136:137]
	v_add_co_u32_e32 v252, vcc, s42, v252
	s_nop 1
	v_addc_co_u32_e32 v253, vcc, 0, v253, vcc
	global_load_dwordx4 v[252:255], v[252:253], off offset:2048
	s_waitcnt lgkmcnt(0)
	s_barrier
	s_nop 0
	v_ashrrev_i32_e32 v15, 31, v14
	s_add_i32 s51, s51, s70
	s_cmpk_gt_i32 s51, 0x3ff
	s_waitcnt vmcnt(1)
	v_lshlrev_b32_e32 v18, 16, v2
	v_and_b32_e32 v19, 0xffff0000, v2
	v_mul_f32_e32 v2, 0xbfb8aa3b, v18
	v_exp_f32_e32 v2, v2
	v_mul_f32_e32 v6, 0xbfb8aa3b, v19
	v_exp_f32_e32 v6, v6
	v_add_f32_e32 v2, 1.0, v2
	v_rcp_f32_e32 v20, v2
	v_add_f32_e32 v2, 1.0, v6
	v_rcp_f32_e32 v21, v2
	ds_read_b128 v[6:9], v178 offset:50176
	ds_read_b128 v[10:13], v178 offset:50192
	v_pk_mul_f32 v[18:19], v[20:21], v[18:19]
	v_lshlrev_b32_e32 v20, 16, v4
	v_and_b32_e32 v21, 0xffff0000, v4
	v_mul_f32_e32 v2, 0xbfb8aa3b, v20
	v_exp_f32_e32 v2, v2
	v_mul_f32_e32 v4, 0xbfb8aa3b, v21
	v_exp_f32_e32 v4, v4
	s_waitcnt lgkmcnt(1)
	v_pk_mul_f32 v[6:7], v[6:7], v[18:19]
	v_add_f32_e32 v2, 1.0, v2
	v_rcp_f32_e32 v18, v2
	v_add_f32_e32 v2, 1.0, v4
	v_rcp_f32_e32 v19, v2
	v_lshlrev_b32_e32 v2, 16, v3
	v_and_b32_e32 v3, 0xffff0000, v3
	v_mul_f32_e32 v4, 0xbfb8aa3b, v2
	v_pk_mul_f32 v[18:19], v[18:19], v[20:21]
	v_lshlrev_b32_e32 v20, 16, v5
	v_mul_f32_e32 v22, 0xbfb8aa3b, v3
	v_and_b32_e32 v21, 0xffff0000, v5
	v_mul_f32_e32 v5, 0xbfb8aa3b, v20
	v_exp_f32_e32 v4, v4
	v_exp_f32_e32 v22, v22
	v_exp_f32_e32 v23, v5
	v_mul_f32_e32 v5, 0xbfb8aa3b, v21
	v_exp_f32_e32 v24, v5
	v_add_f32_e32 v4, 1.0, v4
	v_add_f32_e32 v22, 1.0, v22
	v_rcp_f32_e32 v4, v4
	v_rcp_f32_e32 v5, v22
	v_add_f32_e32 v22, 1.0, v23
	v_add_f32_e32 v23, 1.0, v24
	v_rcp_f32_e32 v22, v22
	v_rcp_f32_e32 v23, v23
	v_pk_mul_f32 v[2:3], v[4:5], v[2:3]
	s_waitcnt lgkmcnt(0)
	v_pk_mul_f32 v[10:11], v[10:11], v[18:19]
	v_pk_mul_f32 v[4:5], v[8:9], v[2:3]
	v_pk_mul_f32 v[2:3], v[22:23], v[20:21]
	s_nop 0
	v_pk_mul_f32 v[8:9], v[12:13], v[2:3]
	v_cvt_pk_bf16_f32 v2, v6, v7
	v_lshlrev_b64 v[6:7], 12, v[14:15]
	v_lshl_add_u64 v[6:7], s[72:73], 0, v[6:7]
	v_lshl_add_u64 v[6:7], v[6:7], 0, s[2:3]
	v_cvt_pk_bf16_f32 v3, v4, v5
	v_cvt_pk_bf16_f32 v4, v10, v11
	v_cvt_pk_bf16_f32 v5, v8, v9
	v_lshl_add_u64 v[6:7], v[6:7], 0, v[136:137]
	v_add_u32_e32 v14, s52, v163
	global_store_dwordx4 v[6:7], v[2:5], off offset:2048
	v_ashrrev_i32_e32 v15, 31, v14
	s_nop 0
	s_waitcnt vmcnt(1)
	v_mov_b32_e32 v2, v252
	v_mov_b32_e32 v3, v253
	v_mov_b32_e32 v4, v254
	v_mov_b32_e32 v5, v255
	v_lshlrev_b32_e32 v16, 16, v2
	v_and_b32_e32 v17, 0xffff0000, v2
	v_mul_f32_e32 v2, 0xbfb8aa3b, v16
	v_exp_f32_e32 v2, v2
	v_mul_f32_e32 v6, 0xbfb8aa3b, v17
	v_exp_f32_e32 v6, v6
	v_add_f32_e32 v2, 1.0, v2
	v_rcp_f32_e32 v18, v2
	v_add_f32_e32 v2, 1.0, v6
	v_rcp_f32_e32 v19, v2
	ds_read_b128 v[6:9], v179 offset:50176
	ds_read_b128 v[10:13], v179 offset:50192
	v_pk_mul_f32 v[16:17], v[18:19], v[16:17]
	v_lshlrev_b32_e32 v18, 16, v4
	v_and_b32_e32 v19, 0xffff0000, v4
	v_mul_f32_e32 v2, 0xbfb8aa3b, v18
	v_exp_f32_e32 v2, v2
	v_mul_f32_e32 v4, 0xbfb8aa3b, v19
	v_exp_f32_e32 v4, v4
	s_waitcnt lgkmcnt(1)
	v_pk_mul_f32 v[6:7], v[6:7], v[16:17]
	v_add_f32_e32 v2, 1.0, v2
	v_rcp_f32_e32 v16, v2
	v_add_f32_e32 v2, 1.0, v4
	v_rcp_f32_e32 v17, v2
	v_lshlrev_b32_e32 v2, 16, v3
	v_and_b32_e32 v3, 0xffff0000, v3
	v_mul_f32_e32 v4, 0xbfb8aa3b, v2
	v_pk_mul_f32 v[16:17], v[16:17], v[18:19]
	v_lshlrev_b32_e32 v18, 16, v5
	v_mul_f32_e32 v20, 0xbfb8aa3b, v3
	v_and_b32_e32 v19, 0xffff0000, v5
	v_mul_f32_e32 v5, 0xbfb8aa3b, v18
	v_exp_f32_e32 v4, v4
	v_exp_f32_e32 v20, v20
	v_exp_f32_e32 v21, v5
	v_mul_f32_e32 v5, 0xbfb8aa3b, v19
	v_exp_f32_e32 v22, v5
	v_add_f32_e32 v4, 1.0, v4
	v_add_f32_e32 v20, 1.0, v20
	v_rcp_f32_e32 v4, v4
	v_rcp_f32_e32 v5, v20
	v_add_f32_e32 v20, 1.0, v21
	v_add_f32_e32 v21, 1.0, v22
	v_rcp_f32_e32 v20, v20
	v_rcp_f32_e32 v21, v21
	v_pk_mul_f32 v[2:3], v[4:5], v[2:3]
	s_waitcnt lgkmcnt(0)
	v_pk_mul_f32 v[10:11], v[10:11], v[16:17]
	v_pk_mul_f32 v[4:5], v[8:9], v[2:3]
	v_pk_mul_f32 v[2:3], v[20:21], v[18:19]
	s_nop 0
	v_pk_mul_f32 v[8:9], v[12:13], v[2:3]
	v_cvt_pk_bf16_f32 v2, v6, v7
	v_lshlrev_b64 v[6:7], 12, v[14:15]
	v_lshl_add_u64 v[6:7], s[72:73], 0, v[6:7]
	v_lshl_add_u64 v[6:7], v[6:7], 0, s[2:3]
	v_cvt_pk_bf16_f32 v3, v4, v5
	v_cvt_pk_bf16_f32 v4, v10, v11
	v_cvt_pk_bf16_f32 v5, v8, v9
	v_lshl_add_u64 v[6:7], v[6:7], 0, v[136:137]
	global_store_dwordx4 v[6:7], v[2:5], off offset:2048
	s_waitcnt lgkmcnt(0)
	s_barrier
	s_cbranch_scc1 .LBB0_819

.LBB0_811:
	v_or_b32_e32 v22, s53, v131
	v_lshlrev_b32_e32 v136, 2, v22
	s_waitcnt lgkmcnt(0)
	v_lshl_add_u64 v[58:59], s[16:17], 0, v[136:137]
	global_load_dwordx4 v[22:25], v136, s[16:17] offset:16
	global_load_dwordx4 v[26:29], v136, s[18:19] offset:16
	v_lshl_add_u64 v[38:39], v[58:59], 0, s[26:27]
	v_add_co_u32_e32 v50, vcc, s44, v58
	global_load_dwordx4 v[30:33], v136, s[16:17]
	global_load_dwordx4 v[34:37], v136, s[18:19]
	s_nop 0
	global_load_dwordx4 v[38:41], v[38:39], off offset:16
	v_addc_co_u32_e32 v51, vcc, 0, v59, vcc
	v_lshl_add_u64 v[46:47], v[58:59], 0, s[28:29]
	global_load_dwordx4 v[42:45], v[50:51], off offset:-4096
	v_lshl_add_u64 v[54:55], v[58:59], 0, s[30:31]
	global_load_dwordx4 v[46:49], v[46:47], off offset:16
	v_add_co_u32_e32 v58, vcc, s33, v58
	global_load_dwordx4 v[50:53], v[50:51], off
	s_nop 0
	global_load_dwordx4 v[54:57], v[54:55], off offset:16
	v_addc_co_u32_e32 v59, vcc, 0, v59, vcc
	global_load_dwordx4 v[58:61], v[58:59], off
	s_lshl_b32 s2, s2, 15
	v_lshl_add_u64 v[78:79], v[140:141], 0, s[2:3]
	global_load_dwordx4 v[62:65], v[78:79], off
	global_load_dwordx4 v[66:69], v[78:79], off offset:64
	s_mov_b32 s13, s3
	s_or_b32 s12, s2, 0x80000
	v_lshl_add_u64 v[108:109], v[140:141], 0, s[12:13]
	global_load_dwordx4 v[70:73], v[108:109], off
	global_load_dwordx4 v[74:77], v[78:79], off offset:128
	s_nop 0
	global_load_dwordx4 v[78:81], v[78:79], off offset:192
	s_nop 0
	global_load_dwordx4 v[82:85], v[108:109], off offset:64
	global_load_dwordx4 v[86:89], v[108:109], off offset:128
	global_load_dwordx4 v[110:113], v[108:109], off offset:192
	s_waitcnt vmcnt(18)
	v_lshlrev_b32_e32 v90, 16, v13
	v_and_b32_e32 v91, 0xffff0000, v13
	v_lshlrev_b32_e32 v92, 16, v9
	v_and_b32_e32 v93, 0xffff0000, v9
	v_lshlrev_b32_e32 v94, 16, v21
	v_and_b32_e32 v95, 0xffff0000, v21
	v_lshlrev_b32_e32 v100, 16, v12
	v_and_b32_e32 v101, 0xffff0000, v12
	v_lshlrev_b32_e32 v12, 16, v8
	v_and_b32_e32 v13, 0xffff0000, v8
	v_lshlrev_b32_e32 v8, 16, v20
	v_and_b32_e32 v9, 0xffff0000, v20
	v_lshlrev_b32_e32 v20, 16, v4
	v_and_b32_e32 v21, 0xffff0000, v4
	v_lshlrev_b32_e32 v96, 16, v5
	v_and_b32_e32 v97, 0xffff0000, v5
	v_lshlrev_b32_e32 v106, 16, v3
	v_and_b32_e32 v107, 0xffff0000, v3
	v_lshlrev_b32_e32 v98, 16, v17
	v_and_b32_e32 v99, 0xffff0000, v17
	v_lshlrev_b32_e32 v4, 16, v16
	v_and_b32_e32 v5, 0xffff0000, v16
	v_lshlrev_b32_e32 v16, 16, v11
	v_and_b32_e32 v17, 0xffff0000, v11
	v_lshlrev_b32_e32 v102, 16, v7
	v_and_b32_e32 v103, 0xffff0000, v7
	v_lshlrev_b32_e32 v104, 16, v19
	v_and_b32_e32 v105, 0xffff0000, v19
	v_and_b32_e32 v19, 0xffff0000, v2
	s_add_u32 s40, s74, s2
	s_addc_u32 s41, s75, 0
	v_mov_b32_e32 v143, v137
	s_add_u32 s12, s74, s12
	s_addc_u32 s13, s75, 0
	v_add_u32_e32 v136, s53, v134
	v_lshlrev_b64 v[150:151], 2, v[136:137]
	v_lshl_add_u64 v[152:153], s[22:23], 0, v[150:151]
	v_lshl_add_u64 v[148:149], s[0:1], 0, v[150:151]
	v_lshl_add_u64 v[150:151], s[20:21], 0, v[150:151]
	s_waitcnt vmcnt(16)
	v_pk_fma_f32 v[20:21], v[22:23], v[20:21], v[26:27]
	v_pk_fma_f32 v[108:109], v[24:25], v[90:91], v[28:29]
	v_pk_fma_f32 v[24:25], v[24:25], v[96:97], v[28:29]
	v_pk_fma_f32 v[28:29], v[22:23], v[100:101], v[26:27]
	s_waitcnt vmcnt(14)
	v_pk_fma_f32 v[26:27], v[32:33], v[106:107], v[36:37]
	s_waitcnt vmcnt(13)
	v_pk_fma_f32 v[20:21], v[38:39], v[100:101], v[20:21]
	v_pk_fma_f32 v[22:23], v[32:33], v[16:17], v[36:37]
	v_pk_fma_f32 v[24:25], v[40:41], v[90:91], v[24:25]
	v_pk_fma_f32 v[28:29], v[38:39], v[12:13], v[28:29]
	s_waitcnt vmcnt(12)
	v_pk_fma_f32 v[16:17], v[44:45], v[16:17], v[26:27]
	s_waitcnt vmcnt(11)
	v_pk_fma_f32 v[12:13], v[46:47], v[12:13], v[20:21]
	v_pk_fma_f32 v[32:33], v[40:41], v[92:93], v[108:109]
	v_pk_fma_f32 v[22:23], v[44:45], v[102:103], v[22:23]
	v_pk_fma_f32 v[24:25], v[48:49], v[92:93], v[24:25]
	v_pk_fma_f32 v[28:29], v[46:47], v[8:9], v[28:29]
	s_waitcnt vmcnt(10)
	v_pk_fma_f32 v[16:17], v[52:53], v[102:103], v[16:17]
	s_waitcnt vmcnt(9)
	v_pk_fma_f32 v[20:21], v[54:55], v[8:9], v[12:13]
	v_lshlrev_b32_e32 v12, 16, v10
	v_and_b32_e32 v13, 0xffff0000, v10
	v_pk_fma_f32 v[26:27], v[48:49], v[94:95], v[32:33]
	v_pk_fma_f32 v[32:33], v[52:53], v[104:105], v[22:23]
	v_pk_fma_f32 v[22:23], v[56:57], v[94:95], v[24:25]
	v_pk_fma_f32 v[24:25], v[54:55], v[4:5], v[28:29]
	s_waitcnt vmcnt(8)
	v_pk_fma_f32 v[4:5], v[60:61], v[104:105], v[16:17]
	v_pk_fma_f32 v[10:11], v[30:31], v[12:13], v[34:35]
	v_lshlrev_b32_e32 v16, 16, v6
	v_and_b32_e32 v17, 0xffff0000, v6
	v_pk_fma_f32 v[6:7], v[42:43], v[16:17], v[10:11]
	v_lshlrev_b32_e32 v10, 16, v18
	v_and_b32_e32 v11, 0xffff0000, v18
	v_lshlrev_b32_e32 v18, 16, v2
	v_pk_fma_f32 v[2:3], v[30:31], v[18:19], v[34:35]
	v_lshlrev_b32_e32 v8, 16, v15
	v_pk_fma_f32 v[2:3], v[42:43], v[12:13], v[2:3]
	v_and_b32_e32 v9, 0xffff0000, v15
	v_pk_fma_f32 v[2:3], v[50:51], v[16:17], v[2:3]
	v_pk_fma_f32 v[6:7], v[50:51], v[10:11], v[6:7]
	v_pk_fma_f32 v[2:3], v[58:59], v[10:11], v[2:3]
	v_lshlrev_b32_e32 v10, 16, v14
	v_and_b32_e32 v11, 0xffff0000, v14
	v_pk_fma_f32 v[26:27], v[56:57], v[98:99], v[26:27]
	v_pk_fma_f32 v[8:9], v[60:61], v[8:9], v[32:33]
	v_pk_fma_f32 v[6:7], v[58:59], v[10:11], v[6:7]
	v_cvt_pk_bf16_f32 v10, v2, v3
	v_cvt_pk_bf16_f32 v11, v4, v5
	v_cvt_pk_bf16_f32 v12, v20, v21
	v_cvt_pk_bf16_f32 v13, v22, v23
	ds_write_b128 v164, v[10:13]
	ds_write_b128 v165, v[2:5] offset:17408
	ds_write_b128 v165, v[20:23] offset:17424
	v_cvt_pk_bf16_f32 v2, v6, v7
	v_cvt_pk_bf16_f32 v3, v8, v9
	v_cvt_pk_bf16_f32 v4, v24, v25
	v_cvt_pk_bf16_f32 v5, v26, v27
	ds_write_b128 v166, v[2:5]
	ds_write_b128 v167, v[6:9] offset:17408
	ds_write_b128 v167, v[24:27] offset:17424
	s_waitcnt lgkmcnt(0)
	s_barrier
	ds_read_b128 v[2:5], v168
	ds_read_b128 v[6:9], v168 offset:64
	ds_read_b128 v[26:29], v168 offset:4352
	ds_read_b128 v[10:13], v168 offset:4416
	ds_read_b128 v[34:37], v168 offset:8704
	ds_read_b128 v[22:25], v168 offset:8768
	s_waitcnt vmcnt(7) lgkmcnt(5)
	v_mfma_f32_16x16x32_bf16 v[14:17], v[2:5], v[62:65], 0
	ds_read_b128 v[42:45], v168 offset:13056
	ds_read_b128 v[30:33], v168 offset:13120
	s_waitcnt vmcnt(5)
	v_mfma_f32_16x16x32_bf16 v[18:21], v[2:5], v[70:73], 0
	s_waitcnt lgkmcnt(5)
	v_mfma_f32_16x16x32_bf16 v[46:49], v[26:29], v[70:73], 0
	s_waitcnt lgkmcnt(3)
	v_mfma_f32_16x16x32_bf16 v[50:53], v[34:37], v[62:65], 0
	v_mfma_f32_16x16x32_bf16 v[38:41], v[26:29], v[62:65], 0
	v_mfma_f32_16x16x32_bf16 v[54:57], v[34:37], v[70:73], 0
	s_waitcnt lgkmcnt(1)
	v_mfma_f32_16x16x32_bf16 v[58:61], v[42:45], v[62:65], 0
	v_mfma_f32_16x16x32_bf16 v[62:65], v[42:45], v[70:73], 0
	v_mfma_f32_16x16x32_bf16 v[14:17], v[6:9], v[66:69], v[14:17]
	s_waitcnt vmcnt(2)
	v_mfma_f32_16x16x32_bf16 v[18:21], v[6:9], v[82:85], v[18:21]
	v_mfma_f32_16x16x32_bf16 v[90:93], v[10:13], v[82:85], v[46:49]
	v_mfma_f32_16x16x32_bf16 v[94:97], v[22:25], v[66:69], v[50:53]
	s_nop 1
	ds_read_b128 v[46:49], v168 offset:128
	ds_read_b128 v[50:53], v168 offset:192
	v_mfma_f32_16x16x32_bf16 v[70:73], v[10:13], v[66:69], v[38:41]
	v_mfma_f32_16x16x32_bf16 v[98:101], v[22:25], v[82:85], v[54:57]
	s_nop 2
	ds_read_b128 v[54:57], v168 offset:4480
	ds_read_b128 v[38:41], v168 offset:4544
	s_waitcnt lgkmcnt(4)
	v_mfma_f32_16x16x32_bf16 v[102:105], v[30:33], v[66:69], v[58:61]
	v_mfma_f32_16x16x32_bf16 v[62:65], v[30:33], v[82:85], v[62:65]
	s_waitcnt lgkmcnt(3)
	v_mfma_f32_16x16x32_bf16 v[82:85], v[46:49], v[74:77], v[14:17]
	s_waitcnt vmcnt(1)
	v_mfma_f32_16x16x32_bf16 v[106:109], v[46:49], v[86:89], v[18:21]
	ds_read_b128 v[58:61], v168 offset:8832
	s_nop 1
	ds_read_b128 v[18:21], v168 offset:8896
	ds_read_b128 v[66:69], v168 offset:13184
	ds_read_b128 v[14:17], v168 offset:13248
	s_waitcnt lgkmcnt(5)
	v_mfma_f32_16x16x32_bf16 v[70:73], v[54:57], v[74:77], v[70:73]
	s_waitcnt lgkmcnt(1)
	v_mfma_f32_16x16x32_bf16 v[184:187], v[66:69], v[86:89], v[62:65]
	s_nop 2
	v_lshl_add_u64 v[62:63], s[40:41], 0, v[138:139]
	v_lshl_add_u64 v[62:63], v[62:63], 0, v[142:143]
	v_mfma_f32_16x16x32_bf16 v[90:93], v[54:57], v[86:89], v[90:93]
	v_lshl_add_u64 v[64:65], v[62:63], 0, s[34:35]
	v_add_co_u32_e32 v62, vcc, s45, v62
	v_mfma_f32_16x16x32_bf16 v[94:97], v[58:61], v[74:77], v[94:97]
	s_nop 0
	v_addc_co_u32_e32 v63, vcc, 0, v63, vcc
	v_mfma_f32_16x16x32_bf16 v[74:77], v[66:69], v[74:77], v[102:105]
	v_mfma_f32_16x16x32_bf16 v[126:129], v[38:41], v[78:81], v[70:73]
	s_nop 2
	v_lshl_add_u64 v[70:71], s[12:13], 0, v[138:139]
	v_lshl_add_u64 v[70:71], v[70:71], 0, v[142:143]
	v_lshl_add_u64 v[72:73], v[70:71], 0, s[34:35]
	v_add_co_u32_e32 v70, vcc, s45, v70
	v_mfma_f32_16x16x32_bf16 v[114:117], v[58:61], v[86:89], v[98:101]
	s_nop 0
	v_addc_co_u32_e32 v71, vcc, 0, v71, vcc
	v_mfma_f32_16x16x32_bf16 v[102:105], v[50:53], v[78:81], v[82:85]
	s_waitcnt vmcnt(0)
	v_mfma_f32_16x16x32_bf16 v[98:101], v[50:53], v[110:113], v[106:109]
	v_mfma_f32_16x16x32_bf16 v[122:125], v[38:41], v[110:113], v[90:93]
	v_mfma_f32_16x16x32_bf16 v[118:121], v[18:21], v[78:81], v[94:97]
	s_waitcnt lgkmcnt(0)
	v_mfma_f32_16x16x32_bf16 v[106:109], v[14:17], v[78:81], v[74:77]
	global_load_dwordx4 v[78:81], v[64:65], off offset:64
	s_nop 1
	global_load_dwordx4 v[74:77], v[64:65], off offset:128
	global_load_dwordx4 v[86:89], v[62:63], off
	s_nop 0
	global_load_dwordx4 v[62:65], v[64:65], off offset:192
	s_nop 0
	global_load_dwordx4 v[90:93], v[72:73], off offset:64
	global_load_dwordx4 v[82:85], v[72:73], off offset:128
	global_load_dwordx4 v[94:97], v[70:71], off
	s_nop 0
	global_load_dwordx4 v[70:73], v[72:73], off offset:192
	s_nop 0
	s_cmp_lg_u32 s98, 0
	s_cbranch_scc1 .Lrgc_c_fast
	global_load_dword v146, v[152:153], off
	global_load_dword v154, v[148:149], off
	global_load_dword v143, v[150:151], off
	v_mfma_f32_16x16x32_bf16 v[114:117], v[18:21], v[110:113], v[114:117]
	s_waitcnt vmcnt(2)
	v_xor_b32_e32 v145, 0x80000000, v146
	v_mfma_f32_16x16x32_bf16 v[110:113], v[14:17], v[110:113], v[184:187]
	v_cmp_ngt_f32_e32 vcc, s46, v146
	s_and_saveexec_b64 s[12:13], vcc
	s_cbranch_execz .LBB0_813
	v_mul_f32_e32 v145, 0xbfb8aa3b, v146
	v_exp_f32_e32 v155, v145
	s_nop 0
	v_add_f32_e32 v145, 1.0, v155
	v_frexp_mant_f32_e32 v157, v145
	v_cvt_f64_f32_e32 v[146:147], v145
	v_add_f32_e32 v156, -1.0, v145
	v_frexp_exp_i32_f64_e32 v146, v[146:147]
	v_cmp_gt_f32_e32 vcc, s47, v157
	v_sub_f32_e32 v184, v156, v145
	v_sub_f32_e32 v156, v155, v156
	v_subbrev_co_u32_e32 v188, vcc, 0, v146, vcc
	v_add_f32_e32 v184, 1.0, v184
	v_sub_u32_e32 v146, 0, v188
	v_add_f32_e32 v156, v156, v184
	v_ldexp_f32 v145, v145, v146
	v_ldexp_f32 v146, v156, v146
	v_add_f32_e32 v156, -1.0, v145
	v_add_f32_e32 v147, 1.0, v156
	v_sub_f32_e32 v147, v145, v147
	v_add_f32_e32 v157, v146, v147
	v_add_f32_e32 v147, 1.0, v145
	v_add_f32_e32 v184, -1.0, v147
	v_sub_f32_e32 v145, v145, v184
	v_add_f32_e32 v145, v146, v145
	v_add_f32_e32 v189, v147, v145
	v_rcp_f32_e32 v190, v189
	v_sub_f32_e32 v146, v189, v147
	v_add_f32_e32 v147, v156, v157
	v_sub_f32_e32 v145, v145, v146
	v_mul_f32_e32 v192, v147, v190
	v_sub_f32_e32 v146, v147, v156
	v_mul_f32_e32 v156, v189, v192
	v_fma_f32 v184, v192, v189, -v156
	v_fmac_f32_e32 v184, v192, v145
	v_sub_f32_e32 v191, v157, v146
	v_add_f32_e32 v146, v156, v184
	v_sub_f32_e32 v157, v147, v146
	v_pk_add_f32 v[186:187], v[146:147], v[156:157] neg_lo:[0,1] neg_hi:[0,1]
	v_mov_b32_e32 v185, v146
	v_pk_add_f32 v[146:147], v[186:187], v[184:185] neg_lo:[0,1] neg_hi:[0,1]
	v_cmp_neq_f32_e32 vcc, s49, v155
	v_add_f32_e32 v147, v191, v147
	v_add_f32_e32 v146, v146, v147
	v_add_f32_e32 v147, v157, v146
	v_mul_f32_e32 v191, v190, v147
	v_mul_f32_e32 v156, v189, v191
	v_fma_f32 v184, v191, v189, -v156
	v_fmac_f32_e32 v184, v191, v145
	v_sub_f32_e32 v145, v157, v147
	v_add_f32_e32 v145, v146, v145
	v_add_f32_e32 v146, v156, v184
	v_sub_f32_e32 v157, v147, v146
	v_pk_add_f32 v[186:187], v[146:147], v[156:157] neg_lo:[0,1] neg_hi:[0,1]
	v_mov_b32_e32 v185, v146
	v_pk_add_f32 v[146:147], v[186:187], v[184:185] neg_lo:[0,1] neg_hi:[0,1]
	s_nop 0
	v_add_f32_e32 v145, v145, v147
	v_add_f32_e32 v145, v146, v145
	v_add_f32_e32 v147, v192, v191
	v_add_f32_e32 v145, v157, v145
	v_sub_f32_e32 v146, v147, v192
	v_mul_f32_e32 v145, v190, v145
	v_sub_f32_e32 v146, v191, v146
	v_add_f32_e32 v156, v146, v145
	v_add_f32_e32 v184, v147, v156
	v_cvt_f32_i32_e32 v146, v188
	v_mul_f32_e32 v185, v184, v184
	v_sub_f32_e32 v147, v184, v147
	v_fmamk_f32 v145, v185, 0x3e9b6dac, v169
	v_sub_f32_e32 v147, v156, v147
	v_fmaak_f32 v145, v185, v145, 0x3f2aaada
	v_ldexp_f32 v186, v147, 1
	v_mul_f32_e32 v147, v184, v185
	v_ldexp_f32 v157, v184, 1
	v_pk_mul_f32 v[184:185], v[146:147], v[144:145]
	s_nop 0
	v_fma_f32 v156, v146, s48, -v184
	v_fmac_f32_e32 v156, 0xb102e308, v146
	v_pk_add_f32 v[146:147], v[184:185], v[156:157]
	s_nop 0
	v_sub_f32_e32 v145, v147, v157
	v_sub_f32_e32 v145, v185, v145
	v_add_f32_e32 v187, v186, v145
	v_mov_b32_e32 v186, v184
	v_pk_add_f32 v[184:185], v[146:147], v[184:185] neg_lo:[0,1] neg_hi:[0,1]
	v_pk_add_f32 v[188:189], v[146:147], v[186:187]
	v_mov_b32_e32 v157, v146
	v_mov_b32_e32 v185, v189
	v_pk_add_f32 v[190:191], v[156:157], v[184:185] neg_lo:[0,1] neg_hi:[0,1]
	v_pk_add_f32 v[156:157], v[156:157], v[184:185]
	v_mov_b32_e32 v186, v187
	v_pk_add_f32 v[184:185], v[156:157], v[146:147] op_sel:[1,0] op_sel_hi:[0,1] neg_lo:[0,1] neg_hi:[0,1]
	v_pk_add_f32 v[192:193], v[188:189], v[184:185] op_sel_hi:[1,0] neg_lo:[0,1] neg_hi:[0,1]
	v_mov_b32_e32 v188, v189
	v_mov_b32_e32 v189, v157
	v_pk_mov_b32 v[184:185], v[146:147], v[184:185] op_sel:[1,0]
	v_mov_b32_e32 v187, v146
	v_pk_add_f32 v[184:185], v[188:189], v[184:185] neg_lo:[0,1] neg_hi:[0,1]
	v_mov_b32_e32 v192, v190
	v_pk_add_f32 v[146:147], v[186:187], v[184:185] neg_lo:[0,1] neg_hi:[0,1]
	v_mov_b32_e32 v191, v157
	v_pk_add_f32 v[184:185], v[192:193], v[146:147]
	s_nop 0
	v_pk_add_f32 v[186:187], v[184:185], v[184:185] op_sel:[0,1] op_sel_hi:[1,0]
	s_nop 0
	v_pk_add_f32 v[156:157], v[156:157], v[186:187] op_sel:[1,0] op_sel_hi:[0,1]
	v_mov_b32_e32 v185, v156
	v_pk_add_f32 v[188:189], v[184:185], v[190:191] neg_lo:[0,1] neg_hi:[0,1]
	v_mov_b32_e32 v147, v186
	v_sub_f32_e32 v145, v184, v188
	v_pk_add_f32 v[146:147], v[146:147], v[188:189] neg_lo:[0,1] neg_hi:[0,1]
	v_sub_f32_e32 v145, v190, v145
	v_add_f32_e32 v145, v146, v145
	v_add_f32_e32 v145, v145, v147
	v_add_f32_e32 v145, v156, v145
	v_cndmask_b32_e32 v145, v180, v145, vcc
	v_cmp_ngt_f32_e32 vcc, -1.0, v155
	s_nop 1
	v_cndmask_b32_e32 v145, v181, v145, vcc
	v_cmp_neq_f32_e32 vcc, -1.0, v155
	s_nop 1
	v_cndmask_b32_e32 v145, v182, v145, vcc
	v_cmp_lt_f32_e64 vcc, |v155|, s50
	s_nop 1
	v_cndmask_b32_e32 v145, v145, v155, vcc
.LBB0_813:
	s_or_b64 exec, exec, s[12:13]
	v_lshlrev_b32_e32 v251, 2, v0
	v_add_u32_e32 v251, 0x24a00, v251
	ds_write_b32 v251, v145 offset:0
	s_waitcnt vmcnt(0)
	ds_write_b32 v251, v154 offset:2048
	ds_write_b32 v251, v143 offset:4096
	s_branch .Lrgc_c_join
.Lrgc_c_fast:
	v_mfma_f32_16x16x32_bf16 v[114:117], v[18:21], v[110:113], v[114:117]
	v_mfma_f32_16x16x32_bf16 v[110:113], v[14:17], v[110:113], v[184:187]
	v_lshlrev_b32_e32 v251, 2, v0
	v_add_u32_e32 v251, 0x24a00, v251
	ds_read_b32 v145, v251 offset:0
	ds_read_b32 v154, v251 offset:2048
	ds_read_b32 v143, v251 offset:4096
	s_nop 7
	s_waitcnt lgkmcnt(0)
.Lrgc_c_join:
	s_nop 0
	v_mul_f32_e32 v154, 0xbfb8aa3b, v154
	v_fmamk_f32 v126, v126, 0xbfb8aa3b, v154
	v_exp_f32_e32 v126, v126
	s_nop 0
	v_mul_f32_e32 v157, 0xbfb8aa3b, v143
	v_mul_f32_e32 v143, 0xc1800000, v145
	v_mul_f32_e32 v143, 0x3fb8aa3b, v143
	v_add_f32_e32 v126, 1.0, v126
	v_rcp_f32_e32 v126, v126
	v_mul_f32_e32 v145, 0.5, v143
	v_fmamk_f32 v122, v122, 0xbfb8aa3b, v157
	v_exp_f32_e32 v122, v122
	v_mul_f32_e32 v126, v126, v145
	v_exp_f32_e32 v184, v126
	v_fmamk_f32 v127, v127, 0xbfb8aa3b, v154
	v_exp_f32_e32 v155, v127
	v_add_u32_e32 v143, v162, v135
	v_fma_f32 v126, v184, v184, -1.0
	v_max_f32_e64 v126, -v126, 0
	v_add_f32_e32 v122, 1.0, v122
	v_sqrt_f32_e32 v156, v126
	ds_read2st64_b32 v[126:127], v143 offset0:100 offset1:102
	v_rcp_f32_e32 v122, v122
	v_add_f32_e32 v155, 1.0, v155
	v_fmamk_f32 v123, v123, 0xbfb8aa3b, v157
	v_exp_f32_e32 v123, v123
	v_rcp_f32_e32 v155, v155
	s_waitcnt lgkmcnt(0)
	v_mul_f32_e32 v122, v122, v126
	v_mul_f32_e32 v185, v122, v156
	v_add_f32_e32 v122, 1.0, v123
	v_mul_f32_e32 v123, v155, v145
	v_exp_f32_e32 v203, v123
	v_fmamk_f32 v123, v128, 0xbfb8aa3b, v154
	v_exp_f32_e32 v123, v123
	v_fmamk_f32 v124, v124, 0xbfb8aa3b, v157
	v_rcp_f32_e32 v122, v122
	v_exp_f32_e32 v124, v124
	v_add_f32_e32 v123, 1.0, v123
	v_rcp_f32_e32 v123, v123
	v_mul_f32_e32 v205, v122, v127
	v_add_f32_e32 v122, 1.0, v124
	v_rcp_f32_e32 v124, v122
	v_mul_f32_e32 v123, v123, v145
	v_exp_f32_e32 v206, v123
	v_fmamk_f32 v122, v129, 0xbfb8aa3b, v154
	v_fmamk_f32 v118, v118, 0xbfb8aa3b, v154
	v_exp_f32_e32 v129, v122
	v_exp_f32_e32 v118, v118
	v_fma_f32 v122, v206, v206, -1.0
	v_max_f32_e64 v155, -v122, 0
	ds_read2st64_b32 v[122:123], v143 offset0:104 offset1:106
	v_fmamk_f32 v125, v125, 0xbfb8aa3b, v157
	v_add_f32_e32 v129, 1.0, v129
	v_exp_f32_e32 v125, v125
	v_add_f32_e32 v118, 1.0, v118
	v_rcp_f32_e32 v129, v129
	v_rcp_f32_e32 v118, v118
	s_waitcnt lgkmcnt(0)
	v_mul_f32_e32 v208, v124, v122
	v_add_f32_e32 v124, 1.0, v125
	v_mul_f32_e32 v125, v129, v145
	v_rcp_f32_e32 v124, v124
	v_mul_f32_e32 v118, v118, v145
	v_exp_f32_e32 v209, v125
	v_exp_f32_e32 v186, v118
	v_fmamk_f32 v114, v114, 0xbfb8aa3b, v157
	v_exp_f32_e32 v114, v114
	v_fmamk_f32 v119, v119, 0xbfb8aa3b, v154
	v_mul_f32_e32 v211, v124, v123
	v_exp_f32_e32 v124, v119
	v_fma_f32 v125, v209, v209, -1.0
	v_fma_f32 v118, v186, v186, -1.0
	v_max_f32_e64 v125, -v125, 0
	v_max_f32_e64 v118, -v118, 0
	v_sqrt_f32_e32 v210, v125
	v_add_f32_e32 v114, 1.0, v114
	v_sqrt_f32_e32 v125, v118
	ds_read2st64_b32 v[118:119], v143 offset0:132 offset1:134
	v_rcp_f32_e32 v114, v114
	v_add_f32_e32 v124, 1.0, v124
	v_fmamk_f32 v115, v115, 0xbfb8aa3b, v157
	v_exp_f32_e32 v115, v115
	v_rcp_f32_e32 v124, v124
	s_waitcnt lgkmcnt(0)
	v_mul_f32_e32 v114, v114, v118
	v_mul_f32_e32 v187, v114, v125
	v_add_f32_e32 v114, 1.0, v115
	v_mul_f32_e32 v115, v124, v145
	v_exp_f32_e32 v214, v115
	v_fmamk_f32 v115, v120, 0xbfb8aa3b, v154
	v_exp_f32_e32 v115, v115
	v_fmamk_f32 v116, v116, 0xbfb8aa3b, v157
	v_fmamk_f32 v106, v106, 0xbfb8aa3b, v154
	v_rcp_f32_e32 v114, v114
	v_add_f32_e32 v115, 1.0, v115
	v_rcp_f32_e32 v115, v115
	v_exp_f32_e32 v116, v116
	v_exp_f32_e32 v106, v106
	v_fma_f32 v120, v214, v214, -1.0
	v_max_f32_e64 v120, -v120, 0
	v_mul_f32_e32 v115, v115, v145
	v_sqrt_f32_e32 v215, v120
	v_mul_f32_e32 v216, v114, v119
	v_add_f32_e32 v114, 1.0, v116
	v_exp_f32_e32 v217, v115
	v_fmamk_f32 v115, v121, 0xbfb8aa3b, v154
	ds_read2st64_b32 v[120:121], v143 offset0:136 offset1:138
	v_fmamk_f32 v117, v117, 0xbfb8aa3b, v157
	v_add_f32_e32 v106, 1.0, v106
	v_rcp_f32_e32 v114, v114
	v_exp_f32_e32 v117, v117
	v_rcp_f32_e32 v106, v106
	v_exp_f32_e32 v115, v115
	v_fmamk_f32 v108, v108, 0xbfb8aa3b, v154
	v_exp_f32_e32 v108, v108
	s_waitcnt lgkmcnt(0)
	v_mul_f32_e32 v219, v114, v120
	v_add_f32_e32 v114, 1.0, v117
	v_mul_f32_e32 v106, v106, v145
	v_add_f32_e32 v115, 1.0, v115
	v_rcp_f32_e32 v114, v114
	v_exp_f32_e32 v188, v106
	v_rcp_f32_e32 v115, v115
	v_fmamk_f32 v110, v110, 0xbfb8aa3b, v157
	v_add_f32_e32 v108, 1.0, v108
	v_exp_f32_e32 v110, v110
	v_rcp_f32_e32 v108, v108
	v_fma_f32 v116, v217, v217, -1.0
	v_mul_f32_e32 v106, v114, v121
	v_fma_f32 v114, v188, v188, -1.0
	v_max_f32_e64 v116, -v116, 0
	v_mul_f32_e32 v115, v115, v145
	v_max_f32_e64 v114, -v114, 0
	v_fmamk_f32 v107, v107, 0xbfb8aa3b, v154
	v_sqrt_f32_e32 v218, v116
	v_exp_f32_e32 v231, v115
	v_add_f32_e32 v110, 1.0, v110
	v_sqrt_f32_e32 v125, v114
	ds_read2st64_b32 v[116:117], v143 offset0:164 offset1:166
	v_exp_f32_e32 v114, v107
	v_fmamk_f32 v107, v111, 0xbfb8aa3b, v157
	v_mul_f32_e32 v108, v108, v145
	v_rcp_f32_e32 v110, v110
	v_exp_f32_e32 v111, v107
	v_exp_f32_e32 v129, v108
	v_fmamk_f32 v108, v109, 0xbfb8aa3b, v154
	v_fmamk_f32 v109, v113, 0xbfb8aa3b, v157
	v_fmamk_f32 v105, v105, 0xbfb8aa3b, v154
	v_exp_f32_e32 v109, v109
	v_exp_f32_e32 v105, v105
	v_fmamk_f32 v104, v104, 0xbfb8aa3b, v154
	v_fma_f32 v115, v231, v231, -1.0
	v_exp_f32_e32 v104, v104
	v_max_f32_e64 v115, -v115, 0
	s_waitcnt lgkmcnt(0)
	v_mul_f32_e32 v107, v110, v116
	v_add_f32_e32 v110, 1.0, v114
	v_add_f32_e32 v111, 1.0, v111
	v_sqrt_f32_e32 v232, v115
	v_rcp_f32_e32 v110, v110
	v_rcp_f32_e32 v124, v111
	v_fmamk_f32 v111, v112, 0xbfb8aa3b, v157
	v_exp_f32_e32 v108, v108
	ds_read2st64_b32 v[114:115], v143 offset0:168 offset1:170
	v_add_f32_e32 v109, 1.0, v109
	v_add_f32_e32 v105, 1.0, v105
	v_exp_f32_e32 v111, v111
	v_rcp_f32_e32 v109, v109
	v_rcp_f32_e32 v113, v105
	v_add_f32_e32 v104, 1.0, v104
	v_rcp_f32_e32 v104, v104
	v_fmamk_f32 v103, v103, 0xbfb8aa3b, v154
	v_fmac_f32_e32 v154, 0xbfb8aa3b, v102
	v_mul_f32_e32 v110, v110, v145
	v_add_f32_e32 v108, 1.0, v108
	v_exp_f32_e32 v102, v154
	v_sqrt_f32_e32 v207, v155
	v_exp_f32_e32 v155, v110
	v_add_f32_e32 v110, 1.0, v111
	v_rcp_f32_e32 v111, v108
	s_waitcnt lgkmcnt(0)
	v_mul_f32_e32 v156, v109, v115
	v_mul_f32_e32 v109, v113, v145
	v_exp_f32_e32 v109, v109
	v_exp_f32_e32 v103, v103
	v_mul_f32_e32 v104, v104, v145
	v_exp_f32_e32 v104, v104
	v_add_f32_e32 v102, 1.0, v102
	v_mul_f32_e32 v112, v111, v145
	v_rcp_f32_e32 v102, v102
	v_exp_f32_e32 v105, v112
	v_fma_f32 v112, v109, v109, -1.0
	v_add_f32_e32 v103, 1.0, v103
	v_max_f32_e64 v112, -v112, 0
	v_rcp_f32_e32 v103, v103
	v_sqrt_f32_e32 v189, v112
	v_fma_f32 v112, v104, v104, -1.0
	v_fmamk_f32 v101, v101, 0xbfb8aa3b, v157
	v_fmamk_f32 v100, v100, 0xbfb8aa3b, v157
	v_max_f32_e64 v190, -v112, 0
	v_fmamk_f32 v99, v99, 0xbfb8aa3b, v157
	v_fmac_f32_e32 v157, 0xbfb8aa3b, v98
	v_mul_f32_e32 v102, v102, v145
	v_sqrt_f32_e32 v154, v190
	v_exp_f32_e32 v98, v157
	v_exp_f32_e32 v190, v102
	v_mul_f32_e32 v103, v103, v145
	v_exp_f32_e32 v99, v99
	v_exp_f32_e32 v103, v103
	v_rcp_f32_e32 v110, v110
	v_exp_f32_e32 v100, v100
	ds_read2st64_b32 v[112:113], v143 offset0:68 offset1:70
	v_add_f32_e32 v98, 1.0, v98
	v_fma_f32 v145, v190, v190, -1.0
	v_rcp_f32_e32 v98, v98
	v_max_f32_e64 v145, -v145, 0
	v_exp_f32_e32 v101, v101
	v_add_f32_e32 v99, 1.0, v99
	v_fma_f32 v102, v103, v103, -1.0
	v_sqrt_f32_e32 v145, v145
	v_rcp_f32_e32 v99, v99
	v_max_f32_e64 v102, -v102, 0
	v_mul_f32_e32 v108, v110, v114
	ds_read2st64_b32 v[110:111], v143 offset0:72 offset1:74
	v_add_f32_e32 v100, 1.0, v100
	v_sqrt_f32_e32 v102, v102
	v_rcp_f32_e32 v100, v100
	s_waitcnt lgkmcnt(1)
	v_mul_f32_e32 v98, v98, v112
	v_add_f32_e32 v101, 1.0, v101
	v_mul_f32_e32 v191, v145, v98
	v_rcp_f32_e32 v101, v101
	v_mul_f32_e32 v99, v99, v113
	v_mul_f32_e32 v192, v103, v191
	v_fmac_f32_e32 v192, v102, v99
	s_waitcnt lgkmcnt(0)
	v_mul_f32_e32 v100, v100, v110
	v_mul_f32_e32 v194, v104, v192
	v_mul_f32_e32 v193, v190, v103
	v_fmac_f32_e32 v194, v154, v100
	v_mul_f32_e32 v101, v101, v111
	v_mul_f32_e32 v195, v104, v193
	v_mul_f32_e32 v196, v109, v194
	v_fmac_f32_e32 v196, v189, v101
	v_mul_f32_e32 v197, v109, v195
	ds_bpermute_b32 v204, v183, v197
	ds_bpermute_b32 v202, v183, v196
	ds_bpermute_b32 v200, v183, v197 offset:64
	ds_bpermute_b32 v201, v183, v196 offset:64
	ds_bpermute_b32 v198, v183, v197 offset:128
	ds_bpermute_b32 v199, v183, v196 offset:128
	ds_bpermute_b32 v98, v183, v197 offset:192
	ds_bpermute_b32 v189, v183, v196 offset:192
	s_lshl_b32 s40, s54, 1
	s_waitcnt lgkmcnt(6)
	v_fmac_f32_e32 v202, 0, v204
	s_waitcnt lgkmcnt(4)
	v_fma_f32 v99, v202, v200, v201
	v_mul_f32_e32 v100, v204, v200
	s_ashr_i32 s41, s40, 31
	v_lshl_add_u64 v[146:147], v[136:137], 2, s[24:25]
	s_waitcnt lgkmcnt(2)
	v_fma_f32 v99, v99, v198, v199
	v_mul_f32_e32 v100, v100, v198
	s_lshl_b64 s[12:13], s[40:41], 12
	s_waitcnt lgkmcnt(0)
	v_fmac_f32_e32 v189, v99, v98
	v_mul_f32_e32 v145, v100, v98
	v_lshl_add_u64 v[98:99], v[146:147], 0, s[12:13]
	global_load_dword v230, v[98:99], off
	v_fma_f32 v128, v203, v203, -1.0
	v_max_f32_e64 v128, -v128, 0
	v_sqrt_f32_e32 v128, v128
	v_mul_f32_e32 v212, v203, v185
	v_mul_f32_e32 v213, v184, v203
	v_mul_f32_e32 v221, v206, v213
	v_fmac_f32_e32 v212, v205, v128
	v_mul_f32_e32 v220, v206, v212
	v_fmac_f32_e32 v220, v208, v207
	v_mul_f32_e32 v222, v209, v220
	v_fmac_f32_e32 v222, v211, v210
	v_mul_f32_e32 v223, v209, v221
	v_mul_f32_e32 v205, v214, v187
	ds_bpermute_b32 v229, v183, v223
	ds_bpermute_b32 v228, v183, v222
	v_fmac_f32_e32 v205, v216, v215
	ds_bpermute_b32 v226, v183, v223 offset:64
	ds_bpermute_b32 v227, v183, v222 offset:64
	v_mul_f32_e32 v208, v217, v205
	ds_bpermute_b32 v224, v183, v223 offset:128
	ds_bpermute_b32 v225, v183, v222 offset:128
	v_mul_f32_e32 v206, v186, v214
	v_fmac_f32_e32 v208, v219, v218
	ds_bpermute_b32 v98, v183, v223 offset:192
	ds_bpermute_b32 v207, v183, v222 offset:192
	v_mul_f32_e32 v209, v217, v206
	v_mul_f32_e32 v210, v231, v208
	v_fmac_f32_e32 v210, v106, v232
	v_mul_f32_e32 v211, v231, v209
	s_waitcnt lgkmcnt(6)
	v_fmac_f32_e32 v228, 0, v229
	ds_bpermute_b32 v219, v183, v211
	ds_bpermute_b32 v218, v183, v210
	s_waitcnt lgkmcnt(6)
	v_fma_f32 v99, v228, v226, v227
	v_mul_f32_e32 v100, v229, v226
	ds_bpermute_b32 v216, v183, v211 offset:64
	ds_bpermute_b32 v217, v183, v210 offset:64
	s_waitcnt lgkmcnt(6)
	v_fma_f32 v99, v99, v224, v225
	v_mul_f32_e32 v100, v100, v224
	ds_bpermute_b32 v214, v183, v211 offset:128
	ds_bpermute_b32 v215, v183, v210 offset:128
	s_waitcnt lgkmcnt(6)
	v_fmac_f32_e32 v207, v99, v98
	v_mul_f32_e32 v233, v100, v98
	ds_bpermute_b32 v98, v183, v211 offset:192
	ds_bpermute_b32 v203, v183, v210 offset:192
	s_waitcnt lgkmcnt(6)
	v_fmac_f32_e32 v218, 0, v219
	s_waitcnt lgkmcnt(4)
	v_fma_f32 v99, v218, v216, v217
	v_mul_f32_e32 v100, v219, v216
	s_waitcnt lgkmcnt(2)
	v_fma_f32 v99, v99, v214, v215
	v_mul_f32_e32 v100, v100, v214
	s_waitcnt lgkmcnt(0)
	v_fmac_f32_e32 v203, v99, v98
	v_mul_f32_e32 v231, v100, v98
	v_fma_f32 v98, v155, v155, -1.0
	v_max_f32_e64 v98, -v98, 0
	v_sqrt_f32_e32 v154, v98
	v_mov_b32_e32 v106, v117
	v_pk_mul_f32 v[98:99], v[124:125], v[106:107]
	v_fma_f32 v102, v105, v105, -1.0
	v_mul_f32_e32 v100, v155, v99
	v_pk_fma_f32 v[100:101], v[154:155], v[98:99], v[100:101] op_sel_hi:[1,1,0]
	v_fma_f32 v98, v129, v129, -1.0
	v_max_f32_e64 v98, -v98, 0
	v_sqrt_f32_e32 v128, v98
	v_max_f32_e64 v102, -v102, 0
	v_sqrt_f32_e32 v104, v102
	v_mov_b32_e32 v109, v100
	v_mul_f32_e32 v98, v129, v100
	v_pk_fma_f32 v[102:103], v[128:129], v[108:109], v[98:99] op_sel_hi:[1,1,0]
	v_mul_f32_e32 v101, v188, v155
	v_mov_b32_e32 v157, v102
	v_mul_f32_e32 v103, v129, v101
	v_pk_mul_f32 v[106:107], v[104:105], v[156:157]
	v_mul_f32_e32 v125, v105, v103
	v_add_f32_e32 v124, v106, v107
	ds_bpermute_b32 v109, v183, v125
	ds_bpermute_b32 v129, v183, v124
	ds_bpermute_b32 v105, v183, v125 offset:64
	ds_bpermute_b32 v128, v183, v124 offset:64
	ds_bpermute_b32 v107, v183, v125 offset:128
	ds_bpermute_b32 v104, v183, v124 offset:128
	ds_bpermute_b32 v106, v183, v125 offset:192
	ds_bpermute_b32 v98, v183, v124 offset:192
	s_lshl_b32 s38, s15, 1
	s_add_i32 s2, s14, 0xffffff7f
	s_waitcnt vmcnt(0)
	v_fmac_f32_e32 v189, v145, v230
	s_cmp_eq_u32 s39, s2
	v_fmac_f32_e32 v207, v233, v189
	s_cselect_b64 s[12:13], -1, 0
	s_waitcnt lgkmcnt(6)
	v_fmac_f32_e32 v129, 0, v109
	v_fmac_f32_e32 v203, v231, v207
	s_and_b64 s[14:15], s[36:37], s[12:13]
	s_and_saveexec_b64 s[12:13], s[14:15]
	s_cbranch_execz .LBB0_815
	s_waitcnt lgkmcnt(4)
	v_fma_f32 v108, v129, v105, v128
	s_ashr_i32 s39, s38, 31
	s_waitcnt lgkmcnt(3)
	v_mul_f32_e32 v108, v108, v107
	s_lshl_b64 s[14:15], s[38:39], 12
	s_waitcnt lgkmcnt(2)
	v_pk_mul_f32 v[156:157], v[108:109], v[104:105]
	s_add_u32 s14, s72, s14
	v_add_f32_e32 v154, v108, v104
	v_mov_b32_e32 v155, v157
	s_addc_u32 s15, s73, s15
	s_waitcnt lgkmcnt(0)
	v_pk_fma_f32 v[154:155], v[154:155], v[106:107], v[98:99]
	v_mul_f32_e32 v98, v157, v107
	v_lshl_add_u64 v[156:157], v[136:137], 2, s[14:15]
	v_mul_f32_e32 v98, v98, v106
	v_add_co_u32_e32 v156, vcc, 0x6000000, v156
	v_fmac_f32_e32 v154, v98, v203
	s_nop 0
	v_addc_co_u32_e32 v157, vcc, 0, v157, vcc
	global_store_dword v[156:157], v154, off
.LBB0_815:
	s_or_b64 exec, exec, s[12:13]
	v_mfma_f32_16x16x32_bf16 v[154:157], v[2:5], v[86:89], 0
	v_mfma_f32_16x16x32_bf16 v[2:5], v[2:5], v[94:97], 0
	v_mfma_f32_16x16x32_bf16 v[232:235], v[26:29], v[86:89], 0
	v_mfma_f32_16x16x32_bf16 v[26:29], v[26:29], v[94:97], 0
	v_mfma_f32_16x16x32_bf16 v[236:239], v[34:37], v[86:89], 0
	v_mfma_f32_16x16x32_bf16 v[34:37], v[34:37], v[94:97], 0
	v_mfma_f32_16x16x32_bf16 v[86:89], v[42:45], v[86:89], 0
	v_mfma_f32_16x16x32_bf16 v[42:45], v[42:45], v[94:97], 0
	v_mfma_f32_16x16x32_bf16 v[94:97], v[6:9], v[78:81], v[154:157]
	v_mfma_f32_16x16x32_bf16 v[2:5], v[6:9], v[90:93], v[2:5]
	v_mfma_f32_16x16x32_bf16 v[6:9], v[10:13], v[78:81], v[232:235]
	v_mfma_f32_16x16x32_bf16 v[10:13], v[10:13], v[90:93], v[26:29]
	v_mfma_f32_16x16x32_bf16 v[26:29], v[22:25], v[78:81], v[236:239]
	v_mfma_f32_16x16x32_bf16 v[22:25], v[22:25], v[90:93], v[34:37]
	v_mfma_f32_16x16x32_bf16 v[34:37], v[30:33], v[78:81], v[86:89]
	v_mfma_f32_16x16x32_bf16 v[30:33], v[30:33], v[90:93], v[42:45]
	v_mfma_f32_16x16x32_bf16 v[42:45], v[46:49], v[74:77], v[94:97]
	v_mfma_f32_16x16x32_bf16 v[10:13], v[54:57], v[82:85], v[10:13]
	v_mfma_f32_16x16x32_bf16 v[46:49], v[46:49], v[82:85], v[2:5]
	v_mfma_f32_16x16x32_bf16 v[78:81], v[54:57], v[74:77], v[6:9]
	v_mfma_f32_16x16x32_bf16 v[2:5], v[50:53], v[62:65], v[42:45]
	s_nop 3
	v_add_co_u32_e32 v42, vcc, s43, v148
	s_mov_b64 s[12:13], vcc
	v_add_co_u32_e32 v44, vcc, 0x1000, v150
	v_mfma_f32_16x16x32_bf16 v[54:57], v[66:69], v[74:77], v[34:37]
	s_mov_b64 s[14:15], vcc
	v_mfma_f32_16x16x32_bf16 v[34:37], v[38:41], v[70:73], v[10:13]
	s_nop 2
	v_add_co_u32_e32 v10, vcc, 0x1000, v152
	v_mfma_f32_16x16x32_bf16 v[26:29], v[58:61], v[74:77], v[26:29]
	s_nop 0
	v_addc_co_u32_e32 v11, vcc, 0, v153, vcc
	v_addc_co_u32_e64 v43, vcc, 0, v149, s[12:13]
	v_mfma_f32_16x16x32_bf16 v[22:25], v[58:61], v[82:85], v[22:25]
	v_addc_co_u32_e64 v45, vcc, 0, v151, s[14:15]
	v_mfma_f32_16x16x32_bf16 v[58:61], v[66:69], v[82:85], v[30:33]
	v_mfma_f32_16x16x32_bf16 v[30:33], v[38:41], v[62:65], v[78:81]
	s_cmp_lg_u32 s98, 0
	s_cbranch_scc1 .Lrgc_d_fast
	global_load_dword v38, v[10:11], off
	global_load_dword v41, v[42:43], off
	global_load_dword v40, v[44:45], off
	v_mfma_f32_16x16x32_bf16 v[6:9], v[50:53], v[70:73], v[46:49]
	s_waitcnt vmcnt(2)
	v_xor_b32_e32 v42, 0x80000000, v38
	v_mfma_f32_16x16x32_bf16 v[26:29], v[18:21], v[62:65], v[26:29]
	v_cmp_ngt_f32_e32 vcc, s46, v38
	v_mfma_f32_16x16x32_bf16 v[22:25], v[18:21], v[70:73], v[22:25]
	v_mfma_f32_16x16x32_bf16 v[18:21], v[14:17], v[62:65], v[54:57]
	v_mfma_f32_16x16x32_bf16 v[10:13], v[14:17], v[70:73], v[58:61]
	s_and_saveexec_b64 s[12:13], vcc
	s_cbranch_execz .LBB0_817
	v_mul_f32_e32 v14, 0xbfb8aa3b, v38
	v_exp_f32_e32 v50, v14
	s_nop 0
	v_add_f32_e32 v16, 1.0, v50
	v_frexp_mant_f32_e32 v38, v16
	v_cvt_f64_f32_e32 v[14:15], v16
	v_frexp_exp_i32_f64_e32 v14, v[14:15]
	v_cmp_gt_f32_e32 vcc, s47, v38
	v_add_f32_e32 v17, -1.0, v16
	v_sub_f32_e32 v39, v17, v16
	v_subbrev_co_u32_e32 v44, vcc, 0, v14, vcc
	v_sub_u32_e32 v14, 0, v44
	v_sub_f32_e32 v17, v50, v17
	v_add_f32_e32 v39, 1.0, v39
	v_ldexp_f32 v15, v16, v14
	v_add_f32_e32 v17, v17, v39
	v_add_f32_e32 v16, -1.0, v15
	v_add_f32_e32 v38, 1.0, v15
	v_ldexp_f32 v14, v17, v14
	v_add_f32_e32 v17, 1.0, v16
	v_add_f32_e32 v39, -1.0, v38
	v_sub_f32_e32 v17, v15, v17
	v_sub_f32_e32 v15, v15, v39
	v_add_f32_e32 v17, v14, v17
	v_add_f32_e32 v14, v14, v15
	v_add_f32_e32 v45, v38, v14
	v_rcp_f32_e32 v47, v45
	v_sub_f32_e32 v15, v45, v38
	v_sub_f32_e32 v46, v14, v15
	v_add_f32_e32 v15, v16, v17
	v_mul_f32_e32 v49, v15, v47
	v_sub_f32_e32 v14, v15, v16
	v_mul_f32_e32 v16, v45, v49
	v_fma_f32 v38, v49, v45, -v16
	v_fmac_f32_e32 v38, v49, v46
	v_sub_f32_e32 v48, v17, v14
	v_add_f32_e32 v14, v16, v38
	v_sub_f32_e32 v17, v15, v14
	v_pk_add_f32 v[42:43], v[14:15], v[16:17] neg_lo:[0,1] neg_hi:[0,1]
	v_mov_b32_e32 v39, v14
	v_pk_add_f32 v[14:15], v[42:43], v[38:39] neg_lo:[0,1] neg_hi:[0,1]
	v_cmp_neq_f32_e32 vcc, s49, v50
	v_add_f32_e32 v15, v48, v15
	v_add_f32_e32 v14, v14, v15
	v_add_f32_e32 v15, v17, v14
	v_mul_f32_e32 v48, v47, v15
	v_mul_f32_e32 v16, v45, v48
	v_fma_f32 v38, v48, v45, -v16
	v_fmac_f32_e32 v38, v48, v46
	v_sub_f32_e32 v17, v17, v15
	v_add_f32_e32 v45, v14, v17
	v_add_f32_e32 v14, v16, v38
	v_sub_f32_e32 v17, v15, v14
	v_pk_add_f32 v[42:43], v[14:15], v[16:17] neg_lo:[0,1] neg_hi:[0,1]
	v_mov_b32_e32 v39, v14
	v_pk_add_f32 v[14:15], v[42:43], v[38:39] neg_lo:[0,1] neg_hi:[0,1]
	s_nop 0
	v_add_f32_e32 v15, v45, v15
	v_add_f32_e32 v14, v14, v15
	v_add_f32_e32 v15, v49, v48
	v_add_f32_e32 v14, v17, v14
	v_sub_f32_e32 v16, v15, v49
	v_mul_f32_e32 v14, v47, v14
	v_sub_f32_e32 v16, v48, v16
	v_add_f32_e32 v16, v16, v14
	v_add_f32_e32 v38, v15, v16
	v_mul_f32_e32 v39, v38, v38
	v_fmamk_f32 v14, v39, 0x3e9b6dac, v169
	v_fmaak_f32 v145, v39, v14, 0x3f2aaada
	v_cvt_f32_i32_e32 v14, v44
	v_sub_f32_e32 v15, v38, v15
	v_sub_f32_e32 v15, v16, v15
	v_ldexp_f32 v42, v15, 1
	v_mul_f32_e32 v15, v38, v39
	v_ldexp_f32 v17, v38, 1
	v_pk_mul_f32 v[38:39], v[14:15], v[144:145]
	s_nop 0
	v_fma_f32 v16, v14, s48, -v38
	v_fmac_f32_e32 v16, 0xb102e308, v14
	v_pk_add_f32 v[14:15], v[38:39], v[16:17]
	s_nop 0
	v_sub_f32_e32 v17, v15, v17
	v_sub_f32_e32 v17, v39, v17
	v_add_f32_e32 v43, v42, v17
	v_mov_b32_e32 v42, v38
	v_pk_add_f32 v[38:39], v[14:15], v[38:39] neg_lo:[0,1] neg_hi:[0,1]
	v_pk_add_f32 v[44:45], v[14:15], v[42:43]
	v_mov_b32_e32 v17, v14
	v_mov_b32_e32 v39, v45
	v_pk_add_f32 v[46:47], v[16:17], v[38:39] neg_lo:[0,1] neg_hi:[0,1]
	v_pk_add_f32 v[16:17], v[16:17], v[38:39]
	v_mov_b32_e32 v42, v43
	v_pk_add_f32 v[38:39], v[16:17], v[14:15] op_sel:[1,0] op_sel_hi:[0,1] neg_lo:[0,1] neg_hi:[0,1]
	v_pk_add_f32 v[48:49], v[44:45], v[38:39] op_sel_hi:[1,0] neg_lo:[0,1] neg_hi:[0,1]
	v_mov_b32_e32 v44, v45
	v_mov_b32_e32 v45, v17
	v_pk_mov_b32 v[38:39], v[14:15], v[38:39] op_sel:[1,0]
	v_mov_b32_e32 v43, v14
	v_pk_add_f32 v[38:39], v[44:45], v[38:39] neg_lo:[0,1] neg_hi:[0,1]
	v_mov_b32_e32 v48, v46
	v_pk_add_f32 v[14:15], v[42:43], v[38:39] neg_lo:[0,1] neg_hi:[0,1]
	v_mov_b32_e32 v47, v17
	v_pk_add_f32 v[38:39], v[48:49], v[14:15]
	s_nop 0
	v_pk_add_f32 v[42:43], v[38:39], v[38:39] op_sel:[0,1] op_sel_hi:[1,0]
	s_nop 0
	v_pk_add_f32 v[16:17], v[16:17], v[42:43] op_sel:[1,0] op_sel_hi:[0,1]
	v_mov_b32_e32 v39, v16
	v_pk_add_f32 v[44:45], v[38:39], v[46:47] neg_lo:[0,1] neg_hi:[0,1]
	v_mov_b32_e32 v15, v42
	v_sub_f32_e32 v17, v38, v44
	v_pk_add_f32 v[14:15], v[14:15], v[44:45] neg_lo:[0,1] neg_hi:[0,1]
	v_sub_f32_e32 v17, v46, v17
	v_add_f32_e32 v14, v14, v17
	v_add_f32_e32 v14, v14, v15
	v_add_f32_e32 v14, v16, v14
	v_cndmask_b32_e32 v14, v180, v14, vcc
	v_cmp_ngt_f32_e32 vcc, -1.0, v50
	s_nop 1
	v_cndmask_b32_e32 v14, v181, v14, vcc
	v_cmp_neq_f32_e32 vcc, -1.0, v50
	s_nop 1
	v_cndmask_b32_e32 v14, v182, v14, vcc
	v_cmp_lt_f32_e64 vcc, |v50|, s50
	s_nop 1
	v_cndmask_b32_e32 v42, v14, v50, vcc
.LBB0_817:
	s_or_b64 exec, exec, s[12:13]
	v_lshlrev_b32_e32 v251, 2, v0
	v_add_u32_e32 v251, 0x24a00, v251
	ds_write_b32 v251, v42 offset:6144
	s_waitcnt vmcnt(0)
	ds_write_b32 v251, v41 offset:8192
	ds_write_b32 v251, v40 offset:10240
	s_mov_b32 s98, 1
	s_branch .Lrgc_d_join
.Lrgc_d_fast:
	v_mfma_f32_16x16x32_bf16 v[6:9], v[50:53], v[70:73], v[46:49]
	v_mfma_f32_16x16x32_bf16 v[26:29], v[18:21], v[62:65], v[26:29]
	v_mfma_f32_16x16x32_bf16 v[22:25], v[18:21], v[70:73], v[22:25]
	v_mfma_f32_16x16x32_bf16 v[18:21], v[14:17], v[62:65], v[54:57]
	v_mfma_f32_16x16x32_bf16 v[10:13], v[14:17], v[70:73], v[58:61]
	v_lshlrev_b32_e32 v251, 2, v0
	v_add_u32_e32 v251, 0x24a00, v251
	ds_read_b32 v42, v251 offset:6144
	ds_read_b32 v41, v251 offset:8192
	ds_read_b32 v40, v251 offset:10240
	s_nop 7
	s_waitcnt lgkmcnt(0)
.Lrgc_d_join:
	s_nop 0
	v_mul_f32_e32 v41, 0xbfb8aa3b, v41
	v_fmamk_f32 v14, v30, 0xbfb8aa3b, v41
	v_exp_f32_e32 v14, v14
	v_mul_f32_e32 v15, 0xc1800000, v42
	s_nop 0
	v_mul_f32_e32 v40, 0xbfb8aa3b, v40
	v_mul_f32_e32 v15, 0x3fb8aa3b, v15
	v_add_f32_e32 v14, 1.0, v14
	v_rcp_f32_e32 v14, v14
	v_fmamk_f32 v16, v34, 0xbfb8aa3b, v40
	v_mul_f32_e32 v34, 0.5, v15
	v_fmamk_f32 v18, v18, 0xbfb8aa3b, v41
	v_mul_f32_e32 v14, v14, v34
	v_exp_f32_e32 v44, v14
	v_fmamk_f32 v14, v31, 0xbfb8aa3b, v41
	v_exp_f32_e32 v14, v14
	v_exp_f32_e32 v18, v18
	v_exp_f32_e32 v16, v16
	v_fmamk_f32 v10, v10, 0xbfb8aa3b, v40
	v_add_f32_e32 v14, 1.0, v14
	v_rcp_f32_e32 v14, v14
	v_add_f32_e32 v18, 1.0, v18
	v_rcp_f32_e32 v18, v18
	v_add_f32_e32 v15, 1.0, v16
	v_mul_f32_e32 v14, v14, v34
	v_exp_f32_e32 v42, v14
	v_fmamk_f32 v14, v32, 0xbfb8aa3b, v41
	v_exp_f32_e32 v14, v14
	v_fma_f32 v16, v44, v44, -1.0
	v_max_f32_e64 v16, -v16, 0
	v_sqrt_f32_e32 v31, v16
	v_add_f32_e32 v14, 1.0, v14
	v_rcp_f32_e32 v14, v14
	v_fma_f32 v16, v42, v42, -1.0
	v_max_f32_e64 v16, -v16, 0
	v_mul_f32_e32 v18, v18, v34
	v_mul_f32_e32 v14, v14, v34
	v_exp_f32_e32 v43, v14
	v_sqrt_f32_e32 v32, v16
	v_exp_f32_e32 v54, v18
	v_fmamk_f32 v18, v19, 0xbfb8aa3b, v41
	v_fma_f32 v16, v43, v43, -1.0
	v_max_f32_e64 v16, -v16, 0
	v_exp_f32_e32 v10, v10
	v_exp_f32_e32 v18, v18
	v_fmamk_f32 v14, v33, 0xbfb8aa3b, v41
	v_sqrt_f32_e32 v33, v16
	v_fmamk_f32 v16, v26, 0xbfb8aa3b, v41
	v_exp_f32_e32 v16, v16
	v_fmamk_f32 v17, v35, 0xbfb8aa3b, v40
	v_rcp_f32_e32 v15, v15
	v_exp_f32_e32 v17, v17
	v_exp_f32_e32 v14, v14
	v_add_f32_e32 v10, 1.0, v10
	v_add_f32_e32 v18, 1.0, v18
	v_fmamk_f32 v11, v11, 0xbfb8aa3b, v40
	v_rcp_f32_e32 v10, v10
	v_exp_f32_e32 v11, v11
	v_rcp_f32_e32 v18, v18
	v_add_f32_e32 v16, 1.0, v16
	v_rcp_f32_e32 v16, v16
	v_mul_f32_e32 v35, v126, v15
	v_add_f32_e32 v15, 1.0, v17
	v_fmamk_f32 v17, v36, 0xbfb8aa3b, v40
	v_add_f32_e32 v14, 1.0, v14
	v_rcp_f32_e32 v15, v15
	v_exp_f32_e32 v17, v17
	v_rcp_f32_e32 v14, v14
	v_mul_f32_e32 v66, v116, v10
	v_add_f32_e32 v10, 1.0, v11
	v_mul_f32_e32 v11, v18, v34
	v_exp_f32_e32 v67, v11
	v_fmamk_f32 v11, v20, 0xbfb8aa3b, v41
	v_mul_f32_e32 v16, v16, v34
	v_exp_f32_e32 v11, v11
	v_exp_f32_e32 v26, v16
	v_fmamk_f32 v16, v27, 0xbfb8aa3b, v41
	v_mul_f32_e32 v36, v127, v15
	v_add_f32_e32 v15, 1.0, v17
	v_fmamk_f32 v17, v37, 0xbfb8aa3b, v40
	v_mul_f32_e32 v14, v14, v34
	v_exp_f32_e32 v16, v16
	v_rcp_f32_e32 v15, v15
	v_exp_f32_e32 v17, v17
	v_exp_f32_e32 v14, v14
	v_add_f32_e32 v11, 1.0, v11
	v_fmamk_f32 v5, v5, 0xbfb8aa3b, v41
	v_rcp_f32_e32 v11, v11
	v_exp_f32_e32 v5, v5
	v_add_f32_e32 v16, 1.0, v16
	v_mul_f32_e32 v37, v122, v15
	v_add_f32_e32 v15, 1.0, v17
	v_fma_f32 v17, v14, v14, -1.0
	v_rcp_f32_e32 v16, v16
	v_fmamk_f32 v9, v9, 0xbfb8aa3b, v40
	v_rcp_f32_e32 v15, v15
	v_max_f32_e64 v17, -v17, 0
	v_fmamk_f32 v22, v22, 0xbfb8aa3b, v40
	v_exp_f32_e32 v9, v9
	v_sqrt_f32_e32 v17, v17
	v_exp_f32_e32 v22, v22
	v_mul_f32_e32 v11, v11, v34
	v_add_f32_e32 v5, 1.0, v5
	v_exp_f32_e32 v70, v11
	v_fmamk_f32 v11, v21, 0xbfb8aa3b, v41
	v_rcp_f32_e32 v5, v5
	v_mul_f32_e32 v16, v16, v34
	v_exp_f32_e32 v11, v11
	v_mul_f32_e32 v15, v123, v15
	v_exp_f32_e32 v49, v16
	v_fmamk_f32 v16, v28, 0xbfb8aa3b, v41
	v_add_f32_e32 v9, 1.0, v9
	v_mul_f32_e32 v15, v15, v17
	v_add_f32_e32 v17, 1.0, v22
	v_fmamk_f32 v23, v23, 0xbfb8aa3b, v40
	v_exp_f32_e32 v16, v16
	v_fmamk_f32 v12, v12, 0xbfb8aa3b, v40
	v_rcp_f32_e32 v9, v9
	v_rcp_f32_e32 v17, v17
	v_exp_f32_e32 v23, v23
	v_rcp_f32_e32 v10, v10
	v_exp_f32_e32 v12, v12
	v_mul_f32_e32 v5, v5, v34
	v_add_f32_e32 v11, 1.0, v11
	v_exp_f32_e32 v20, v5
	v_fmamk_f32 v5, v8, 0xbfb8aa3b, v40
	v_rcp_f32_e32 v11, v11
	v_exp_f32_e32 v8, v5
	v_fmamk_f32 v4, v4, 0xbfb8aa3b, v41
	v_add_f32_e32 v16, 1.0, v16
	v_mul_f32_e32 v111, v111, v9
	v_exp_f32_e32 v9, v4
	v_mul_f32_e32 v48, v118, v17
	v_add_f32_e32 v17, 1.0, v23
	v_fmamk_f32 v23, v24, 0xbfb8aa3b, v40
	v_rcp_f32_e32 v16, v16
	v_mul_f32_e32 v69, v117, v10
	v_add_f32_e32 v10, 1.0, v12
	v_fma_f32 v12, v70, v70, -1.0
	v_rcp_f32_e32 v17, v17
	v_exp_f32_e32 v23, v23
	v_fma_f32 v18, v67, v67, -1.0
	v_max_f32_e64 v12, -v12, 0
	v_max_f32_e64 v18, -v18, 0
	v_sqrt_f32_e32 v71, v12
	v_fmamk_f32 v12, v13, 0xbfb8aa3b, v40
	v_mul_f32_e32 v11, v11, v34
	v_add_f32_e32 v8, 1.0, v8
	v_fmamk_f32 v4, v7, 0xbfb8aa3b, v40
	v_fmamk_f32 v3, v3, 0xbfb8aa3b, v41
	v_sqrt_f32_e32 v68, v18
	v_rcp_f32_e32 v10, v10
	v_exp_f32_e32 v12, v12
	v_exp_f32_e32 v18, v11
	v_exp_f32_e32 v7, v4
	v_rcp_f32_e32 v4, v8
	v_add_f32_e32 v8, 1.0, v9
	v_exp_f32_e32 v3, v3
	v_mul_f32_e32 v16, v16, v34
	v_rcp_f32_e32 v8, v8
	v_mul_f32_e32 v50, v119, v17
	v_add_f32_e32 v17, 1.0, v23
	v_exp_f32_e32 v51, v16
	v_fmamk_f32 v16, v29, 0xbfb8aa3b, v41
	v_fmamk_f32 v23, v25, 0xbfb8aa3b, v40
	v_fmac_f32_e32 v40, 0xbfb8aa3b, v6
	v_exp_f32_e32 v16, v16
	v_exp_f32_e32 v6, v40
	v_mul_f32_e32 v72, v114, v10
	v_add_f32_e32 v10, 1.0, v12
	v_fma_f32 v11, v18, v18, -1.0
	v_add_f32_e32 v7, 1.0, v7
	v_add_f32_e32 v3, 1.0, v3
	v_fmac_f32_e32 v41, 0xbfb8aa3b, v2
	v_rcp_f32_e32 v10, v10
	v_max_f32_e64 v11, -v11, 0
	v_rcp_f32_e32 v9, v7
	v_mul_f32_e32 v7, v8, v34
	v_exp_f32_e32 v2, v41
	v_rcp_f32_e32 v3, v3
	v_sqrt_f32_e32 v11, v11
	v_exp_f32_e32 v7, v7
	v_add_f32_e32 v16, 1.0, v16
	v_add_f32_e32 v6, 1.0, v6
	v_rcp_f32_e32 v16, v16
	v_fma_f32 v19, v54, v54, -1.0
	v_fma_f32 v5, v20, v20, -1.0
	v_rcp_f32_e32 v6, v6
	v_max_f32_e64 v19, -v19, 0
	v_mul_f32_e32 v10, v115, v10
	v_max_f32_e64 v5, -v5, 0
	v_add_f32_e32 v2, 1.0, v2
	v_mul_f32_e32 v3, v3, v34
	v_sqrt_f32_e32 v65, v19
	v_mul_f32_e32 v19, v10, v11
	v_sqrt_f32_e32 v5, v5
	v_rcp_f32_e32 v2, v2
	v_exp_f32_e32 v11, v3
	v_fma_f32 v3, v7, v7, -1.0
	v_fma_f32 v22, v26, v26, -1.0
	v_max_f32_e64 v3, -v3, 0
	v_max_f32_e64 v22, -v22, 0
	v_mul_f32_e32 v16, v16, v34
	v_mul_f32_e32 v12, v112, v6
	v_sqrt_f32_e32 v6, v3
	v_sqrt_f32_e32 v27, v22
	v_fma_f32 v22, v49, v49, -1.0
	v_rcp_f32_e32 v17, v17
	v_exp_f32_e32 v23, v23
	v_exp_f32_e32 v16, v16
	v_max_f32_e64 v22, -v22, 0
	v_mul_f32_e32 v2, v2, v34
	v_pk_mul_f32 v[4:5], v[110:111], v[4:5]
	v_sqrt_f32_e32 v28, v22
	v_fma_f32 v22, v51, v51, -1.0
	v_exp_f32_e32 v25, v2
	v_mul_f32_e32 v2, v5, v7
	v_max_f32_e64 v22, -v22, 0
	v_pk_fma_f32 v[2:3], v[4:5], v[6:7], v[2:3] op_sel_hi:[1,1,0]
	v_sqrt_f32_e32 v29, v22
	v_mul_f32_e32 v52, v120, v17
	v_add_f32_e32 v17, 1.0, v23
	v_fma_f32 v22, v16, v16, -1.0
	v_fma_f32 v3, v11, v11, -1.0
	v_rcp_f32_e32 v17, v17
	v_max_f32_e64 v22, -v22, 0
	v_max_f32_e64 v3, -v3, 0
	v_sqrt_f32_e32 v22, v22
	v_sqrt_f32_e32 v10, v3
	s_or_b32 s12, s40, 1
	s_ashr_i32 s13, s12, 31
	v_mul_f32_e32 v17, v121, v17
	v_mul_f32_e32 v8, v113, v9
	v_mul_f32_e32 v21, v20, v7
	v_mov_b32_e32 v9, v2
	v_mul_f32_e32 v4, v2, v11
	v_fma_f32 v3, v25, v25, -1.0
	s_lshl_b64 s[12:13], s[12:13], 12
	v_mul_f32_e32 v17, v17, v22
	v_max_f32_e64 v3, -v3, 0
	v_pk_fma_f32 v[6:7], v[8:9], v[10:11], v[4:5] op_sel_hi:[1,1,0]
	v_mul_f32_e32 v22, v11, v21
	v_lshl_add_u64 v[10:11], v[146:147], 0, s[12:13]
	v_sqrt_f32_e32 v24, v3
	global_load_dword v3, v[10:11], off
	v_mul_f32_e32 v45, v43, v15
	v_fmac_f32_e32 v45, v37, v33
	v_mul_f32_e32 v47, v14, v43
	v_mul_f32_e32 v43, v42, v45
	v_fmac_f32_e32 v43, v36, v32
	v_mul_f32_e32 v46, v42, v47
	v_mul_f32_e32 v42, v44, v43
	v_or_b32_e32 v30, 0xc0, v183
	v_fmac_f32_e32 v42, v35, v31
	v_mul_f32_e32 v44, v44, v46
	v_mul_f32_e32 v34, v51, v17
	v_or_b32_e32 v39, 0x80, v183
	ds_bpermute_b32 v60, v30, v44
	ds_bpermute_b32 v59, v30, v42
	v_fmac_f32_e32 v34, v52, v29
	v_or_b32_e32 v38, 64, v183
	ds_bpermute_b32 v55, v39, v44
	ds_bpermute_b32 v58, v39, v42
	v_mul_f32_e32 v32, v49, v34
	v_mov_b32_e32 v13, v6
	ds_bpermute_b32 v56, v38, v44
	ds_bpermute_b32 v57, v38, v42
	v_mul_f32_e32 v36, v16, v51
	v_fmac_f32_e32 v32, v50, v28
	v_pk_mul_f32 v[8:9], v[12:13], v[24:25]
	ds_bpermute_b32 v12, v183, v44
	ds_bpermute_b32 v64, v183, v42
	v_mul_f32_e32 v35, v49, v36
	v_mul_f32_e32 v31, v26, v32
	v_fmac_f32_e32 v31, v48, v27
	v_mul_f32_e32 v33, v26, v35
	s_waitcnt lgkmcnt(6)
	v_fmac_f32_e32 v59, 0, v60
	ds_bpermute_b32 v53, v30, v33
	ds_bpermute_b32 v52, v30, v31
	s_waitcnt lgkmcnt(6)
	v_fma_f32 v24, v59, v55, v58
	ds_bpermute_b32 v48, v39, v33
	ds_bpermute_b32 v51, v39, v31
	s_waitcnt lgkmcnt(6)
	v_fma_f32 v24, v24, v56, v57
	ds_bpermute_b32 v49, v38, v33
	ds_bpermute_b32 v50, v38, v31
	s_waitcnt lgkmcnt(6)
	v_fmac_f32_e32 v64, v24, v12
	ds_bpermute_b32 v24, v183, v33
	ds_bpermute_b32 v61, v183, v31
	v_mul_f32_e32 v23, v25, v22
	v_mul_f32_e32 v25, v55, v60
	v_mul_f32_e32 v25, v25, v56
	s_waitcnt lgkmcnt(6)
	v_fmac_f32_e32 v52, 0, v53
	v_mul_f32_e32 v12, v25, v12
	s_waitcnt lgkmcnt(4)
	v_fma_f32 v25, v52, v48, v51
	v_mul_f32_e32 v27, v70, v19
	s_waitcnt lgkmcnt(2)
	v_fma_f32 v25, v25, v49, v50
	v_fmac_f32_e32 v27, v72, v71
	v_mul_f32_e32 v26, v48, v53
	s_waitcnt lgkmcnt(0)
	v_fmac_f32_e32 v61, v25, v24
	v_mul_f32_e32 v25, v67, v27
	v_mul_f32_e32 v26, v26, v49
	v_fmac_f32_e32 v25, v69, v68
	v_mul_f32_e32 v29, v18, v70
	v_mul_f32_e32 v73, v26, v24
	v_mul_f32_e32 v24, v54, v25
	v_mul_f32_e32 v28, v67, v29
	v_fmac_f32_e32 v24, v66, v65
	v_mul_f32_e32 v26, v54, v28
	v_add_f32_e32 v7, v8, v9
	ds_bpermute_b32 v41, v30, v26
	ds_bpermute_b32 v40, v30, v24
	ds_bpermute_b32 v13, v39, v23
	ds_bpermute_b32 v63, v39, v7
	ds_bpermute_b32 v37, v39, v26
	ds_bpermute_b32 v39, v39, v24
	ds_bpermute_b32 v11, v30, v23
	ds_bpermute_b32 v62, v30, v7
	ds_bpermute_b32 v9, v38, v23
	ds_bpermute_b32 v10, v38, v7
	ds_bpermute_b32 v30, v38, v26
	ds_bpermute_b32 v38, v38, v24
	ds_bpermute_b32 v65, v183, v26
	ds_bpermute_b32 v54, v183, v24
	s_waitcnt lgkmcnt(12)
	v_fmac_f32_e32 v40, 0, v41
	s_waitcnt lgkmcnt(8)
	v_fma_f32 v66, v40, v37, v39
	v_mul_f32_e32 v67, v37, v41
	ds_bpermute_b32 v8, v183, v23
	ds_bpermute_b32 v4, v183, v7
	s_waitcnt lgkmcnt(4)
	v_fma_f32 v66, v66, v30, v38
	v_mul_f32_e32 v67, v67, v30
	s_waitcnt lgkmcnt(2)
	v_fmac_f32_e32 v54, v66, v65
	v_mul_f32_e32 v65, v67, v65
	s_waitcnt vmcnt(0)
	v_fmac_f32_e32 v54, v3, v65
	s_cmp_eq_u32 s54, s55
	v_fmac_f32_e32 v61, v73, v54
	s_cselect_b64 s[12:13], -1, 0
	v_fmac_f32_e32 v62, 0, v11
	v_fmac_f32_e32 v64, v12, v61
	s_and_b64 s[14:15], s[36:37], s[12:13]
	s_and_saveexec_b64 s[12:13], s[14:15]
	s_cbranch_execz .LBB0_796
	s_or_b32 s14, s38, 1
	v_fma_f32 v12, v62, v13, v63
	s_ashr_i32 s15, s14, 31
	v_mul_f32_e32 v12, v12, v9
	s_lshl_b64 s[14:15], s[14:15], 12
	v_pk_mul_f32 v[68:69], v[12:13], v[10:11]
	s_add_u32 s14, s72, s14
	v_add_f32_e32 v66, v12, v10
	v_mov_b32_e32 v67, v69
	s_addc_u32 s15, s73, s15
	s_waitcnt lgkmcnt(0)
	v_pk_fma_f32 v[66:67], v[66:67], v[8:9], v[4:5]
	v_mul_f32_e32 v4, v69, v9
	v_lshl_add_u64 v[68:69], v[136:137], 2, s[14:15]
	v_mul_f32_e32 v4, v4, v8
	v_add_co_u32_e32 v68, vcc, 0x6000000, v68
	v_fmac_f32_e32 v66, v4, v64
	s_nop 0
	v_addc_co_u32_e32 v69, vcc, 0, v69, vcc
	global_store_dword v[68:69], v66, off
	s_branch .LBB0_796

.LBB0_864:
	s_waitcnt lgkmcnt(0)
	s_barrier
	ds_read_b128 v[90:93], v157
	ds_read_b128 v[94:97], v157 offset:64
	s_waitcnt lgkmcnt(1)
	v_mfma_f32_16x16x32_bf16 v[98:101], v[90:93], v[14:17], 0
	v_mfma_f32_16x16x32_bf16 v[90:93], v[90:93], v[30:33], 0
	s_waitcnt lgkmcnt(0)
	v_mfma_f32_16x16x32_bf16 v[98:101], v[94:97], v[6:9], v[98:101]
	v_mfma_f32_16x16x32_bf16 v[90:93], v[94:97], v[22:25], v[90:93]
	ds_read_b128 v[94:97], v157 offset:128
	ds_read_b128 v[102:105], v157 offset:192
	ds_read_b128 v[106:109], v157 offset:4352
	ds_read_b128 v[110:113], v157 offset:4416
	ds_read_b128 v[114:117], v157 offset:8704
	ds_read_b128 v[118:121], v157 offset:8768
	s_waitcnt lgkmcnt(5)
	v_mfma_f32_16x16x32_bf16 v[98:101], v[94:97], v[10:13], v[98:101]
	s_waitcnt lgkmcnt(4)
	v_mfma_f32_16x16x32_bf16 v[98:101], v[102:105], v[18:21], v[98:101]
	v_mfma_f32_16x16x32_bf16 v[90:93], v[94:97], v[26:29], v[90:93]
	ds_read_b128 v[94:97], v157 offset:13056
	ds_read_b128 v[122:125], v157 offset:13120
	ds_read_b128 v[164:167], v157 offset:4480
	ds_read_b128 v[168:171], v157 offset:4544
	s_nop 2
	v_fmamk_f32 v3, v98, 0xbfb8aa3b, v161
	v_exp_f32_e32 v3, v3
	v_mfma_f32_16x16x32_bf16 v[180:183], v[102:105], v[34:37], v[90:93]
	ds_read_b128 v[172:175], v157 offset:8832
	ds_read_b128 v[176:179], v157 offset:8896
	ds_read_b128 v[184:187], v157 offset:13184
	ds_read_b128 v[188:191], v157 offset:13248
	v_add_f32_e32 v3, 1.0, v3
	v_rcp_f32_e32 v3, v3
	s_nop 1
	v_fmamk_f32 v4, v180, 0xbfb8aa3b, v162
	v_exp_f32_e32 v4, v4
	s_waitcnt lgkmcnt(11)
	v_mfma_f32_16x16x32_bf16 v[192:195], v[106:109], v[14:17], 0
	v_mul_f32_e32 v3, v163, v3
	v_exp_f32_e32 v93, v3
	v_fmamk_f32 v3, v99, 0xbfb8aa3b, v161
	v_exp_f32_e32 v3, v3
	v_add_f32_e32 v90, 1.0, v4
	ds_read2st64_b32 v[4:5], v159 offset0:68 offset1:70
	v_rcp_f32_e32 v90, v90
	v_add_f32_e32 v3, 1.0, v3
	v_rcp_f32_e32 v3, v3
	v_mfma_f32_16x16x32_bf16 v[106:109], v[106:109], v[30:33], 0
	s_waitcnt lgkmcnt(0)
	v_mul_f32_e32 v102, v90, v4
	v_fmamk_f32 v4, v181, 0xbfb8aa3b, v162
	v_exp_f32_e32 v4, v4
	v_mul_f32_e32 v3, v163, v3
	v_exp_f32_e32 v105, v3
	v_fmamk_f32 v3, v100, 0xbfb8aa3b, v161
	v_add_f32_e32 v4, 1.0, v4
	v_exp_f32_e32 v3, v3
	v_rcp_f32_e32 v4, v4
	v_mfma_f32_16x16x32_bf16 v[200:203], v[94:97], v[14:17], 0
	ds_read2st64_b32 v[90:91], v159 offset0:72 offset1:74
	v_add_f32_e32 v3, 1.0, v3
	v_rcp_f32_e32 v3, v3
	v_mfma_f32_16x16x32_bf16 v[96:99], v[94:97], v[30:33], 0
	v_mul_f32_e32 v94, v4, v5
	v_fmamk_f32 v5, v101, 0xbfb8aa3b, v161
	v_exp_f32_e32 v5, v5
	v_mfma_f32_16x16x32_bf16 v[196:199], v[114:117], v[14:17], 0
	v_mul_f32_e32 v3, v163, v3
	v_fmamk_f32 v4, v182, 0xbfb8aa3b, v162
	v_exp_f32_e32 v4, v4
	v_mfma_f32_16x16x32_bf16 v[114:117], v[114:117], v[30:33], 0
	v_add_f32_e32 v4, 1.0, v4
	v_mfma_f32_16x16x32_bf16 v[192:195], v[110:113], v[6:9], v[192:195]
	v_rcp_f32_e32 v4, v4
	v_mfma_f32_16x16x32_bf16 v[106:109], v[110:113], v[22:25], v[106:109]
	v_mfma_f32_16x16x32_bf16 v[110:113], v[118:121], v[6:9], v[196:199]
	v_mfma_f32_16x16x32_bf16 v[114:117], v[118:121], v[22:25], v[114:117]
	v_exp_f32_e32 v121, v3
	v_add_f32_e32 v3, 1.0, v5
	v_fmamk_f32 v5, v183, 0xbfb8aa3b, v162
	v_exp_f32_e32 v5, v5
	v_mfma_f32_16x16x32_bf16 v[180:183], v[164:167], v[10:13], v[192:195]
	v_rcp_f32_e32 v3, v3
	v_add_f32_e32 v5, 1.0, v5
	v_mfma_f32_16x16x32_bf16 v[106:109], v[164:167], v[26:29], v[106:109]
	v_rcp_f32_e32 v92, v5
	v_mul_f32_e32 v3, v163, v3
	v_exp_f32_e32 v3, v3
	v_mfma_f32_16x16x32_bf16 v[164:167], v[168:171], v[18:21], v[180:183]
	s_waitcnt lgkmcnt(0)
	v_mul_f32_e32 v91, v92, v91
	v_fma_f32 v5, v3, v3, -1.0
	v_mfma_f32_16x16x32_bf16 v[168:171], v[168:171], v[34:37], v[106:109]
	v_max_f32_e64 v5, -v5, 0
	s_nop 2
	v_fmamk_f32 v92, v164, 0xbfb8aa3b, v161
	v_exp_f32_e32 v92, v92
	ds_read2st64_b32 v[106:107], v159 offset0:100 offset1:102
	v_mfma_f32_16x16x32_bf16 v[98:101], v[122:125], v[22:25], v[96:99]
	v_fmamk_f32 v95, v168, 0xbfb8aa3b, v162
	v_exp_f32_e32 v95, v95
	v_add_f32_e32 v92, 1.0, v92
	v_rcp_f32_e32 v92, v92
	v_mfma_f32_16x16x32_bf16 v[108:111], v[172:175], v[10:13], v[110:113]
	v_add_f32_e32 v95, 1.0, v95
	v_rcp_f32_e32 v95, v95
	v_mul_f32_e32 v92, v163, v92
	v_exp_f32_e32 v97, v92
	v_fmamk_f32 v92, v165, 0xbfb8aa3b, v161
	s_waitcnt lgkmcnt(0)
	v_mul_f32_e32 v106, v95, v106
	v_fmamk_f32 v95, v169, 0xbfb8aa3b, v162
	v_exp_f32_e32 v92, v92
	v_exp_f32_e32 v95, v95
	v_fmamk_f32 v96, v166, 0xbfb8aa3b, v161
	v_mfma_f32_16x16x32_bf16 v[112:115], v[172:175], v[26:29], v[114:117]
	v_add_f32_e32 v92, 1.0, v92
	v_add_f32_e32 v95, 1.0, v95
	v_rcp_f32_e32 v92, v92
	v_rcp_f32_e32 v95, v95
	v_exp_f32_e32 v96, v96
	v_mfma_f32_16x16x32_bf16 v[172:175], v[176:179], v[18:21], v[108:111]
	v_mul_f32_e32 v92, v163, v92
	ds_read2st64_b32 v[168:169], v159 offset0:168 offset1:170
	v_sqrt_f32_e32 v5, v5
	v_mul_f32_e32 v108, v95, v107
	v_fmamk_f32 v95, v170, 0xbfb8aa3b, v162
	v_mfma_f32_16x16x32_bf16 v[176:179], v[176:179], v[34:37], v[112:115]
	v_exp_f32_e32 v95, v95
	v_pk_mul_f32 v[90:91], v[4:5], v[90:91]
	v_add_f32_e32 v95, 1.0, v95
	v_exp_f32_e32 v113, v92
	v_add_f32_e32 v92, 1.0, v96
	v_fmamk_f32 v96, v167, 0xbfb8aa3b, v161
	v_exp_f32_e32 v96, v96
	v_mfma_f32_16x16x32_bf16 v[196:199], v[122:125], v[6:9], v[200:203]
	v_rcp_f32_e32 v124, v95
	v_rcp_f32_e32 v92, v92
	v_add_f32_e32 v95, 1.0, v96
	v_rcp_f32_e32 v95, v95
	ds_read2st64_b32 v[166:167], v159 offset0:104 offset1:106
	v_mul_f32_e32 v92, v163, v92
	v_exp_f32_e32 v123, v92
	v_mul_f32_e32 v95, v163, v95
	v_exp_f32_e32 v164, v95
	v_fmamk_f32 v92, v171, 0xbfb8aa3b, v162
	v_exp_f32_e32 v92, v92
	v_fmamk_f32 v96, v176, 0xbfb8aa3b, v162
	v_fma_f32 v95, v164, v164, -1.0
	v_max_f32_e64 v95, -v95, 0
	v_add_f32_e32 v92, 1.0, v92
	v_sqrt_f32_e32 v125, v95
	v_fmamk_f32 v95, v172, 0xbfb8aa3b, v161
	v_rcp_f32_e32 v92, v92
	v_exp_f32_e32 v95, v95
	v_mfma_f32_16x16x32_bf16 v[98:101], v[184:187], v[26:29], v[98:101]
	v_exp_f32_e32 v96, v96
	s_waitcnt lgkmcnt(0)
	v_mul_f32_e32 v167, v92, v167
	v_add_f32_e32 v92, 1.0, v95
	v_mfma_f32_16x16x32_bf16 v[116:119], v[184:187], v[10:13], v[196:199]
	v_rcp_f32_e32 v92, v92
	v_add_f32_e32 v95, 1.0, v96
	v_fmamk_f32 v96, v173, 0xbfb8aa3b, v161
	v_mfma_f32_16x16x32_bf16 v[184:187], v[188:191], v[34:37], v[98:101]
	v_rcp_f32_e32 v95, v95
	v_exp_f32_e32 v96, v96
	v_mul_f32_e32 v92, v163, v92
	ds_read2st64_b32 v[98:99], v159 offset0:132 offset1:134
	v_exp_f32_e32 v111, v92
	v_add_f32_e32 v92, 1.0, v96
	v_fmamk_f32 v96, v174, 0xbfb8aa3b, v161
	v_exp_f32_e32 v96, v96
	s_waitcnt lgkmcnt(0)
	v_mul_f32_e32 v114, v95, v98
	v_fmamk_f32 v95, v177, 0xbfb8aa3b, v162
	v_exp_f32_e32 v95, v95
	v_add_f32_e32 v96, 1.0, v96
	v_rcp_f32_e32 v96, v96
	v_fmamk_f32 v98, v178, 0xbfb8aa3b, v162
	v_add_f32_e32 v95, 1.0, v95
	v_rcp_f32_e32 v95, v95
	v_exp_f32_e32 v100, v98
	v_rcp_f32_e32 v92, v92
	v_mfma_f32_16x16x32_bf16 v[180:183], v[188:191], v[18:21], v[116:119]
	v_mul_f32_e32 v98, v95, v99
	v_mul_f32_e32 v95, v163, v96
	v_exp_f32_e32 v110, v95
	v_fmamk_f32 v95, v175, 0xbfb8aa3b, v161
	v_exp_f32_e32 v95, v95
	v_mul_f32_e32 v92, v163, v92
	v_fma_f32 v96, v110, v110, -1.0
	v_max_f32_e64 v96, -v96, 0
	v_add_f32_e32 v95, 1.0, v95
	v_rcp_f32_e32 v95, v95
	v_exp_f32_e32 v119, v92
	v_add_f32_e32 v92, 1.0, v100
	v_sqrt_f32_e32 v115, v96
	ds_read2st64_b32 v[100:101], v159 offset0:136 offset1:138
	v_fmamk_f32 v96, v179, 0xbfb8aa3b, v162
	v_mul_f32_e32 v95, v163, v95
	v_rcp_f32_e32 v92, v92
	v_exp_f32_e32 v96, v96
	v_exp_f32_e32 v170, v95
	v_fmamk_f32 v99, v184, 0xbfb8aa3b, v162
	s_waitcnt lgkmcnt(0)
	v_mul_f32_e32 v116, v92, v100
	v_add_f32_e32 v92, 1.0, v96
	v_fma_f32 v95, v170, v170, -1.0
	v_rcp_f32_e32 v92, v92
	v_max_f32_e64 v95, -v95, 0
	v_fmamk_f32 v96, v180, 0xbfb8aa3b, v161
	v_sqrt_f32_e32 v95, v95
	v_exp_f32_e32 v96, v96
	v_mul_f32_e32 v92, v92, v101
	v_exp_f32_e32 v99, v99
	v_mul_f32_e32 v171, v95, v92
	v_add_f32_e32 v92, 1.0, v96
	v_fmamk_f32 v96, v181, 0xbfb8aa3b, v161
	v_exp_f32_e32 v96, v96
	v_add_f32_e32 v95, 1.0, v99
	ds_read2st64_b32 v[100:101], v159 offset0:164 offset1:166
	v_rcp_f32_e32 v95, v95
	v_add_f32_e32 v96, 1.0, v96
	v_rcp_f32_e32 v96, v96
	v_rcp_f32_e32 v92, v92
	s_waitcnt lgkmcnt(0)
	v_mul_f32_e32 v100, v95, v100
	v_fmamk_f32 v99, v185, 0xbfb8aa3b, v162
	v_mul_f32_e32 v95, v163, v96
	v_exp_f32_e32 v172, v95
	v_fmamk_f32 v95, v182, 0xbfb8aa3b, v161
	v_exp_f32_e32 v95, v95
	v_exp_f32_e32 v99, v99
	v_mul_f32_e32 v92, v163, v92
	v_exp_f32_e32 v117, v92
	v_add_f32_e32 v95, 1.0, v95
	v_add_f32_e32 v92, 1.0, v99
	v_rcp_f32_e32 v95, v95
	v_rcp_f32_e32 v92, v92
	v_fmamk_f32 v99, v186, 0xbfb8aa3b, v162
	v_fma_f32 v96, v172, v172, -1.0
	v_mul_f32_e32 v95, v163, v95
	v_mul_f32_e32 v174, v92, v101
	v_exp_f32_e32 v101, v95
	v_fmamk_f32 v95, v183, 0xbfb8aa3b, v161
	v_exp_f32_e32 v99, v99
	v_exp_f32_e32 v95, v95
	v_max_f32_e64 v96, -v96, 0
	v_sqrt_f32_e32 v173, v96
	v_fma_f32 v96, v101, v101, -1.0
	v_max_f32_e64 v96, -v96, 0
	v_add_f32_e32 v92, 1.0, v99
	v_sqrt_f32_e32 v175, v96
	v_add_f32_e32 v95, 1.0, v95
	v_fmamk_f32 v96, v187, 0xbfb8aa3b, v162
	v_rcp_f32_e32 v92, v92
	v_rcp_f32_e32 v95, v95
	v_exp_f32_e32 v96, v96
	v_mul_f32_e32 v4, v121, v91
	v_mul_f32_e32 v168, v92, v168
	v_mul_f32_e32 v95, v163, v95
	v_add_f32_e32 v92, 1.0, v96
	v_fma_f32 v96, v121, v121, -1.0
	v_exp_f32_e32 v176, v95
	v_max_f32_e64 v96, -v96, 0
	v_sqrt_f32_e32 v120, v96
	v_rcp_f32_e32 v92, v92
	v_fma_f32 v95, v176, v176, -1.0
	v_max_f32_e64 v95, -v95, 0
	v_pk_fma_f32 v[4:5], v[120:121], v[90:91], v[4:5] op_sel_hi:[1,1,0]
	v_sqrt_f32_e32 v95, v95
	v_fma_f32 v5, v105, v105, -1.0
	v_max_f32_e64 v5, -v5, 0
	v_sqrt_f32_e32 v104, v5
	v_fma_f32 v5, v93, v93, -1.0
	v_mul_f32_e32 v92, v92, v169
	v_max_f32_e64 v5, -v5, 0
	v_mul_f32_e32 v169, v95, v92
	v_sqrt_f32_e32 v92, v5
	v_mov_b32_e32 v95, v4
	v_mul_f32_e32 v90, v105, v4
	v_pk_fma_f32 v[94:95], v[104:105], v[94:95], v[90:91] op_sel_hi:[1,1,0]
	v_mul_f32_e32 v177, v3, v121
	v_mov_b32_e32 v103, v94
	v_mul_f32_e32 v178, v105, v177
	v_pk_mul_f32 v[102:103], v[92:93], v[102:103]
	v_mul_f32_e32 v120, v93, v178
	v_add_f32_e32 v179, v102, v103
	ds_bpermute_b32 v93, v160, v120
	ds_bpermute_b32 v121, v160, v179
	ds_bpermute_b32 v95, v73, v120
	ds_bpermute_b32 v165, v73, v179
	ds_bpermute_b32 v5, v69, v120
	ds_bpermute_b32 v92, v69, v179
	s_waitcnt lgkmcnt(4)
	v_fmac_f32_e32 v121, 0, v93
	v_cndmask_b32_e64 v96, v121, 0, s[8:9]
	s_waitcnt lgkmcnt(2)
	v_fma_f32 v102, v96, v95, v165
	v_cndmask_b32_e64 v96, v96, v102, s[10:11]
	s_waitcnt lgkmcnt(0)
	v_fma_f32 v102, v96, v5, v92
	v_cndmask_b32_e64 v99, v93, 1.0, s[8:9]
	v_cndmask_b32_e64 v180, v96, v102, s[4:5]
	v_fma_f32 v96, v123, v123, -1.0
	v_mul_f32_e32 v103, v99, v95
	v_max_f32_e64 v96, -v96, 0
	v_cndmask_b32_e64 v99, v99, v103, s[10:11]
	v_sqrt_f32_e32 v122, v96
	v_mul_f32_e32 v103, v99, v5
	v_cndmask_b32_e64 v181, v99, v103, s[4:5]
	v_pk_mul_f32 v[102:103], v[124:125], v[166:167]
	ds_bpermute_b32 v90, v158, v179
	v_mul_f32_e32 v96, v123, v103
	v_pk_fma_f32 v[104:105], v[122:123], v[102:103], v[96:97] op_sel_hi:[1,1,0]
	v_fma_f32 v96, v113, v113, -1.0
	v_max_f32_e64 v96, -v96, 0
	v_sqrt_f32_e32 v112, v96
	v_fma_f32 v96, v97, v97, -1.0
	v_max_f32_e64 v96, -v96, 0
	v_sqrt_f32_e32 v96, v96
	v_mov_b32_e32 v109, v104
	v_mul_f32_e32 v102, v113, v104
	v_pk_fma_f32 v[108:109], v[112:113], v[108:109], v[102:103] op_sel_hi:[1,1,0]
	v_mul_f32_e32 v105, v164, v123
	v_mov_b32_e32 v107, v108
	v_mul_f32_e32 v109, v113, v105
	v_pk_mul_f32 v[106:107], v[96:97], v[106:107]
	v_mul_f32_e32 v167, v97, v109
	v_add_f32_e32 v166, v106, v107
	ds_bpermute_b32 v113, v160, v167
	ds_bpermute_b32 v97, v160, v166
	ds_bpermute_b32 v123, v73, v167
	ds_bpermute_b32 v99, v73, v166
	ds_bpermute_b32 v107, v69, v167
	ds_bpermute_b32 v112, v69, v166
	s_waitcnt lgkmcnt(4)
	v_fmac_f32_e32 v97, 0, v113
	v_cndmask_b32_e64 v118, v113, 1.0, s[8:9]
	v_cndmask_b32_e64 v102, v97, 0, s[8:9]
	s_waitcnt lgkmcnt(3)
	v_mul_f32_e32 v124, v118, v123
	ds_bpermute_b32 v106, v158, v167
	ds_bpermute_b32 v96, v158, v166
	s_waitcnt lgkmcnt(4)
	v_fma_f32 v122, v102, v123, v99
	v_cndmask_b32_e64 v118, v118, v124, s[10:11]
	v_cndmask_b32_e64 v102, v102, v122, s[10:11]
	v_fmac_f32_e32 v99, v97, v123
	s_waitcnt lgkmcnt(3)
	v_mul_f32_e32 v122, v118, v107
	v_cndmask_b32_e64 v183, v118, v122, s[4:5]
	v_mul_f32_e32 v122, v99, v107
	s_waitcnt lgkmcnt(2)
	v_fma_f32 v97, v102, v107, v112
	v_add_f32_e32 v124, v122, v112
	v_pk_mul_f32 v[112:113], v[122:123], v[112:113]
	v_cndmask_b32_e64 v182, v102, v97, s[4:5]
	v_mov_b32_e32 v125, v113
	v_fma_f32 v102, v119, v119, -1.0
	s_waitcnt lgkmcnt(0)
	v_pk_fma_f32 v[96:97], v[124:125], v[106:107], v[96:97]
	v_max_f32_e64 v102, -v102, 0
	v_mul_f32_e32 v99, v110, v171
	v_mul_f32_e32 v97, v170, v110
	v_sqrt_f32_e32 v118, v102
	v_fma_f32 v110, v111, v111, -1.0
	v_max_f32_e64 v110, -v110, 0
	v_fmac_f32_e32 v99, v115, v116
	v_sqrt_f32_e32 v110, v110
	v_mul_f32_e32 v102, v119, v99
	v_pk_fma_f32 v[122:123], v[118:119], v[98:99], v[102:103] op_sel_hi:[1,1,0]
	v_mul_f32_e32 v102, v119, v97
	v_mov_b32_e32 v115, v122
	v_pk_mul_f32 v[114:115], v[110:111], v[114:115]
	v_mul_f32_e32 v123, v111, v102
	v_add_f32_e32 v112, v114, v115
	ds_bpermute_b32 v115, v160, v123
	ds_bpermute_b32 v116, v160, v112
	ds_bpermute_b32 v119, v73, v123
	ds_bpermute_b32 v118, v73, v112
	ds_bpermute_b32 v111, v69, v123
	ds_bpermute_b32 v114, v69, v112
	s_waitcnt lgkmcnt(4)
	v_fmac_f32_e32 v116, 0, v115
	v_cndmask_b32_e64 v124, v116, 0, s[8:9]
	ds_bpermute_b32 v110, v158, v123
	ds_bpermute_b32 v98, v158, v112
	v_cndmask_b32_e64 v125, v115, 1.0, s[8:9]
	s_waitcnt lgkmcnt(4)
	v_fma_f32 v184, v124, v119, v118
	v_mul_f32_e32 v185, v125, v119
	v_cndmask_b32_e64 v124, v124, v184, s[10:11]
	v_fmac_f32_e32 v118, v116, v119
	v_cndmask_b32_e64 v125, v125, v185, s[10:11]
	s_waitcnt lgkmcnt(2)
	v_fma_f32 v116, v124, v111, v114
	v_mul_f32_e32 v118, v118, v111
	v_mul_f32_e32 v184, v125, v111
	v_cndmask_b32_e64 v185, v124, v116, s[4:5]
	v_add_f32_e32 v124, v118, v114
	v_pk_mul_f32 v[114:115], v[118:119], v[114:115]
	v_cndmask_b32_e64 v184, v125, v184, s[4:5]
	v_mov_b32_e32 v125, v115
	s_waitcnt lgkmcnt(0)
	v_pk_fma_f32 v[118:119], v[124:125], v[110:111], v[98:99]
	v_mul_f32_e32 v98, v101, v169
	v_mul_f32_e32 v114, v176, v101
	v_fma_f32 v101, v117, v117, -1.0
	v_max_f32_e64 v101, -v101, 0
	v_sqrt_f32_e32 v116, v101
	v_fmac_f32_e32 v98, v175, v168
	v_mul_f32_e32 v101, v172, v98
	v_fmac_f32_e32 v101, v173, v174
	v_mul_f32_e32 v119, v172, v114
	v_pk_mul_f32 v[124:125], v[116:117], v[100:101]
	v_mul_f32_e32 v168, v117, v119
	v_add_f32_e32 v100, v124, v125
	ds_bpermute_b32 v124, v160, v168
	ds_bpermute_b32 v125, v160, v100
	ds_bpermute_b32 v173, v73, v168
	ds_bpermute_b32 v174, v73, v100
	ds_bpermute_b32 v116, v69, v168
	ds_bpermute_b32 v175, v69, v100
	s_waitcnt lgkmcnt(4)
	v_fmac_f32_e32 v125, 0, v124
	v_cndmask_b32_e64 v186, v125, 0, s[8:9]
	ds_bpermute_b32 v117, v158, v168
	v_cndmask_b32_e64 v187, v124, 1.0, s[8:9]
	s_waitcnt lgkmcnt(3)
	v_fma_f32 v188, v186, v173, v174
	v_mul_f32_e32 v189, v187, v173
	v_cndmask_b32_e64 v186, v186, v188, s[10:11]
	v_cndmask_b32_e64 v187, v187, v189, s[10:11]
	v_fmac_f32_e32 v174, v125, v173
	s_waitcnt lgkmcnt(1)
	v_fma_f32 v125, v186, v116, v175
	v_mul_f32_e32 v188, v187, v116
	v_cndmask_b32_e64 v186, v186, v125, s[4:5]
	v_mul_f32_e32 v125, v174, v116
	v_cndmask_b32_e64 v187, v187, v188, s[4:5]
	v_mul_f32_e32 v124, v173, v124
	v_add_f32_e32 v125, v125, v175
	s_waitcnt lgkmcnt(0)
	v_pk_mul_f32 v[124:125], v[124:125], v[116:117]
	v_fmac_f32_e32 v186, v71, v187
	v_add_u32_e32 v116, s44, v129
	ds_bpermute_b32 v172, v158, v100
	v_fmac_f32_e32 v100, v168, v186
	v_add_u32_e32 v168, 0x23400, v116
	v_add_u32_e32 v173, 0x23500, v116
	v_add_u32_e32 v174, 0x23600, v116
	v_add_u32_e32 v175, 0x23700, v116
	v_add_u32_e32 v187, 0x22400, v116
	v_add_u32_e32 v188, 0x22500, v116
	v_add_u32_e32 v189, 0x22600, v116
	v_add_u32_e32 v190, 0x22700, v116
	ds_read_u16 v168, v168
	ds_read_u16 v173, v173
	ds_read_u16 v174, v174
	ds_read_u16 v175, v175
	ds_read_u16 v187, v187
	ds_read_u16 v188, v188
	ds_read_u16 v189, v189
	ds_read_u16 v190, v190
	s_waitcnt lgkmcnt(7)
	v_lshlrev_b32_e32 v168, 16, v168
	v_add_f32_e32 v100, v100, v168
	ds_write_b32 v133, v100 offset:50176
	v_fmac_f32_e32 v101, v119, v186
	s_waitcnt lgkmcnt(7)
	v_lshlrev_b32_e32 v100, 16, v173
	v_add_f32_e32 v100, v101, v100
	ds_write_b32 v134, v100 offset:50176
	v_fmac_f32_e32 v98, v114, v186
	s_waitcnt lgkmcnt(7)
	v_lshlrev_b32_e32 v100, 16, v174
	v_add_f32_e32 v98, v98, v100
	ds_write_b32 v135, v98 offset:50176
	v_fmac_f32_e32 v169, v176, v186
	s_waitcnt lgkmcnt(7)
	v_lshlrev_b32_e32 v98, 16, v175
	v_add_f32_e32 v98, v169, v98
	ds_write_b32 v136, v98 offset:50176
	v_mul_f32_e32 v98, v124, v117
	v_add_f32_e32 v100, v125, v172
	v_fmac_f32_e32 v100, v71, v98
	v_fmac_f32_e32 v185, v184, v100
	v_fmac_f32_e32 v112, v123, v185
	s_waitcnt lgkmcnt(7)
	v_lshlrev_b32_e32 v71, 16, v187
	v_add_f32_e32 v71, v112, v71
	ds_write_b32 v137, v71 offset:50176
	v_fmac_f32_e32 v122, v102, v185
	s_waitcnt lgkmcnt(7)
	v_lshlrev_b32_e32 v71, 16, v188
	v_add_f32_e32 v71, v122, v71
	ds_write_b32 v138, v71 offset:50176
	v_fmac_f32_e32 v99, v97, v185
	s_waitcnt lgkmcnt(7)
	v_lshlrev_b32_e32 v71, 16, v189
	v_add_f32_e32 v71, v99, v71
	ds_write_b32 v139, v71 offset:50176
	v_fmac_f32_e32 v171, v170, v185
	s_waitcnt lgkmcnt(7)
	v_lshlrev_b32_e32 v71, 16, v190
	v_add_f32_e32 v71, v171, v71
	ds_write_b32 v140, v71 offset:50176
	v_mul_f32_e32 v71, v115, v111
	v_mul_f32_e32 v71, v71, v110
	v_fmac_f32_e32 v118, v71, v100
	v_add_u32_e32 v71, 0x21400, v116
	v_add_u32_e32 v97, 0x21500, v116
	v_add_u32_e32 v98, 0x21600, v116
	v_add_u32_e32 v99, 0x21700, v116
	v_add_u32_e32 v100, 0x20400, v116
	v_add_u32_e32 v101, 0x20500, v116
	v_add_u32_e32 v102, 0x20600, v116
	v_add_u32_e32 v110, 0x20700, v116
	v_fmac_f32_e32 v182, v183, v118
	ds_read_u16 v71, v71
	ds_read_u16 v97, v97
	ds_read_u16 v98, v98
	ds_read_u16 v99, v99
	ds_read_u16 v100, v100
	ds_read_u16 v101, v101
	ds_read_u16 v102, v102
	ds_read_u16 v110, v110
	v_fmac_f32_e32 v166, v167, v182
	s_waitcnt lgkmcnt(7)
	v_lshlrev_b32_e32 v71, 16, v71
	v_add_f32_e32 v71, v166, v71
	ds_write_b32 v141, v71 offset:50176
	v_fmac_f32_e32 v108, v109, v182
	s_waitcnt lgkmcnt(7)
	v_lshlrev_b32_e32 v71, 16, v97
	v_add_f32_e32 v71, v108, v71
	ds_write_b32 v142, v71 offset:50176
	v_fmac_f32_e32 v104, v105, v182
	s_waitcnt lgkmcnt(7)
	v_lshlrev_b32_e32 v71, 16, v98
	v_add_f32_e32 v71, v104, v71
	ds_write_b32 v143, v71 offset:50176
	v_fmac_f32_e32 v103, v164, v182
	s_waitcnt lgkmcnt(7)
	v_lshlrev_b32_e32 v71, 16, v99
	v_add_f32_e32 v71, v103, v71
	ds_write_b32 v144, v71 offset:50176
	v_mul_f32_e32 v71, v113, v107
	v_mul_f32_e32 v71, v71, v106
	v_fmac_f32_e32 v96, v71, v118
	v_fmac_f32_e32 v180, v181, v96
	v_fmac_f32_e32 v179, v120, v180
	s_waitcnt lgkmcnt(7)
	v_lshlrev_b32_e32 v71, 16, v100
	v_add_f32_e32 v71, v179, v71
	ds_write_b32 v159, v71 offset:50176
	v_fmac_f32_e32 v94, v178, v180
	s_waitcnt lgkmcnt(7)
	v_lshlrev_b32_e32 v71, 16, v101
	v_add_f32_e32 v71, v94, v71
	v_fmac_f32_e32 v91, v3, v180
	s_waitcnt lgkmcnt(5)
	v_lshlrev_b32_e32 v3, 16, v110
	v_add_u32_e32 v110, s42, v131
	v_mov_b64_e32 v[112:113], s[74:75]
	ds_write_b32 v145, v71 offset:50176
	v_fmac_f32_e32 v4, v177, v180
	v_lshlrev_b32_e32 v71, 16, v102
	v_mad_i64_i32 v[98:99], s[12:13], v110, s38, v[112:113]
	v_add_f32_e32 v4, v4, v71
	v_lshl_add_u64 v[98:99], v[98:99], 0, s[2:3]
	v_mov_b32_e32 v71, v2
	v_add_f32_e32 v3, v91, v3
	v_lshl_add_u64 v[98:99], v[98:99], 0, v[70:71]
	ds_write_b32 v146, v4 offset:50176
	ds_write_b32 v147, v3 offset:50176
	v_add_co_u32_e32 v98, vcc, s39, v98
	s_nop 1
	v_addc_co_u32_e32 v99, vcc, 0, v99, vcc
	global_load_dwordx4 v[98:101], v[98:99], off offset:2048 nt
	v_add_u32_e32 v251, s42, v130
	v_mad_i64_i32 v[252:253], s[12:13], v251, s38, v[112:113]
	v_lshl_add_u64 v[252:253], v[252:253], 0, s[2:3]
	v_lshl_add_u64 v[252:253], v[252:253], 0, v[70:71]
	v_add_co_u32_e32 v252, vcc, s39, v252
	s_nop 1
	v_addc_co_u32_e32 v253, vcc, 0, v253, vcc
	global_load_dwordx4 v[252:255], v[252:253], off offset:2048 nt
	s_waitcnt lgkmcnt(0)
	s_barrier
	s_nop 0
	ds_read_b128 v[102:105], v148 offset:50176
	ds_read_b128 v[106:109], v148 offset:50192
	v_ashrrev_i32_e32 v111, 31, v110
	v_fmac_f32_e32 v165, v121, v95
	v_mul_f32_e32 v94, v165, v5
	s_addk_i32 s44, 0xc000
	s_waitcnt vmcnt(1)
	v_lshlrev_b32_e32 v114, 16, v98
	v_and_b32_e32 v115, 0xffff0000, v98
	v_mul_f32_e32 v3, 0xbfb8aa3b, v114
	v_exp_f32_e32 v3, v3
	v_mul_f32_e32 v4, 0xbfb8aa3b, v115
	v_exp_f32_e32 v4, v4
	v_lshlrev_b32_e32 v98, 16, v99
	v_add_f32_e32 v3, 1.0, v3
	v_rcp_f32_e32 v116, v3
	v_add_f32_e32 v3, 1.0, v4
	v_rcp_f32_e32 v117, v3
	v_and_b32_e32 v99, 0xffff0000, v99
	v_pk_mul_f32 v[114:115], v[116:117], v[114:115]
	v_lshlrev_b32_e32 v116, 16, v100
	v_and_b32_e32 v117, 0xffff0000, v100
	v_mul_f32_e32 v3, 0xbfb8aa3b, v116
	v_exp_f32_e32 v3, v3
	v_mul_f32_e32 v4, 0xbfb8aa3b, v117
	v_exp_f32_e32 v4, v4
	s_waitcnt lgkmcnt(1)
	v_pk_mul_f32 v[102:103], v[102:103], v[114:115]
	v_add_f32_e32 v3, 1.0, v3
	v_rcp_f32_e32 v114, v3
	v_add_f32_e32 v3, 1.0, v4
	v_rcp_f32_e32 v115, v3
	v_mul_f32_e32 v3, 0xbfb8aa3b, v98
	v_exp_f32_e32 v3, v3
	v_mul_f32_e32 v4, 0xbfb8aa3b, v99
	v_exp_f32_e32 v4, v4
	v_pk_mul_f32 v[114:115], v[114:115], v[116:117]
	v_add_f32_e32 v3, 1.0, v3
	v_lshlrev_b32_e32 v116, 16, v101
	v_rcp_f32_e32 v100, v3
	v_add_f32_e32 v3, 1.0, v4
	v_and_b32_e32 v117, 0xffff0000, v101
	v_mul_f32_e32 v4, 0xbfb8aa3b, v116
	v_exp_f32_e32 v4, v4
	v_mul_f32_e32 v91, 0xbfb8aa3b, v117
	v_exp_f32_e32 v91, v91
	v_rcp_f32_e32 v101, v3
	v_add_f32_e32 v3, 1.0, v4
	v_rcp_f32_e32 v118, v3
	v_add_f32_e32 v3, 1.0, v91
	v_rcp_f32_e32 v119, v3
	v_pk_mul_f32 v[98:99], v[100:101], v[98:99]
	s_waitcnt lgkmcnt(0)
	v_pk_mul_f32 v[106:107], v[106:107], v[114:115]
	v_pk_mul_f32 v[100:101], v[104:105], v[98:99]
	v_pk_mul_f32 v[98:99], v[118:119], v[116:117]
	ds_bpermute_b32 v4, v158, v120
	v_pk_mul_f32 v[104:105], v[108:109], v[98:99]
	v_cvt_pk_bf16_f32 v98, v102, v103
	v_lshlrev_b64 v[102:103], 12, v[110:111]
	v_cvt_pk_bf16_f32 v99, v100, v101
	v_cvt_pk_bf16_f32 v100, v106, v107
	v_cvt_pk_bf16_f32 v101, v104, v105
	v_lshl_add_u64 v[102:103], v[88:89], 0, v[102:103]
	v_add_u32_e32 v106, s42, v130
	global_store_dwordx4 v[102:103], v[98:101], off offset:2048
	v_add_f32_e32 v102, v94, v92
	v_pk_mul_f32 v[94:95], v[94:95], v[92:93]
	v_mov_b32_e32 v103, v95
	s_waitcnt lgkmcnt(0)
	v_pk_fma_f32 v[110:111], v[102:103], v[4:5], v[90:91]
	ds_read_b128 v[90:93], v149 offset:50176
	ds_read_b128 v[102:105], v149 offset:50192
	v_ashrrev_i32_e32 v107, 31, v106
	s_sub_i32 s42, s42, 64
	s_cmp_eq_u32 s44, 0xffff0000
	s_waitcnt vmcnt(1)
	v_mov_b32_e32 v98, v252
	v_mov_b32_e32 v99, v253
	v_mov_b32_e32 v100, v254
	v_mov_b32_e32 v101, v255
	v_lshlrev_b32_e32 v108, 16, v98
	v_and_b32_e32 v109, 0xffff0000, v98
	v_mul_f32_e32 v3, 0xbfb8aa3b, v108
	v_exp_f32_e32 v3, v3
	v_mul_f32_e32 v71, 0xbfb8aa3b, v109
	v_exp_f32_e32 v71, v71
	v_lshlrev_b32_e32 v98, 16, v99
	v_add_f32_e32 v3, 1.0, v3
	v_rcp_f32_e32 v112, v3
	v_add_f32_e32 v3, 1.0, v71
	v_rcp_f32_e32 v113, v3
	v_and_b32_e32 v99, 0xffff0000, v99
	v_pk_mul_f32 v[108:109], v[112:113], v[108:109]
	v_lshlrev_b32_e32 v112, 16, v100
	v_and_b32_e32 v113, 0xffff0000, v100
	v_mul_f32_e32 v3, 0xbfb8aa3b, v112
	v_exp_f32_e32 v3, v3
	v_mul_f32_e32 v71, 0xbfb8aa3b, v113
	v_exp_f32_e32 v71, v71
	s_waitcnt lgkmcnt(1)
	v_pk_mul_f32 v[90:91], v[90:91], v[108:109]
	v_add_f32_e32 v3, 1.0, v3
	v_rcp_f32_e32 v108, v3
	v_add_f32_e32 v3, 1.0, v71
	v_rcp_f32_e32 v109, v3
	v_mul_f32_e32 v3, 0xbfb8aa3b, v98
	v_exp_f32_e32 v3, v3
	v_mul_f32_e32 v71, 0xbfb8aa3b, v99
	v_exp_f32_e32 v71, v71
	v_pk_mul_f32 v[108:109], v[108:109], v[112:113]
	v_add_f32_e32 v3, 1.0, v3
	v_lshlrev_b32_e32 v112, 16, v101
	v_rcp_f32_e32 v100, v3
	v_add_f32_e32 v3, 1.0, v71
	v_and_b32_e32 v113, 0xffff0000, v101
	v_mul_f32_e32 v71, 0xbfb8aa3b, v112
	v_exp_f32_e32 v71, v71
	v_mul_f32_e32 v94, 0xbfb8aa3b, v113
	v_exp_f32_e32 v94, v94
	v_rcp_f32_e32 v101, v3
	v_add_f32_e32 v3, 1.0, v71
	v_rcp_f32_e32 v114, v3
	v_add_f32_e32 v3, 1.0, v94
	v_rcp_f32_e32 v115, v3
	v_pk_mul_f32 v[98:99], v[100:101], v[98:99]
	s_waitcnt lgkmcnt(0)
	v_pk_mul_f32 v[102:103], v[102:103], v[108:109]
	v_pk_mul_f32 v[92:93], v[92:93], v[98:99]
	v_pk_mul_f32 v[98:99], v[114:115], v[112:113]
	v_cvt_pk_bf16_f32 v90, v90, v91
	v_pk_mul_f32 v[98:99], v[104:105], v[98:99]
	v_cvt_pk_bf16_f32 v91, v92, v93
	v_cvt_pk_bf16_f32 v93, v98, v99
	v_lshlrev_b64 v[98:99], 12, v[106:107]
	v_cvt_pk_bf16_f32 v92, v102, v103
	v_lshl_add_u64 v[98:99], v[88:89], 0, v[98:99]
	global_store_dwordx4 v[98:99], v[90:93], off offset:2048
	v_mul_f32_e32 v3, v95, v5
	s_waitcnt lgkmcnt(0)
	s_barrier
	v_mul_f32_e32 v3, v3, v4
	v_mov_b32_e32 v71, v110
	v_fmac_f32_e32 v71, v3, v96
	s_cbranch_scc1 .LBB0_876

	.amdhsa_kernel _Z14fwd_megakernel6Params
		.amdhsa_group_segment_fixed_size 0
		.amdhsa_private_segment_fixed_size 0
		.amdhsa_kernarg_size 464
		.amdhsa_user_sgpr_count 2
		.amdhsa_user_sgpr_dispatch_ptr 0
		.amdhsa_user_sgpr_queue_ptr 0
		.amdhsa_user_sgpr_kernarg_segment_ptr 1
		.amdhsa_user_sgpr_dispatch_id 0
		.amdhsa_user_sgpr_kernarg_preload_length 0
		.amdhsa_user_sgpr_kernarg_preload_offset 0
		.amdhsa_user_sgpr_private_segment_size 0
		.amdhsa_uses_dynamic_stack 0
		.amdhsa_enable_private_segment 0
		.amdhsa_system_sgpr_workgroup_id_x 1
		.amdhsa_system_sgpr_workgroup_id_y 0
		.amdhsa_system_sgpr_workgroup_id_z 0
		.amdhsa_system_sgpr_workgroup_info 0
		.amdhsa_system_vgpr_workitem_id 0
		.amdhsa_next_free_vgpr 256
		.amdhsa_next_free_sgpr 99
		.amdhsa_accum_offset 256
		.amdhsa_reserve_vcc 1
		.amdhsa_float_round_mode_32 0
		.amdhsa_float_round_mode_16_64 0
		.amdhsa_float_denorm_mode_32 3
		.amdhsa_float_denorm_mode_16_64 3
		.amdhsa_dx10_clamp 1
		.amdhsa_ieee_mode 1
		.amdhsa_fp16_overflow 0
		.amdhsa_tg_split 0
		.amdhsa_exception_fp_ieee_invalid_op 0
		.amdhsa_exception_fp_denorm_src 0
		.amdhsa_exception_fp_ieee_div_zero 0
		.amdhsa_exception_fp_ieee_overflow 0
		.amdhsa_exception_fp_ieee_underflow 0
		.amdhsa_exception_fp_ieee_inexact 0
		.amdhsa_exception_int_div_zero 0
	.end_amdhsa_kernel

amdhsa.kernels:
  - .agpr_count:     0
    .args:
      - .offset:         0
        .size:           208
        .value_kind:     by_value
      - .offset:         208
        .size:           4
        .value_kind:     hidden_block_count_x
      - .offset:         212
        .size:           4
        .value_kind:     hidden_block_count_y
      - .offset:         216
        .size:           4
        .value_kind:     hidden_block_count_z
      - .offset:         220
        .size:           2
        .value_kind:     hidden_group_size_x
      - .offset:         222
        .size:           2
        .value_kind:     hidden_group_size_y
      - .offset:         224
        .size:           2
        .value_kind:     hidden_group_size_z
      - .offset:         226
        .size:           2
        .value_kind:     hidden_remainder_x
      - .offset:         228
        .size:           2
        .value_kind:     hidden_remainder_y
      - .offset:         230
        .size:           2
        .value_kind:     hidden_remainder_z
      - .offset:         248
        .size:           8
        .value_kind:     hidden_global_offset_x
      - .offset:         256
        .size:           8
        .value_kind:     hidden_global_offset_y
      - .offset:         264
        .size:           8
        .value_kind:     hidden_global_offset_z
      - .offset:         272
        .size:           2
        .value_kind:     hidden_grid_dims
      - .offset:         328
        .size:           4
        .value_kind:     hidden_dynamic_lds_size
    .group_segment_fixed_size: 0
    .kernarg_segment_align: 8
    .kernarg_segment_size: 464
    .language:       OpenCL C
    .language_version:
      - 2
      - 0
    .max_flat_workgroup_size: 512
    .name:           _Z14fwd_megakernel6Params
    .private_segment_fixed_size: 0
    .sgpr_count:     105
    .sgpr_spill_count: 59
    .symbol:         _Z14fwd_megakernel6Params.kd
    .uniform_work_group_size: 1
    .uses_dynamic_stack: false
    .vgpr_count:     256
    .vgpr_spill_count: 0
    .wavefront_size: 64
